# all per-segment s_setprio flips deleted from the five K-loops and their peeled copies (both halves arbitrate by age); rest as v65
# baseline (speedup 1.0000x reference)
;     __host__ __device__ bool next(int i, Unit& u) const { return at((long)i * G + c, u); }
; #define PG8_STAGE(bufoff, gbase, voff) do { _Pragma("unroll") for (int _i = 0; _i < 2; ++_i) \
;         __builtin_amdgcn_global_load_lds((const unsigned*)((const char*)(gbase) + (voff)[_i]), (PG8_LAS unsigned*)(lds + (bufoff) + ldsw + _i * 8192), 16, 0, 0); } while (0)
; #define PG8_LDA(dst, b, h) do { _Pragma("unroll") for (int m = 0; m < 4; ++m) _Pragma("unroll") for (int k = 0; k < 2; ++k) dst[m][k] = *(const PG8_LAS bf16x8*)(lds + PG8_SA(b, h) + aoff + m * 2048 + k * 1024); } while (0)
; #define PG8_LDB(dst, b, h) do { _Pragma("unroll") for (int n = 0; n < 2; ++n) _Pragma("unroll") for (int k = 0; k < 2; ++k) dst[n][k] = *(const PG8_LAS bf16x8*)(lds + PG8_SB(b, h) + boff + n * 2048 + k * 1024); } while (0)
; #define PG8_WAIT_V(n) asm volatile("s_waitcnt vmcnt(" #n ")" ::: "memory")
; #define PG8_BAR __builtin_amdgcn_s_barrier()
; template <class Epi, class Sched, bool ALIGN_EPI = false, bool SP2 = false>
; __device__ __forceinline__ void gemm_phase(PG8_LAS unsigned char* lds, const Gemm g, const Sched& S, const Epi& E) {
;     ...
;         const bool has_next = S.next(ui + 1, nxt);
;         const char* nA = has_next ? (const char*)g.A + (size_t)nxt.pm * tstep + (size_t)nxt.k0 * kstep : cA; const char* nB = has_next ? (const char*)g.Bt + (size_t)nxt.pn * tstep + (size_t)nxt.k0 * kstep : cB;
;         const int nt = cur.nt;
;         for (int t = 0; t < nt; t += 2) {
;             const bool last = (t == nt - 2);
;             const char* a1 = cA + (size_t)(t + 1) * kstep;
;             const char* a2 = last ? nA : cA + (size_t)(t + 2) * kstep; const char* b2 = last ? nB : cB + (size_t)(t + 2) * kstep;
;             const char* a3 = a2 + kstep; const char* b3 = b2 + kstep;
;             if (last && has_next) S.a_ready(nxt);
;             if constexpr (SP2) {
;             PG8_LDB(B0, 0, 0); PG8_LDB(B1, 0, 1); PG8_SCHED; PG8_LDA(At, 0, 0); PG8_STAGE(PG8_SA(1, 1), a1 + hstep, voffA);
;             PG8_WAIT_V(8); PG8_WAIT_L(0); PG8_BAR; PG8_MMA(0, 0, At, B0); PG8_MMA(0, 1, At, B1); PG8_BAR; PG8_SCHED;
;             PG8_LDA(At, 0, 1); PG8_STAGE(PG8_SB(0, 0), b2, voffB); PG8_STAGE(PG8_SB(0, 1), b2 + hstep, voffB); PG8_STAGE(PG8_SA(0, 0), a2, voffA);
;             PG8_WAIT_V(8); PG8_WAIT_L(0); PG8_BAR; PG8_MMA(1, 0, At, B0); PG8_MMA(1, 1, At, B1); PG8_BAR; PG8_SCHED;
.LBB0_123:
	s_ashr_i32 s55, s54, 31
	s_lshl_b64 s[16:17], s[54:55], 21
	s_add_u32 s58, s4, s16
	s_addc_u32 s59, s5, s17
	s_and_b64 s[16:17], s[56:57], exec
	s_cselect_b32 s30, s59, s29
	s_cselect_b32 s31, s58, s28
	s_ashr_i32 s53, s52, 31
	s_lshl_b64 s[16:17], s[52:53], 21
	s_add_u32 s60, s6, s16
	s_addc_u32 s61, s7, s17
	s_and_b64 s[16:17], s[56:57], exec
	s_cselect_b32 s53, s61, s27
	s_cselect_b32 s55, s60, s26
	s_add_u32 vcc_lo, s26, 0x100
	s_addc_u32 s16, s27, 0
	s_add_u32 s62, s28, 0x100080
	s_addc_u32 s63, s29, 0
	s_mov_b32 s17, -2
	s_waitcnt vmcnt(0)
	s_add_u32 s26, s62, 0xfff00080
	s_addc_u32 s27, s63, -1
	s_add_i32 s65, 0, 0x10000
	s_cmp_eq_u32 s17, 60
	s_cselect_b32 s29, s30, s27
	s_cselect_b32 s28, s31, s26
	v_add_u32_e32 v170, s65, v182
	s_cselect_b32 s27, s53, s16
	s_cselect_b32 s26, s55, vcc_lo
	s_add_i32 s70, 0, 0x14000
	ds_read_b128 v[122:125], v170
	ds_read_b128 v[126:129], v170 offset:1024
	ds_read_b128 v[130:133], v170 offset:2048
	ds_read_b128 v[172:175], v170 offset:3072
	v_add_u32_e32 v170, s70, v182
	ds_read_b128 v[176:179], v170
	ds_read_b128 v[192:195], v170 offset:1024
	ds_read_b128 v[196:199], v170 offset:2048
	ds_read_b128 v[200:203], v170 offset:3072
	v_lshl_add_u64 v[180:181], s[62:63], 0, v[156:157]
	s_add_i32 m0, s10, 0xc000
	ds_read_b128 v[204:207], v191
	ds_read_b128 v[220:223], v191 offset:1024
	ds_read_b128 v[224:227], v191 offset:2048
	ds_read_b128 v[228:231], v191 offset:3072
	ds_read_b128 v[232:235], v191 offset:4096
	ds_read_b128 v[236:239], v191 offset:5120
	ds_read_b128 v[240:243], v191 offset:6144
	ds_read_b128 v[244:247], v191 offset:7168
	global_load_lds_dwordx4 v[180:181], off
	v_lshl_add_u64 v[180:181], s[62:63], 0, v[154:155]
	s_add_i32 m0, s10, 0xe000
	s_nop 0
	global_load_lds_dwordx4 v[180:181], off
	s_waitcnt vmcnt(8)
	s_waitcnt lgkmcnt(0)
	s_barrier
	v_mfma_f32_16x16x32_bf16 v[118:121], v[122:125], v[204:207], 0
	v_mfma_f32_16x16x32_bf16 v[138:141], v[130:133], v[204:207], 0
	v_mfma_f32_16x16x32_bf16 v[102:105], v[122:125], v[224:227], 0
	v_mfma_f32_16x16x32_bf16 v[114:117], v[130:133], v[224:227], 0
	v_mfma_f32_16x16x32_bf16 v[86:89], v[122:125], v[232:235], 0
	v_mfma_f32_16x16x32_bf16 v[98:101], v[130:133], v[232:235], 0
	v_mfma_f32_16x16x32_bf16 v[70:73], v[122:125], v[240:243], 0
	v_mfma_f32_16x16x32_bf16 v[82:85], v[130:133], v[240:243], 0
	v_mfma_f32_16x16x32_bf16 v[118:121], v[126:129], v[220:223], v[118:121]
	v_mfma_f32_16x16x32_bf16 v[138:141], v[172:175], v[220:223], v[138:141]
	v_mfma_f32_16x16x32_bf16 v[102:105], v[126:129], v[228:231], v[102:105]
	v_mfma_f32_16x16x32_bf16 v[114:117], v[172:175], v[228:231], v[114:117]
	v_mfma_f32_16x16x32_bf16 v[86:89], v[126:129], v[236:239], v[86:89]
	v_mfma_f32_16x16x32_bf16 v[98:101], v[172:175], v[236:239], v[98:101]
	v_mfma_f32_16x16x32_bf16 v[70:73], v[126:129], v[244:247], v[70:73]
	v_mfma_f32_16x16x32_bf16 v[82:85], v[172:175], v[244:247], v[82:85]
	v_mfma_f32_16x16x32_bf16 v[134:137], v[176:179], v[204:207], 0
	v_mfma_f32_16x16x32_bf16 v[110:113], v[196:199], v[204:207], 0
	v_mfma_f32_16x16x32_bf16 v[106:109], v[176:179], v[224:227], 0
	v_mfma_f32_16x16x32_bf16 v[94:97], v[196:199], v[224:227], 0
	v_mfma_f32_16x16x32_bf16 v[90:93], v[176:179], v[232:235], 0
	v_mfma_f32_16x16x32_bf16 v[78:81], v[196:199], v[232:235], 0
	v_mfma_f32_16x16x32_bf16 v[74:77], v[176:179], v[240:243], 0
	v_mfma_f32_16x16x32_bf16 v[66:69], v[196:199], v[240:243], 0
	v_mfma_f32_16x16x32_bf16 v[134:137], v[192:195], v[220:223], v[134:137]
	v_mfma_f32_16x16x32_bf16 v[110:113], v[200:203], v[220:223], v[110:113]
	v_mfma_f32_16x16x32_bf16 v[106:109], v[192:195], v[228:231], v[106:109]
	v_mfma_f32_16x16x32_bf16 v[94:97], v[200:203], v[228:231], v[94:97]
	v_mfma_f32_16x16x32_bf16 v[90:93], v[192:195], v[236:239], v[90:93]
	v_mfma_f32_16x16x32_bf16 v[78:81], v[200:203], v[236:239], v[78:81]
	v_mfma_f32_16x16x32_bf16 v[74:77], v[192:195], v[244:247], v[74:77]
	v_mfma_f32_16x16x32_bf16 v[66:69], v[200:203], v[244:247], v[66:69]
	s_barrier
	s_add_i32 s65, s65, s9
	v_lshl_add_u64 v[180:181], s[26:27], 0, v[158:159]
	s_mov_b32 m0, s65
	ds_read_b128 v[204:207], v191 offset:16384
	ds_read_b128 v[220:223], v191 offset:17408
	ds_read_b128 v[224:227], v191 offset:18432
	ds_read_b128 v[228:231], v191 offset:19456
	ds_read_b128 v[232:235], v191 offset:20480
	ds_read_b128 v[236:239], v191 offset:21504
	ds_read_b128 v[240:243], v191 offset:22528
	ds_read_b128 v[244:247], v191 offset:23552
	global_load_lds_dwordx4 v[180:181], off
	s_add_i32 m0, s65, 0x2000
	s_add_u32 s68, s26, 0x100000
	v_lshl_add_u64 v[208:209], s[26:27], 0, v[142:143]
	s_addc_u32 s69, s27, 0
	s_add_i32 s65, s70, s9
	global_load_lds_dwordx4 v[208:209], off
	v_lshl_add_u64 v[248:249], s[68:69], 0, v[158:159]
	s_mov_b32 m0, s65
	v_lshl_add_u64 v[170:171], s[28:29], 0, v[144:145]
	global_load_lds_dwordx4 v[248:249], off
	v_lshl_add_u64 v[248:249], s[68:69], 0, v[142:143]
	s_add_i32 m0, s65, 0x2000
	s_nop 0
	global_load_lds_dwordx4 v[248:249], off
	v_lshl_add_u64 v[248:249], s[28:29], 0, v[146:147]
	s_mov_b32 m0, s10
	s_nop 0
	global_load_lds_dwordx4 v[248:249], off
	s_mov_b32 m0, s11
	s_nop 0
	global_load_lds_dwordx4 v[170:171], off
	s_waitcnt vmcnt(8)
	s_waitcnt lgkmcnt(0)
	s_barrier
; #define PG8_STAGE(bufoff, gbase, voff) do { _Pragma("unroll") for (int _i = 0; _i < 2; ++_i) \
;         __builtin_amdgcn_global_load_lds((const unsigned*)((const char*)(gbase) + (voff)[_i]), (PG8_LAS unsigned*)(lds + (bufoff) + ldsw + _i * 8192), 16, 0, 0); } while (0)
; #define PG8_LDA(dst, b, h) do { _Pragma("unroll") for (int m = 0; m < 4; ++m) _Pragma("unroll") for (int k = 0; k < 2; ++k) dst[m][k] = *(const PG8_LAS bf16x8*)(lds + PG8_SA(b, h) + aoff + m * 2048 + k * 1024); } while (0)
; #define PG8_LDB(dst, b, h) do { _Pragma("unroll") for (int n = 0; n < 2; ++n) _Pragma("unroll") for (int k = 0; k < 2; ++k) dst[n][k] = *(const PG8_LAS bf16x8*)(lds + PG8_SB(b, h) + boff + n * 2048 + k * 1024); } while (0)
; #define PG8_MMA(ai, bj, At, Bt) do { __builtin_amdgcn_s_setprio(1); _Pragma("unroll") for (int m = 0; m < 4; ++m) _Pragma("unroll") for (int n = 0; n < 2; ++n) _Pragma("unroll") for (int k = 0; k < 2; ++k) \
;         acc[ai][bj][m][n] = __builtin_amdgcn_mfma_f32_16x16x32_bf16(Bt[n][k], At[m][k], acc[ai][bj][m][n], 0, 0, 0); __builtin_amdgcn_s_setprio(0); } while (0)
; #define PG8_WAIT_V(n) asm volatile("s_waitcnt vmcnt(" #n ")" ::: "memory")
; #define PG8_WAIT_L(n) asm volatile("s_waitcnt lgkmcnt(" #n ")" ::: "memory")
; #define PG8_BAR __builtin_amdgcn_s_barrier()
; #define PG8_SCHED __builtin_amdgcn_sched_barrier(0)
; template <class Epi, class Sched, bool ALIGN_EPI = false, bool SP2 = false>
; __device__ __forceinline__ void gemm_phase(PG8_LAS unsigned char* lds, const Gemm g, const Sched& S, const Epi& E) {
;     ...
;             PG8_WAIT_V(8); PG8_WAIT_L(0); PG8_BAR; PG8_MMA(0, 0, At, B0); PG8_MMA(0, 1, At, B1); PG8_BAR; PG8_SCHED;
;             PG8_LDA(At, 0, 1); PG8_STAGE(PG8_SB(0, 0), b2, voffB); PG8_STAGE(PG8_SB(0, 1), b2 + hstep, voffB); PG8_STAGE(PG8_SA(0, 0), a2, voffA);
;             PG8_WAIT_V(8); PG8_WAIT_L(0); PG8_BAR; PG8_MMA(1, 0, At, B0); PG8_MMA(1, 1, At, B1); PG8_BAR; PG8_SCHED;
;             PG8_LDB(B0, 1, 0); PG8_LDB(B1, 1, 1); PG8_SCHED; PG8_LDA(At, 1, 0); PG8_STAGE(PG8_SA(0, 1), a2 + hstep, voffA);
;             PG8_WAIT_V(8); PG8_WAIT_L(0); PG8_BAR; PG8_MMA(0, 0, At, B0); PG8_MMA(0, 1, At, B1); PG8_BAR; PG8_SCHED;
	v_mfma_f32_16x16x32_bf16 v[54:57], v[122:125], v[204:207], 0
	v_mfma_f32_16x16x32_bf16 v[62:65], v[130:133], v[204:207], 0
	v_mfma_f32_16x16x32_bf16 v[38:41], v[122:125], v[224:227], 0
	v_mfma_f32_16x16x32_bf16 v[50:53], v[130:133], v[224:227], 0
	v_mfma_f32_16x16x32_bf16 v[22:25], v[122:125], v[232:235], 0
	v_mfma_f32_16x16x32_bf16 v[34:37], v[130:133], v[232:235], 0
	v_mfma_f32_16x16x32_bf16 v[6:9], v[122:125], v[240:243], 0
	v_mfma_f32_16x16x32_bf16 v[18:21], v[130:133], v[240:243], 0
	v_mfma_f32_16x16x32_bf16 v[54:57], v[126:129], v[220:223], v[54:57]
	v_mfma_f32_16x16x32_bf16 v[62:65], v[172:175], v[220:223], v[62:65]
	v_mfma_f32_16x16x32_bf16 v[38:41], v[126:129], v[228:231], v[38:41]
	v_mfma_f32_16x16x32_bf16 v[50:53], v[172:175], v[228:231], v[50:53]
	v_mfma_f32_16x16x32_bf16 v[22:25], v[126:129], v[236:239], v[22:25]
	v_mfma_f32_16x16x32_bf16 v[34:37], v[172:175], v[236:239], v[34:37]
	v_mfma_f32_16x16x32_bf16 v[6:9], v[126:129], v[244:247], v[6:9]
	v_mfma_f32_16x16x32_bf16 v[18:21], v[172:175], v[244:247], v[18:21]
	v_mfma_f32_16x16x32_bf16 v[58:61], v[176:179], v[204:207], 0
	v_mfma_f32_16x16x32_bf16 v[46:49], v[196:199], v[204:207], 0
	v_mfma_f32_16x16x32_bf16 v[42:45], v[176:179], v[224:227], 0
	v_mfma_f32_16x16x32_bf16 v[30:33], v[196:199], v[224:227], 0
	v_mfma_f32_16x16x32_bf16 v[26:29], v[176:179], v[232:235], 0
	v_mfma_f32_16x16x32_bf16 v[14:17], v[196:199], v[232:235], 0
	v_mfma_f32_16x16x32_bf16 v[10:13], v[176:179], v[240:243], 0
	v_mfma_f32_16x16x32_bf16 v[2:5], v[196:199], v[240:243], 0
	v_mfma_f32_16x16x32_bf16 v[58:61], v[192:195], v[220:223], v[58:61]
	v_mfma_f32_16x16x32_bf16 v[46:49], v[200:203], v[220:223], v[46:49]
	v_mfma_f32_16x16x32_bf16 v[42:45], v[192:195], v[228:231], v[42:45]
	v_mfma_f32_16x16x32_bf16 v[30:33], v[200:203], v[228:231], v[30:33]
	v_mfma_f32_16x16x32_bf16 v[26:29], v[192:195], v[236:239], v[26:29]
	v_mfma_f32_16x16x32_bf16 v[14:17], v[200:203], v[236:239], v[14:17]
	v_mfma_f32_16x16x32_bf16 v[10:13], v[192:195], v[244:247], v[10:13]
	v_mfma_f32_16x16x32_bf16 v[2:5], v[200:203], v[244:247], v[2:5]
	s_barrier
	s_add_i32 s65, 0, 0x18000
	s_add_i32 s68, 0, 0x1c000
	v_add_u32_e32 v172, s65, v182
	v_add_u32_e32 v200, s68, v182
	ds_read_b128 v[122:125], v172
	ds_read_b128 v[126:129], v172 offset:1024
	ds_read_b128 v[130:133], v172 offset:2048
	ds_read_b128 v[172:175], v172 offset:3072
	ds_read_b128 v[176:179], v200
	ds_read_b128 v[192:195], v200 offset:1024
	ds_read_b128 v[196:199], v200 offset:2048
	ds_read_b128 v[200:203], v200 offset:3072
	s_add_u32 s28, s28, 0x100000
	s_addc_u32 s29, s29, 0
	s_mov_b32 m0, s12
	v_lshl_add_u64 v[210:211], s[28:29], 0, v[146:147]
	ds_read_b128 v[204:207], v191 offset:32768
	ds_read_b128 v[220:223], v191 offset:33792
	ds_read_b128 v[224:227], v191 offset:34816
	ds_read_b128 v[228:231], v191 offset:35840
	ds_read_b128 v[232:235], v191 offset:36864
	ds_read_b128 v[236:239], v191 offset:37888
	ds_read_b128 v[240:243], v191 offset:38912
	ds_read_b128 v[244:247], v191 offset:39936
	global_load_lds_dwordx4 v[210:211], off
	v_lshl_add_u64 v[210:211], s[28:29], 0, v[144:145]
	s_mov_b32 m0, s13
	s_nop 0
	global_load_lds_dwordx4 v[210:211], off
	s_waitcnt vmcnt(8)
	s_waitcnt lgkmcnt(0)
	s_barrier
	v_mfma_f32_16x16x32_bf16 v[118:121], v[122:125], v[204:207], v[118:121]
	v_mfma_f32_16x16x32_bf16 v[138:141], v[130:133], v[204:207], v[138:141]
	v_mfma_f32_16x16x32_bf16 v[102:105], v[122:125], v[224:227], v[102:105]
	v_mfma_f32_16x16x32_bf16 v[114:117], v[130:133], v[224:227], v[114:117]
	v_mfma_f32_16x16x32_bf16 v[86:89], v[122:125], v[232:235], v[86:89]
	v_mfma_f32_16x16x32_bf16 v[98:101], v[130:133], v[232:235], v[98:101]
	v_mfma_f32_16x16x32_bf16 v[70:73], v[122:125], v[240:243], v[70:73]
	v_mfma_f32_16x16x32_bf16 v[82:85], v[130:133], v[240:243], v[82:85]
	v_mfma_f32_16x16x32_bf16 v[118:121], v[126:129], v[220:223], v[118:121]
	v_mfma_f32_16x16x32_bf16 v[138:141], v[172:175], v[220:223], v[138:141]
	v_mfma_f32_16x16x32_bf16 v[102:105], v[126:129], v[228:231], v[102:105]
	v_mfma_f32_16x16x32_bf16 v[114:117], v[172:175], v[228:231], v[114:117]
	v_mfma_f32_16x16x32_bf16 v[86:89], v[126:129], v[236:239], v[86:89]
	v_mfma_f32_16x16x32_bf16 v[98:101], v[172:175], v[236:239], v[98:101]
	v_mfma_f32_16x16x32_bf16 v[70:73], v[126:129], v[244:247], v[70:73]
	v_mfma_f32_16x16x32_bf16 v[82:85], v[172:175], v[244:247], v[82:85]
	v_mfma_f32_16x16x32_bf16 v[134:137], v[176:179], v[204:207], v[134:137]
	v_mfma_f32_16x16x32_bf16 v[110:113], v[196:199], v[204:207], v[110:113]
	v_mfma_f32_16x16x32_bf16 v[106:109], v[176:179], v[224:227], v[106:109]
	v_mfma_f32_16x16x32_bf16 v[94:97], v[196:199], v[224:227], v[94:97]
	v_mfma_f32_16x16x32_bf16 v[90:93], v[176:179], v[232:235], v[90:93]
	v_mfma_f32_16x16x32_bf16 v[78:81], v[196:199], v[232:235], v[78:81]
	v_mfma_f32_16x16x32_bf16 v[74:77], v[176:179], v[240:243], v[74:77]
	v_mfma_f32_16x16x32_bf16 v[66:69], v[196:199], v[240:243], v[66:69]
	v_mfma_f32_16x16x32_bf16 v[134:137], v[192:195], v[220:223], v[134:137]
	v_mfma_f32_16x16x32_bf16 v[110:113], v[200:203], v[220:223], v[110:113]
	v_mfma_f32_16x16x32_bf16 v[106:109], v[192:195], v[228:231], v[106:109]
	v_mfma_f32_16x16x32_bf16 v[94:97], v[200:203], v[228:231], v[94:97]
	v_mfma_f32_16x16x32_bf16 v[90:93], v[192:195], v[236:239], v[90:93]
	v_mfma_f32_16x16x32_bf16 v[78:81], v[200:203], v[236:239], v[78:81]
	v_mfma_f32_16x16x32_bf16 v[74:77], v[192:195], v[244:247], v[74:77]
	v_mfma_f32_16x16x32_bf16 v[66:69], v[200:203], v[244:247], v[66:69]
	s_barrier
; #define PG8_STAGE(bufoff, gbase, voff) do { _Pragma("unroll") for (int _i = 0; _i < 2; ++_i) \
;         __builtin_amdgcn_global_load_lds((const unsigned*)((const char*)(gbase) + (voff)[_i]), (PG8_LAS unsigned*)(lds + (bufoff) + ldsw + _i * 8192), 16, 0, 0); } while (0)
; #define PG8_LDA(dst, b, h) do { _Pragma("unroll") for (int m = 0; m < 4; ++m) _Pragma("unroll") for (int k = 0; k < 2; ++k) dst[m][k] = *(const PG8_LAS bf16x8*)(lds + PG8_SA(b, h) + aoff + m * 2048 + k * 1024); } while (0)
; #define PG8_LDB(dst, b, h) do { _Pragma("unroll") for (int n = 0; n < 2; ++n) _Pragma("unroll") for (int k = 0; k < 2; ++k) dst[n][k] = *(const PG8_LAS bf16x8*)(lds + PG8_SB(b, h) + boff + n * 2048 + k * 1024); } while (0)
; #define PG8_MMA(ai, bj, At, Bt) do { __builtin_amdgcn_s_setprio(1); _Pragma("unroll") for (int m = 0; m < 4; ++m) _Pragma("unroll") for (int n = 0; n < 2; ++n) _Pragma("unroll") for (int k = 0; k < 2; ++k) \
;         acc[ai][bj][m][n] = __builtin_amdgcn_mfma_f32_16x16x32_bf16(Bt[n][k], At[m][k], acc[ai][bj][m][n], 0, 0, 0); __builtin_amdgcn_s_setprio(0); } while (0)
; #define PG8_WAIT_V(n) asm volatile("s_waitcnt vmcnt(" #n ")" ::: "memory")
; #define PG8_WAIT_L(n) asm volatile("s_waitcnt lgkmcnt(" #n ")" ::: "memory")
; #define PG8_BAR __builtin_amdgcn_s_barrier()
; #define PG8_SCHED __builtin_amdgcn_sched_barrier(0)
; template <class Epi, class Sched, bool ALIGN_EPI = false, bool SP2 = false>
; __device__ __forceinline__ void gemm_phase(PG8_LAS unsigned char* lds, const Gemm g, const Sched& S, const Epi& E) {
;     ...
;             PG8_LDB(B0, 0, 0); PG8_LDB(B1, 0, 1); PG8_SCHED; PG8_LDA(At, 0, 0); PG8_STAGE(PG8_SA(1, 1), a1 + hstep, voffA);
;             PG8_WAIT_V(8); PG8_WAIT_L(0); PG8_BAR; PG8_MMA(0, 0, At, B0); PG8_MMA(0, 1, At, B1); PG8_BAR; PG8_SCHED;
;     ...
;             PG8_WAIT_V(8); PG8_WAIT_L(0); PG8_BAR; PG8_MMA(0, 0, At, B0); PG8_MMA(0, 1, At, B1); PG8_BAR; PG8_SCHED;
;             PG8_LDA(At, 1, 1); PG8_STAGE(PG8_SB(1, 0), b3, voffB); PG8_STAGE(PG8_SB(1, 1), b3 + hstep, voffB); PG8_STAGE(PG8_SA(1, 0), a3, voffA);
;             PG8_WAIT_V(8); PG8_WAIT_L(0); PG8_BAR; PG8_MMA(1, 0, At, B0); PG8_MMA(1, 1, At, B1); PG8_BAR; PG8_SCHED;
	s_add_i32 s28, s65, s9
	v_lshl_add_u64 v[180:181], v[180:181], 0, s[96:97]
	s_mov_b32 m0, s28
	ds_read_b128 v[204:207], v191 offset:49152
	ds_read_b128 v[220:223], v191 offset:50176
	ds_read_b128 v[224:227], v191 offset:51200
	ds_read_b128 v[228:231], v191 offset:52224
	ds_read_b128 v[232:235], v191 offset:53248
	ds_read_b128 v[236:239], v191 offset:54272
	ds_read_b128 v[240:243], v191 offset:55296
	ds_read_b128 v[244:247], v191 offset:56320
	global_load_lds_dwordx4 v[180:181], off
	s_add_i32 m0, s28, 0x2000
	s_add_u32 s26, s26, 0x100080
	v_lshl_add_u64 v[180:181], v[208:209], 0, s[96:97]
	s_addc_u32 s27, s27, 0
	s_add_i32 s28, s68, s9
	global_load_lds_dwordx4 v[180:181], off
	v_lshl_add_u64 v[180:181], s[26:27], 0, v[158:159]
	s_mov_b32 m0, s28
	v_lshl_add_u64 v[170:171], v[170:171], 0, s[96:97]
	global_load_lds_dwordx4 v[180:181], off
	v_lshl_add_u64 v[180:181], s[26:27], 0, v[142:143]
	s_add_i32 m0, s28, 0x2000
	s_nop 0
	global_load_lds_dwordx4 v[180:181], off
	v_lshl_add_u64 v[180:181], v[248:249], 0, s[96:97]
	s_mov_b32 m0, s0
	s_nop 0
	global_load_lds_dwordx4 v[180:181], off
	s_mov_b32 m0, s34
	s_nop 0
	global_load_lds_dwordx4 v[170:171], off
	s_waitcnt vmcnt(8)
	s_waitcnt lgkmcnt(0)
	s_barrier
	v_mfma_f32_16x16x32_bf16 v[54:57], v[122:125], v[204:207], v[54:57]
	v_mfma_f32_16x16x32_bf16 v[62:65], v[130:133], v[204:207], v[62:65]
	v_mfma_f32_16x16x32_bf16 v[38:41], v[122:125], v[224:227], v[38:41]
	v_mfma_f32_16x16x32_bf16 v[50:53], v[130:133], v[224:227], v[50:53]
	v_mfma_f32_16x16x32_bf16 v[22:25], v[122:125], v[232:235], v[22:25]
	v_mfma_f32_16x16x32_bf16 v[34:37], v[130:133], v[232:235], v[34:37]
	v_mfma_f32_16x16x32_bf16 v[6:9], v[122:125], v[240:243], v[6:9]
	v_mfma_f32_16x16x32_bf16 v[18:21], v[130:133], v[240:243], v[18:21]
	v_mfma_f32_16x16x32_bf16 v[54:57], v[126:129], v[220:223], v[54:57]
	v_mfma_f32_16x16x32_bf16 v[62:65], v[172:175], v[220:223], v[62:65]
	v_mfma_f32_16x16x32_bf16 v[38:41], v[126:129], v[228:231], v[38:41]
	v_mfma_f32_16x16x32_bf16 v[50:53], v[172:175], v[228:231], v[50:53]
	v_mfma_f32_16x16x32_bf16 v[22:25], v[126:129], v[236:239], v[22:25]
	v_mfma_f32_16x16x32_bf16 v[34:37], v[172:175], v[236:239], v[34:37]
	v_mfma_f32_16x16x32_bf16 v[6:9], v[126:129], v[244:247], v[6:9]
	v_mfma_f32_16x16x32_bf16 v[18:21], v[172:175], v[244:247], v[18:21]
	v_mfma_f32_16x16x32_bf16 v[58:61], v[176:179], v[204:207], v[58:61]
	v_mfma_f32_16x16x32_bf16 v[46:49], v[196:199], v[204:207], v[46:49]
	v_mfma_f32_16x16x32_bf16 v[42:45], v[176:179], v[224:227], v[42:45]
	v_mfma_f32_16x16x32_bf16 v[30:33], v[196:199], v[224:227], v[30:33]
	v_mfma_f32_16x16x32_bf16 v[26:29], v[176:179], v[232:235], v[26:29]
	v_mfma_f32_16x16x32_bf16 v[14:17], v[196:199], v[232:235], v[14:17]
	v_mfma_f32_16x16x32_bf16 v[10:13], v[176:179], v[240:243], v[10:13]
	v_mfma_f32_16x16x32_bf16 v[2:5], v[196:199], v[240:243], v[2:5]
	v_mfma_f32_16x16x32_bf16 v[58:61], v[192:195], v[220:223], v[58:61]
	v_mfma_f32_16x16x32_bf16 v[46:49], v[200:203], v[220:223], v[46:49]
	v_mfma_f32_16x16x32_bf16 v[42:45], v[192:195], v[228:231], v[42:45]
	v_mfma_f32_16x16x32_bf16 v[30:33], v[200:203], v[228:231], v[30:33]
	v_mfma_f32_16x16x32_bf16 v[26:29], v[192:195], v[236:239], v[26:29]
	v_mfma_f32_16x16x32_bf16 v[14:17], v[200:203], v[236:239], v[14:17]
	v_mfma_f32_16x16x32_bf16 v[10:13], v[192:195], v[244:247], v[10:13]
	v_mfma_f32_16x16x32_bf16 v[2:5], v[200:203], v[244:247], v[2:5]
	s_barrier
	s_add_i32 s17, s17, 2
	s_add_u32 vcc_lo, vcc_lo, 0x100
	s_addc_u32 s16, s16, 0
	s_add_u32 s62, s62, 0x100
	s_addc_u32 s63, s63, 0
	s_cmp_gt_u32 s17, 61
	s_cbranch_scc1 .Lpeel_exit_0
.LBB0_124:
	s_add_u32 s26, s62, 0xfff00080
	s_addc_u32 s27, s63, -1
	s_add_i32 s65, 0, 0x10000
	s_cmp_eq_u32 s17, 60
	s_cselect_b32 s29, s30, s27
	s_cselect_b32 s28, s31, s26
	v_add_u32_e32 v170, s65, v182
	s_cselect_b32 s27, s53, s16
	s_cselect_b32 s26, s55, vcc_lo
	s_add_i32 s70, 0, 0x14000
	ds_read_b128 v[122:125], v170
	ds_read_b128 v[126:129], v170 offset:1024
	ds_read_b128 v[130:133], v170 offset:2048
	ds_read_b128 v[172:175], v170 offset:3072
	v_add_u32_e32 v170, s70, v182
	ds_read_b128 v[176:179], v170
	ds_read_b128 v[192:195], v170 offset:1024
	ds_read_b128 v[196:199], v170 offset:2048
	ds_read_b128 v[200:203], v170 offset:3072
	v_lshl_add_u64 v[180:181], s[62:63], 0, v[156:157]
	s_add_i32 m0, s10, 0xc000
	ds_read_b128 v[204:207], v191
	ds_read_b128 v[220:223], v191 offset:1024
	ds_read_b128 v[224:227], v191 offset:2048
	ds_read_b128 v[228:231], v191 offset:3072
	ds_read_b128 v[232:235], v191 offset:4096
	ds_read_b128 v[236:239], v191 offset:5120
	ds_read_b128 v[240:243], v191 offset:6144
	ds_read_b128 v[244:247], v191 offset:7168
	global_load_lds_dwordx4 v[180:181], off
	v_lshl_add_u64 v[180:181], s[62:63], 0, v[154:155]
	s_add_i32 m0, s10, 0xe000
	s_nop 0
	global_load_lds_dwordx4 v[180:181], off
	s_waitcnt vmcnt(8)
	s_waitcnt lgkmcnt(0)
	s_barrier
; #define PG8_STAGE(bufoff, gbase, voff) do { _Pragma("unroll") for (int _i = 0; _i < 2; ++_i) \
;         __builtin_amdgcn_global_load_lds((const unsigned*)((const char*)(gbase) + (voff)[_i]), (PG8_LAS unsigned*)(lds + (bufoff) + ldsw + _i * 8192), 16, 0, 0); } while (0)
; #define PG8_LDA(dst, b, h) do { _Pragma("unroll") for (int m = 0; m < 4; ++m) _Pragma("unroll") for (int k = 0; k < 2; ++k) dst[m][k] = *(const PG8_LAS bf16x8*)(lds + PG8_SA(b, h) + aoff + m * 2048 + k * 1024); } while (0)
; #define PG8_LDB(dst, b, h) do { _Pragma("unroll") for (int n = 0; n < 2; ++n) _Pragma("unroll") for (int k = 0; k < 2; ++k) dst[n][k] = *(const PG8_LAS bf16x8*)(lds + PG8_SB(b, h) + boff + n * 2048 + k * 1024); } while (0)
; #define PG8_MMA(ai, bj, At, Bt) do { __builtin_amdgcn_s_setprio(1); _Pragma("unroll") for (int m = 0; m < 4; ++m) _Pragma("unroll") for (int n = 0; n < 2; ++n) _Pragma("unroll") for (int k = 0; k < 2; ++k) \
;         acc[ai][bj][m][n] = __builtin_amdgcn_mfma_f32_16x16x32_bf16(Bt[n][k], At[m][k], acc[ai][bj][m][n], 0, 0, 0); __builtin_amdgcn_s_setprio(0); } while (0)
; #define PG8_WAIT_V(n) asm volatile("s_waitcnt vmcnt(" #n ")" ::: "memory")
; #define PG8_WAIT_L(n) asm volatile("s_waitcnt lgkmcnt(" #n ")" ::: "memory")
; #define PG8_BAR __builtin_amdgcn_s_barrier()
; #define PG8_SCHED __builtin_amdgcn_sched_barrier(0)
; template <class Epi, class Sched, bool ALIGN_EPI = false, bool SP2 = false>
; __device__ __forceinline__ void gemm_phase(PG8_LAS unsigned char* lds, const Gemm g, const Sched& S, const Epi& E) {
;     ...
;             PG8_LDB(B0, 0, 0); PG8_LDB(B1, 0, 1); PG8_SCHED; PG8_LDA(At, 0, 0); PG8_STAGE(PG8_SA(1, 1), a1 + hstep, voffA);
;             PG8_WAIT_V(8); PG8_WAIT_L(0); PG8_BAR; PG8_MMA(0, 0, At, B0); PG8_MMA(0, 1, At, B1); PG8_BAR; PG8_SCHED;
;             PG8_LDA(At, 0, 1); PG8_STAGE(PG8_SB(0, 0), b2, voffB); PG8_STAGE(PG8_SB(0, 1), b2 + hstep, voffB); PG8_STAGE(PG8_SA(0, 0), a2, voffA);
;             PG8_WAIT_V(8); PG8_WAIT_L(0); PG8_BAR; PG8_MMA(1, 0, At, B0); PG8_MMA(1, 1, At, B1); PG8_BAR; PG8_SCHED;
	v_mfma_f32_16x16x32_bf16 v[118:121], v[122:125], v[204:207], v[118:121]
	v_mfma_f32_16x16x32_bf16 v[138:141], v[130:133], v[204:207], v[138:141]
	v_mfma_f32_16x16x32_bf16 v[102:105], v[122:125], v[224:227], v[102:105]
	v_mfma_f32_16x16x32_bf16 v[114:117], v[130:133], v[224:227], v[114:117]
	v_mfma_f32_16x16x32_bf16 v[86:89], v[122:125], v[232:235], v[86:89]
	v_mfma_f32_16x16x32_bf16 v[98:101], v[130:133], v[232:235], v[98:101]
	v_mfma_f32_16x16x32_bf16 v[70:73], v[122:125], v[240:243], v[70:73]
	v_mfma_f32_16x16x32_bf16 v[82:85], v[130:133], v[240:243], v[82:85]
	v_mfma_f32_16x16x32_bf16 v[118:121], v[126:129], v[220:223], v[118:121]
	v_mfma_f32_16x16x32_bf16 v[138:141], v[172:175], v[220:223], v[138:141]
	v_mfma_f32_16x16x32_bf16 v[102:105], v[126:129], v[228:231], v[102:105]
	v_mfma_f32_16x16x32_bf16 v[114:117], v[172:175], v[228:231], v[114:117]
	v_mfma_f32_16x16x32_bf16 v[86:89], v[126:129], v[236:239], v[86:89]
	v_mfma_f32_16x16x32_bf16 v[98:101], v[172:175], v[236:239], v[98:101]
	v_mfma_f32_16x16x32_bf16 v[70:73], v[126:129], v[244:247], v[70:73]
	v_mfma_f32_16x16x32_bf16 v[82:85], v[172:175], v[244:247], v[82:85]
	v_mfma_f32_16x16x32_bf16 v[134:137], v[176:179], v[204:207], v[134:137]
	v_mfma_f32_16x16x32_bf16 v[110:113], v[196:199], v[204:207], v[110:113]
	v_mfma_f32_16x16x32_bf16 v[106:109], v[176:179], v[224:227], v[106:109]
	v_mfma_f32_16x16x32_bf16 v[94:97], v[196:199], v[224:227], v[94:97]
	v_mfma_f32_16x16x32_bf16 v[90:93], v[176:179], v[232:235], v[90:93]
	v_mfma_f32_16x16x32_bf16 v[78:81], v[196:199], v[232:235], v[78:81]
	v_mfma_f32_16x16x32_bf16 v[74:77], v[176:179], v[240:243], v[74:77]
	v_mfma_f32_16x16x32_bf16 v[66:69], v[196:199], v[240:243], v[66:69]
	v_mfma_f32_16x16x32_bf16 v[134:137], v[192:195], v[220:223], v[134:137]
	v_mfma_f32_16x16x32_bf16 v[110:113], v[200:203], v[220:223], v[110:113]
	v_mfma_f32_16x16x32_bf16 v[106:109], v[192:195], v[228:231], v[106:109]
	v_mfma_f32_16x16x32_bf16 v[94:97], v[200:203], v[228:231], v[94:97]
	v_mfma_f32_16x16x32_bf16 v[90:93], v[192:195], v[236:239], v[90:93]
	v_mfma_f32_16x16x32_bf16 v[78:81], v[200:203], v[236:239], v[78:81]
	v_mfma_f32_16x16x32_bf16 v[74:77], v[192:195], v[244:247], v[74:77]
	v_mfma_f32_16x16x32_bf16 v[66:69], v[200:203], v[244:247], v[66:69]
	s_barrier
	s_add_i32 s65, s65, s9
	v_lshl_add_u64 v[180:181], s[26:27], 0, v[158:159]
	s_mov_b32 m0, s65
	ds_read_b128 v[204:207], v191 offset:16384
	ds_read_b128 v[220:223], v191 offset:17408
	ds_read_b128 v[224:227], v191 offset:18432
	ds_read_b128 v[228:231], v191 offset:19456
	ds_read_b128 v[232:235], v191 offset:20480
	ds_read_b128 v[236:239], v191 offset:21504
	ds_read_b128 v[240:243], v191 offset:22528
	ds_read_b128 v[244:247], v191 offset:23552
	global_load_lds_dwordx4 v[180:181], off
	s_add_i32 m0, s65, 0x2000
	s_add_u32 s68, s26, 0x100000
	v_lshl_add_u64 v[208:209], s[26:27], 0, v[142:143]
	s_addc_u32 s69, s27, 0
	s_add_i32 s65, s70, s9
	global_load_lds_dwordx4 v[208:209], off
	v_lshl_add_u64 v[248:249], s[68:69], 0, v[158:159]
	s_mov_b32 m0, s65
	v_lshl_add_u64 v[170:171], s[28:29], 0, v[144:145]
	global_load_lds_dwordx4 v[248:249], off
	v_lshl_add_u64 v[248:249], s[68:69], 0, v[142:143]
	s_add_i32 m0, s65, 0x2000
	s_nop 0
	global_load_lds_dwordx4 v[248:249], off
	v_lshl_add_u64 v[248:249], s[28:29], 0, v[146:147]
	s_mov_b32 m0, s10
	s_nop 0
	global_load_lds_dwordx4 v[248:249], off
	s_mov_b32 m0, s11
	s_nop 0
	global_load_lds_dwordx4 v[170:171], off
	s_waitcnt vmcnt(8)
	s_waitcnt lgkmcnt(0)
	s_barrier
	v_mfma_f32_16x16x32_bf16 v[54:57], v[122:125], v[204:207], v[54:57]
	v_mfma_f32_16x16x32_bf16 v[62:65], v[130:133], v[204:207], v[62:65]
	v_mfma_f32_16x16x32_bf16 v[38:41], v[122:125], v[224:227], v[38:41]
	v_mfma_f32_16x16x32_bf16 v[50:53], v[130:133], v[224:227], v[50:53]
	v_mfma_f32_16x16x32_bf16 v[22:25], v[122:125], v[232:235], v[22:25]
	v_mfma_f32_16x16x32_bf16 v[34:37], v[130:133], v[232:235], v[34:37]
	v_mfma_f32_16x16x32_bf16 v[6:9], v[122:125], v[240:243], v[6:9]
	v_mfma_f32_16x16x32_bf16 v[18:21], v[130:133], v[240:243], v[18:21]
	v_mfma_f32_16x16x32_bf16 v[54:57], v[126:129], v[220:223], v[54:57]
	v_mfma_f32_16x16x32_bf16 v[62:65], v[172:175], v[220:223], v[62:65]
	v_mfma_f32_16x16x32_bf16 v[38:41], v[126:129], v[228:231], v[38:41]
	v_mfma_f32_16x16x32_bf16 v[50:53], v[172:175], v[228:231], v[50:53]
	v_mfma_f32_16x16x32_bf16 v[22:25], v[126:129], v[236:239], v[22:25]
	v_mfma_f32_16x16x32_bf16 v[34:37], v[172:175], v[236:239], v[34:37]
	v_mfma_f32_16x16x32_bf16 v[6:9], v[126:129], v[244:247], v[6:9]
	v_mfma_f32_16x16x32_bf16 v[18:21], v[172:175], v[244:247], v[18:21]
	v_mfma_f32_16x16x32_bf16 v[58:61], v[176:179], v[204:207], v[58:61]
	v_mfma_f32_16x16x32_bf16 v[46:49], v[196:199], v[204:207], v[46:49]
	v_mfma_f32_16x16x32_bf16 v[42:45], v[176:179], v[224:227], v[42:45]
	v_mfma_f32_16x16x32_bf16 v[30:33], v[196:199], v[224:227], v[30:33]
	v_mfma_f32_16x16x32_bf16 v[26:29], v[176:179], v[232:235], v[26:29]
	v_mfma_f32_16x16x32_bf16 v[14:17], v[196:199], v[232:235], v[14:17]
	v_mfma_f32_16x16x32_bf16 v[10:13], v[176:179], v[240:243], v[10:13]
	v_mfma_f32_16x16x32_bf16 v[2:5], v[196:199], v[240:243], v[2:5]
	v_mfma_f32_16x16x32_bf16 v[58:61], v[192:195], v[220:223], v[58:61]
	v_mfma_f32_16x16x32_bf16 v[46:49], v[200:203], v[220:223], v[46:49]
	v_mfma_f32_16x16x32_bf16 v[42:45], v[192:195], v[228:231], v[42:45]
	v_mfma_f32_16x16x32_bf16 v[30:33], v[200:203], v[228:231], v[30:33]
	v_mfma_f32_16x16x32_bf16 v[26:29], v[192:195], v[236:239], v[26:29]
	v_mfma_f32_16x16x32_bf16 v[14:17], v[200:203], v[236:239], v[14:17]
	v_mfma_f32_16x16x32_bf16 v[10:13], v[192:195], v[244:247], v[10:13]
	v_mfma_f32_16x16x32_bf16 v[2:5], v[200:203], v[244:247], v[2:5]
	s_barrier
; #define PG8_STAGE(bufoff, gbase, voff) do { _Pragma("unroll") for (int _i = 0; _i < 2; ++_i) \
;         __builtin_amdgcn_global_load_lds((const unsigned*)((const char*)(gbase) + (voff)[_i]), (PG8_LAS unsigned*)(lds + (bufoff) + ldsw + _i * 8192), 16, 0, 0); } while (0)
; #define PG8_LDA(dst, b, h) do { _Pragma("unroll") for (int m = 0; m < 4; ++m) _Pragma("unroll") for (int k = 0; k < 2; ++k) dst[m][k] = *(const PG8_LAS bf16x8*)(lds + PG8_SA(b, h) + aoff + m * 2048 + k * 1024); } while (0)
; #define PG8_LDB(dst, b, h) do { _Pragma("unroll") for (int n = 0; n < 2; ++n) _Pragma("unroll") for (int k = 0; k < 2; ++k) dst[n][k] = *(const PG8_LAS bf16x8*)(lds + PG8_SB(b, h) + boff + n * 2048 + k * 1024); } while (0)
; #define PG8_MMA(ai, bj, At, Bt) do { __builtin_amdgcn_s_setprio(1); _Pragma("unroll") for (int m = 0; m < 4; ++m) _Pragma("unroll") for (int n = 0; n < 2; ++n) _Pragma("unroll") for (int k = 0; k < 2; ++k) \
;         acc[ai][bj][m][n] = __builtin_amdgcn_mfma_f32_16x16x32_bf16(Bt[n][k], At[m][k], acc[ai][bj][m][n], 0, 0, 0); __builtin_amdgcn_s_setprio(0); } while (0)
; #define PG8_WAIT_V(n) asm volatile("s_waitcnt vmcnt(" #n ")" ::: "memory")
; #define PG8_WAIT_L(n) asm volatile("s_waitcnt lgkmcnt(" #n ")" ::: "memory")
; #define PG8_BAR __builtin_amdgcn_s_barrier()
; #define PG8_SCHED __builtin_amdgcn_sched_barrier(0)
; template <class Epi, class Sched, bool ALIGN_EPI = false, bool SP2 = false>
; __device__ __forceinline__ void gemm_phase(PG8_LAS unsigned char* lds, const Gemm g, const Sched& S, const Epi& E) {
;     ...
;             PG8_LDB(B0, 1, 0); PG8_LDB(B1, 1, 1); PG8_SCHED; PG8_LDA(At, 1, 0); PG8_STAGE(PG8_SA(0, 1), a2 + hstep, voffA);
;             PG8_WAIT_V(8); PG8_WAIT_L(0); PG8_BAR; PG8_MMA(0, 0, At, B0); PG8_MMA(0, 1, At, B1); PG8_BAR; PG8_SCHED;
;             PG8_LDA(At, 1, 1); PG8_STAGE(PG8_SB(1, 0), b3, voffB); PG8_STAGE(PG8_SB(1, 1), b3 + hstep, voffB); PG8_STAGE(PG8_SA(1, 0), a3, voffA);
;             PG8_WAIT_V(8); PG8_WAIT_L(0); PG8_BAR; PG8_MMA(1, 0, At, B0); PG8_MMA(1, 1, At, B1); PG8_BAR; PG8_SCHED;
	s_add_i32 s65, 0, 0x18000
	s_add_i32 s68, 0, 0x1c000
	v_add_u32_e32 v172, s65, v182
	v_add_u32_e32 v200, s68, v182
	ds_read_b128 v[122:125], v172
	ds_read_b128 v[126:129], v172 offset:1024
	ds_read_b128 v[130:133], v172 offset:2048
	ds_read_b128 v[172:175], v172 offset:3072
	ds_read_b128 v[176:179], v200
	ds_read_b128 v[192:195], v200 offset:1024
	ds_read_b128 v[196:199], v200 offset:2048
	ds_read_b128 v[200:203], v200 offset:3072
	s_add_u32 s28, s28, 0x100000
	s_addc_u32 s29, s29, 0
	s_mov_b32 m0, s12
	v_lshl_add_u64 v[210:211], s[28:29], 0, v[146:147]
	ds_read_b128 v[204:207], v191 offset:32768
	ds_read_b128 v[220:223], v191 offset:33792
	ds_read_b128 v[224:227], v191 offset:34816
	ds_read_b128 v[228:231], v191 offset:35840
	ds_read_b128 v[232:235], v191 offset:36864
	ds_read_b128 v[236:239], v191 offset:37888
	ds_read_b128 v[240:243], v191 offset:38912
	ds_read_b128 v[244:247], v191 offset:39936
	global_load_lds_dwordx4 v[210:211], off
	v_lshl_add_u64 v[210:211], s[28:29], 0, v[144:145]
	s_mov_b32 m0, s13
	s_nop 0
	global_load_lds_dwordx4 v[210:211], off
	s_waitcnt vmcnt(8)
	s_waitcnt lgkmcnt(0)
	s_barrier
	v_mfma_f32_16x16x32_bf16 v[118:121], v[122:125], v[204:207], v[118:121]
	v_mfma_f32_16x16x32_bf16 v[138:141], v[130:133], v[204:207], v[138:141]
	v_mfma_f32_16x16x32_bf16 v[102:105], v[122:125], v[224:227], v[102:105]
	v_mfma_f32_16x16x32_bf16 v[114:117], v[130:133], v[224:227], v[114:117]
	v_mfma_f32_16x16x32_bf16 v[86:89], v[122:125], v[232:235], v[86:89]
	v_mfma_f32_16x16x32_bf16 v[98:101], v[130:133], v[232:235], v[98:101]
	v_mfma_f32_16x16x32_bf16 v[70:73], v[122:125], v[240:243], v[70:73]
	v_mfma_f32_16x16x32_bf16 v[82:85], v[130:133], v[240:243], v[82:85]
	v_mfma_f32_16x16x32_bf16 v[118:121], v[126:129], v[220:223], v[118:121]
	v_mfma_f32_16x16x32_bf16 v[138:141], v[172:175], v[220:223], v[138:141]
	v_mfma_f32_16x16x32_bf16 v[102:105], v[126:129], v[228:231], v[102:105]
	v_mfma_f32_16x16x32_bf16 v[114:117], v[172:175], v[228:231], v[114:117]
	v_mfma_f32_16x16x32_bf16 v[86:89], v[126:129], v[236:239], v[86:89]
	v_mfma_f32_16x16x32_bf16 v[98:101], v[172:175], v[236:239], v[98:101]
	v_mfma_f32_16x16x32_bf16 v[70:73], v[126:129], v[244:247], v[70:73]
	v_mfma_f32_16x16x32_bf16 v[82:85], v[172:175], v[244:247], v[82:85]
	v_mfma_f32_16x16x32_bf16 v[134:137], v[176:179], v[204:207], v[134:137]
	v_mfma_f32_16x16x32_bf16 v[110:113], v[196:199], v[204:207], v[110:113]
	v_mfma_f32_16x16x32_bf16 v[106:109], v[176:179], v[224:227], v[106:109]
	v_mfma_f32_16x16x32_bf16 v[94:97], v[196:199], v[224:227], v[94:97]
	v_mfma_f32_16x16x32_bf16 v[90:93], v[176:179], v[232:235], v[90:93]
	v_mfma_f32_16x16x32_bf16 v[78:81], v[196:199], v[232:235], v[78:81]
	v_mfma_f32_16x16x32_bf16 v[74:77], v[176:179], v[240:243], v[74:77]
	v_mfma_f32_16x16x32_bf16 v[66:69], v[196:199], v[240:243], v[66:69]
	v_mfma_f32_16x16x32_bf16 v[134:137], v[192:195], v[220:223], v[134:137]
	v_mfma_f32_16x16x32_bf16 v[110:113], v[200:203], v[220:223], v[110:113]
	v_mfma_f32_16x16x32_bf16 v[106:109], v[192:195], v[228:231], v[106:109]
	v_mfma_f32_16x16x32_bf16 v[94:97], v[200:203], v[228:231], v[94:97]
	v_mfma_f32_16x16x32_bf16 v[90:93], v[192:195], v[236:239], v[90:93]
	v_mfma_f32_16x16x32_bf16 v[78:81], v[200:203], v[236:239], v[78:81]
	v_mfma_f32_16x16x32_bf16 v[74:77], v[192:195], v[244:247], v[74:77]
	v_mfma_f32_16x16x32_bf16 v[66:69], v[200:203], v[244:247], v[66:69]
	s_barrier
	s_add_i32 s28, s65, s9
	v_lshl_add_u64 v[180:181], v[180:181], 0, s[96:97]
	s_mov_b32 m0, s28
	ds_read_b128 v[204:207], v191 offset:49152
	ds_read_b128 v[220:223], v191 offset:50176
	ds_read_b128 v[224:227], v191 offset:51200
	ds_read_b128 v[228:231], v191 offset:52224
	ds_read_b128 v[232:235], v191 offset:53248
	ds_read_b128 v[236:239], v191 offset:54272
	ds_read_b128 v[240:243], v191 offset:55296
	ds_read_b128 v[244:247], v191 offset:56320
	global_load_lds_dwordx4 v[180:181], off
	s_add_i32 m0, s28, 0x2000
	s_add_u32 s26, s26, 0x100080
	v_lshl_add_u64 v[180:181], v[208:209], 0, s[96:97]
	s_addc_u32 s27, s27, 0
	s_add_i32 s28, s68, s9
	global_load_lds_dwordx4 v[180:181], off
	v_lshl_add_u64 v[180:181], s[26:27], 0, v[158:159]
	s_mov_b32 m0, s28
	v_lshl_add_u64 v[170:171], v[170:171], 0, s[96:97]
	global_load_lds_dwordx4 v[180:181], off
	v_lshl_add_u64 v[180:181], s[26:27], 0, v[142:143]
	s_add_i32 m0, s28, 0x2000
	s_nop 0
	global_load_lds_dwordx4 v[180:181], off
	v_lshl_add_u64 v[180:181], v[248:249], 0, s[96:97]
	s_mov_b32 m0, s0
	s_nop 0
	global_load_lds_dwordx4 v[180:181], off
	s_mov_b32 m0, s34
	s_nop 0
	global_load_lds_dwordx4 v[170:171], off
	s_waitcnt vmcnt(8)
	s_waitcnt lgkmcnt(0)
	s_barrier
	v_mfma_f32_16x16x32_bf16 v[54:57], v[122:125], v[204:207], v[54:57]
	v_mfma_f32_16x16x32_bf16 v[62:65], v[130:133], v[204:207], v[62:65]
	v_mfma_f32_16x16x32_bf16 v[38:41], v[122:125], v[224:227], v[38:41]
	v_mfma_f32_16x16x32_bf16 v[50:53], v[130:133], v[224:227], v[50:53]
	v_mfma_f32_16x16x32_bf16 v[22:25], v[122:125], v[232:235], v[22:25]
	v_mfma_f32_16x16x32_bf16 v[34:37], v[130:133], v[232:235], v[34:37]
	v_mfma_f32_16x16x32_bf16 v[6:9], v[122:125], v[240:243], v[6:9]
	v_mfma_f32_16x16x32_bf16 v[18:21], v[130:133], v[240:243], v[18:21]
	v_mfma_f32_16x16x32_bf16 v[54:57], v[126:129], v[220:223], v[54:57]
	v_mfma_f32_16x16x32_bf16 v[62:65], v[172:175], v[220:223], v[62:65]
	v_mfma_f32_16x16x32_bf16 v[38:41], v[126:129], v[228:231], v[38:41]
	v_mfma_f32_16x16x32_bf16 v[50:53], v[172:175], v[228:231], v[50:53]
	v_mfma_f32_16x16x32_bf16 v[22:25], v[126:129], v[236:239], v[22:25]
	v_mfma_f32_16x16x32_bf16 v[34:37], v[172:175], v[236:239], v[34:37]
	v_mfma_f32_16x16x32_bf16 v[6:9], v[126:129], v[244:247], v[6:9]
	v_mfma_f32_16x16x32_bf16 v[18:21], v[172:175], v[244:247], v[18:21]
	v_mfma_f32_16x16x32_bf16 v[58:61], v[176:179], v[204:207], v[58:61]
	v_mfma_f32_16x16x32_bf16 v[46:49], v[196:199], v[204:207], v[46:49]
	v_mfma_f32_16x16x32_bf16 v[42:45], v[176:179], v[224:227], v[42:45]
	v_mfma_f32_16x16x32_bf16 v[30:33], v[196:199], v[224:227], v[30:33]
	v_mfma_f32_16x16x32_bf16 v[26:29], v[176:179], v[232:235], v[26:29]
	v_mfma_f32_16x16x32_bf16 v[14:17], v[196:199], v[232:235], v[14:17]
	v_mfma_f32_16x16x32_bf16 v[10:13], v[176:179], v[240:243], v[10:13]
	v_mfma_f32_16x16x32_bf16 v[2:5], v[196:199], v[240:243], v[2:5]
	v_mfma_f32_16x16x32_bf16 v[58:61], v[192:195], v[220:223], v[58:61]
	v_mfma_f32_16x16x32_bf16 v[46:49], v[200:203], v[220:223], v[46:49]
	v_mfma_f32_16x16x32_bf16 v[42:45], v[192:195], v[228:231], v[42:45]
	v_mfma_f32_16x16x32_bf16 v[30:33], v[200:203], v[228:231], v[30:33]
	v_mfma_f32_16x16x32_bf16 v[26:29], v[192:195], v[236:239], v[26:29]
	v_mfma_f32_16x16x32_bf16 v[14:17], v[200:203], v[236:239], v[14:17]
	v_mfma_f32_16x16x32_bf16 v[10:13], v[192:195], v[244:247], v[10:13]
	v_mfma_f32_16x16x32_bf16 v[2:5], v[200:203], v[244:247], v[2:5]
	s_barrier
	s_add_i32 s17, s17, 2
	s_add_u32 vcc_lo, vcc_lo, 0x100
	s_addc_u32 s16, s16, 0
	s_add_u32 s62, s62, 0x100
	s_addc_u32 s63, s63, 0
	s_cmp_gt_u32 s17, 61
	s_cbranch_scc0 .LBB0_124

;     __host__ __device__ bool next(int i, Unit& u) const { return at((long)i * G + c, u); }
; #define PG8_STAGE(bufoff, gbase, voff) do { _Pragma("unroll") for (int _i = 0; _i < 2; ++_i) \
;         __builtin_amdgcn_global_load_lds((const unsigned*)((const char*)(gbase) + (voff)[_i]), (PG8_LAS unsigned*)(lds + (bufoff) + ldsw + _i * 8192), 16, 0, 0); } while (0)
; #define PG8_LDA(dst, b, h) do { _Pragma("unroll") for (int m = 0; m < 4; ++m) _Pragma("unroll") for (int k = 0; k < 2; ++k) dst[m][k] = *(const PG8_LAS bf16x8*)(lds + PG8_SA(b, h) + aoff + m * 2048 + k * 1024); } while (0)
; #define PG8_LDB(dst, b, h) do { _Pragma("unroll") for (int n = 0; n < 2; ++n) _Pragma("unroll") for (int k = 0; k < 2; ++k) dst[n][k] = *(const PG8_LAS bf16x8*)(lds + PG8_SB(b, h) + boff + n * 2048 + k * 1024); } while (0)
; #define PG8_WAIT_V(n) asm volatile("s_waitcnt vmcnt(" #n ")" ::: "memory")
; #define PG8_BAR __builtin_amdgcn_s_barrier()
; template <class Epi, class Sched, bool ALIGN_EPI = false, bool SP2 = false>
; __device__ __forceinline__ void gemm_phase(PG8_LAS unsigned char* lds, const Gemm g, const Sched& S, const Epi& E) {
;     ...
;         const bool has_next = S.next(ui + 1, nxt);
;         const char* nA = has_next ? (const char*)g.A + (size_t)nxt.pm * tstep + (size_t)nxt.k0 * kstep : cA; const char* nB = has_next ? (const char*)g.Bt + (size_t)nxt.pn * tstep + (size_t)nxt.k0 * kstep : cB;
;         const int nt = cur.nt;
;         for (int t = 0; t < nt; t += 2) {
;             const bool last = (t == nt - 2);
;             const char* a1 = cA + (size_t)(t + 1) * kstep;
;             const char* a2 = last ? nA : cA + (size_t)(t + 2) * kstep; const char* b2 = last ? nB : cB + (size_t)(t + 2) * kstep;
;             const char* a3 = a2 + kstep; const char* b3 = b2 + kstep;
;             if (last && has_next) S.a_ready(nxt);
;             if constexpr (SP2) {
;             PG8_LDB(B0, 0, 0); PG8_LDB(B1, 0, 1); PG8_SCHED; PG8_LDA(At, 0, 0); PG8_STAGE(PG8_SA(1, 1), a1 + hstep, voffA);
;             PG8_WAIT_V(8); PG8_WAIT_L(0); PG8_BAR; PG8_MMA(0, 0, At, B0); PG8_MMA(0, 1, At, B1); PG8_BAR; PG8_SCHED;
;             PG8_LDA(At, 0, 1); PG8_STAGE(PG8_SB(0, 0), b2, voffB); PG8_STAGE(PG8_SB(0, 1), b2 + hstep, voffB); PG8_STAGE(PG8_SA(0, 0), a2, voffA);
;             PG8_WAIT_V(8); PG8_WAIT_L(0); PG8_BAR; PG8_MMA(1, 0, At, B0); PG8_MMA(1, 1, At, B1); PG8_BAR; PG8_SCHED;
.LBB0_418:
	s_ashr_i32 s41, s40, 31
	s_lshl_b64 s[16:17], s[40:41], 20
	s_add_u32 s44, s20, s16
	s_addc_u32 s45, s21, s17
	s_and_b64 s[16:17], s[42:43], exec
	s_cselect_b32 s15, s45, s29
	s_cselect_b32 s30, s44, s28
	s_ashr_i32 s39, s38, 31
	s_lshl_b64 s[16:17], s[38:39], 20
	s_add_u32 s46, s0, s16
	s_addc_u32 s47, s4, s17
	s_and_b64 s[16:17], s[42:43], exec
	s_cselect_b32 s31, s47, s27
	s_cselect_b32 s34, s46, s26
	s_add_u32 s35, s26, 0x100
	s_addc_u32 s16, s27, 0
	s_add_u32 s48, s28, 0x80080
	s_addc_u32 s49, s29, 0
	s_mov_b32 s17, -2
	s_waitcnt vmcnt(0)
	s_waitcnt vmcnt(0)
	s_add_u32 s26, s48, 0xfff80080
	s_addc_u32 s27, s49, -1
	s_add_i32 s39, 0, 0x10000
	s_cmp_eq_u32 s17, 28
	s_cselect_b32 s29, s15, s27
	s_cselect_b32 s28, s30, s26
	s_cselect_b32 s27, s31, s16
	s_cselect_b32 s26, s34, s35
	s_add_i32 s41, 0, 0x14000
	v_add_u32_e32 v142, s39, v190
	v_add_u32_e32 v170, s41, v190
	ds_read_b128 v[130:133], v142
	ds_read_b128 v[134:137], v142 offset:1024
	ds_read_b128 v[138:141], v142 offset:2048
	ds_read_b128 v[142:145], v142 offset:3072
	ds_read_b128 v[146:149], v170
	ds_read_b128 v[150:153], v170 offset:1024
	ds_read_b128 v[178:181], v170 offset:2048
	ds_read_b128 v[182:185], v170 offset:3072
	v_lshl_add_u64 v[170:171], s[48:49], 0, v[176:177]
	s_add_i32 m0, s6, 0xc000
	ds_read_b128 v[186:189], v192
	ds_read_b128 v[194:197], v192 offset:1024
	ds_read_b128 v[198:201], v192 offset:2048
	ds_read_b128 v[202:205], v192 offset:3072
	ds_read_b128 v[206:209], v192 offset:4096
	ds_read_b128 v[220:223], v192 offset:5120
	ds_read_b128 v[224:227], v192 offset:6144
	ds_read_b128 v[228:231], v192 offset:7168
	global_load_lds_dwordx4 v[170:171], off
	v_lshl_add_u64 v[170:171], s[48:49], 0, v[174:175]
	s_add_i32 m0, s6, 0xe000
	s_nop 0
	global_load_lds_dwordx4 v[170:171], off
	s_waitcnt vmcnt(8)
	s_waitcnt lgkmcnt(0)
	s_barrier
	v_mfma_f32_16x16x32_bf16 v[126:129], v[130:133], v[186:189], 0
	v_mfma_f32_16x16x32_bf16 v[122:125], v[138:141], v[186:189], 0
	v_mfma_f32_16x16x32_bf16 v[110:113], v[130:133], v[198:201], 0
	v_mfma_f32_16x16x32_bf16 v[106:109], v[138:141], v[198:201], 0
	v_mfma_f32_16x16x32_bf16 v[94:97], v[130:133], v[206:209], 0
	v_mfma_f32_16x16x32_bf16 v[90:93], v[138:141], v[206:209], 0
	v_mfma_f32_16x16x32_bf16 v[78:81], v[130:133], v[224:227], 0
	v_mfma_f32_16x16x32_bf16 v[74:77], v[138:141], v[224:227], 0
	v_mfma_f32_16x16x32_bf16 v[126:129], v[134:137], v[194:197], v[126:129]
	v_mfma_f32_16x16x32_bf16 v[122:125], v[142:145], v[194:197], v[122:125]
	v_mfma_f32_16x16x32_bf16 v[110:113], v[134:137], v[202:205], v[110:113]
	v_mfma_f32_16x16x32_bf16 v[106:109], v[142:145], v[202:205], v[106:109]
	v_mfma_f32_16x16x32_bf16 v[94:97], v[134:137], v[220:223], v[94:97]
	v_mfma_f32_16x16x32_bf16 v[90:93], v[142:145], v[220:223], v[90:93]
	v_mfma_f32_16x16x32_bf16 v[78:81], v[134:137], v[228:231], v[78:81]
	v_mfma_f32_16x16x32_bf16 v[74:77], v[142:145], v[228:231], v[74:77]
	v_mfma_f32_16x16x32_bf16 v[118:121], v[146:149], v[186:189], 0
	v_mfma_f32_16x16x32_bf16 v[114:117], v[178:181], v[186:189], 0
	v_mfma_f32_16x16x32_bf16 v[102:105], v[146:149], v[198:201], 0
	v_mfma_f32_16x16x32_bf16 v[98:101], v[178:181], v[198:201], 0
	v_mfma_f32_16x16x32_bf16 v[86:89], v[146:149], v[206:209], 0
	v_mfma_f32_16x16x32_bf16 v[82:85], v[178:181], v[206:209], 0
	v_mfma_f32_16x16x32_bf16 v[70:73], v[146:149], v[224:227], 0
	v_mfma_f32_16x16x32_bf16 v[66:69], v[178:181], v[224:227], 0
	v_mfma_f32_16x16x32_bf16 v[118:121], v[150:153], v[194:197], v[118:121]
	v_mfma_f32_16x16x32_bf16 v[114:117], v[182:185], v[194:197], v[114:117]
	v_mfma_f32_16x16x32_bf16 v[102:105], v[150:153], v[202:205], v[102:105]
	v_mfma_f32_16x16x32_bf16 v[98:101], v[182:185], v[202:205], v[98:101]
	v_mfma_f32_16x16x32_bf16 v[86:89], v[150:153], v[220:223], v[86:89]
	v_mfma_f32_16x16x32_bf16 v[82:85], v[182:185], v[220:223], v[82:85]
	v_mfma_f32_16x16x32_bf16 v[70:73], v[150:153], v[228:231], v[70:73]
	v_mfma_f32_16x16x32_bf16 v[66:69], v[182:185], v[228:231], v[66:69]
	s_barrier
	s_add_i32 s39, s39, s5
	v_lshl_add_u64 v[170:171], s[26:27], 0, v[158:159]
	s_mov_b32 m0, s39
	ds_read_b128 v[186:189], v192 offset:16384
	ds_read_b128 v[194:197], v192 offset:17408
	ds_read_b128 v[198:201], v192 offset:18432
	ds_read_b128 v[202:205], v192 offset:19456
	ds_read_b128 v[206:209], v192 offset:20480
	ds_read_b128 v[220:223], v192 offset:21504
	ds_read_b128 v[224:227], v192 offset:22528
	ds_read_b128 v[228:231], v192 offset:23552
	global_load_lds_dwordx4 v[170:171], off
	s_add_i32 m0, s39, 0x2000
	s_add_u32 s50, s26, 0x80000
	v_lshl_add_u64 v[210:211], s[26:27], 0, v[154:155]
	s_addc_u32 s51, s27, 0
	s_add_i32 s39, s41, s5
	global_load_lds_dwordx4 v[210:211], off
	v_lshl_add_u64 v[232:233], s[50:51], 0, v[158:159]
	s_mov_b32 m0, s39
	v_lshl_add_u64 v[234:235], s[28:29], 0, v[156:157]
	global_load_lds_dwordx4 v[232:233], off
	v_lshl_add_u64 v[232:233], s[50:51], 0, v[154:155]
	s_add_i32 m0, s39, 0x2000
	s_nop 0
	global_load_lds_dwordx4 v[232:233], off
	v_lshl_add_u64 v[232:233], s[28:29], 0, v[172:173]
	s_mov_b32 m0, s6
	s_nop 0
	global_load_lds_dwordx4 v[232:233], off
	s_mov_b32 m0, s7
	s_nop 0
	global_load_lds_dwordx4 v[234:235], off
	s_waitcnt vmcnt(8)
	s_waitcnt lgkmcnt(0)
	s_barrier
; #define PG8_STAGE(bufoff, gbase, voff) do { _Pragma("unroll") for (int _i = 0; _i < 2; ++_i) \
;         __builtin_amdgcn_global_load_lds((const unsigned*)((const char*)(gbase) + (voff)[_i]), (PG8_LAS unsigned*)(lds + (bufoff) + ldsw + _i * 8192), 16, 0, 0); } while (0)
; #define PG8_LDA(dst, b, h) do { _Pragma("unroll") for (int m = 0; m < 4; ++m) _Pragma("unroll") for (int k = 0; k < 2; ++k) dst[m][k] = *(const PG8_LAS bf16x8*)(lds + PG8_SA(b, h) + aoff + m * 2048 + k * 1024); } while (0)
; #define PG8_LDB(dst, b, h) do { _Pragma("unroll") for (int n = 0; n < 2; ++n) _Pragma("unroll") for (int k = 0; k < 2; ++k) dst[n][k] = *(const PG8_LAS bf16x8*)(lds + PG8_SB(b, h) + boff + n * 2048 + k * 1024); } while (0)
; #define PG8_MMA(ai, bj, At, Bt) do { __builtin_amdgcn_s_setprio(1); _Pragma("unroll") for (int m = 0; m < 4; ++m) _Pragma("unroll") for (int n = 0; n < 2; ++n) _Pragma("unroll") for (int k = 0; k < 2; ++k) \
;         acc[ai][bj][m][n] = __builtin_amdgcn_mfma_f32_16x16x32_bf16(Bt[n][k], At[m][k], acc[ai][bj][m][n], 0, 0, 0); __builtin_amdgcn_s_setprio(0); } while (0)
; #define PG8_WAIT_V(n) asm volatile("s_waitcnt vmcnt(" #n ")" ::: "memory")
; #define PG8_WAIT_L(n) asm volatile("s_waitcnt lgkmcnt(" #n ")" ::: "memory")
; #define PG8_BAR __builtin_amdgcn_s_barrier()
; #define PG8_SCHED __builtin_amdgcn_sched_barrier(0)
; template <class Epi, class Sched, bool ALIGN_EPI = false, bool SP2 = false>
; __device__ __forceinline__ void gemm_phase(PG8_LAS unsigned char* lds, const Gemm g, const Sched& S, const Epi& E) {
;     ...
;             PG8_WAIT_V(8); PG8_WAIT_L(0); PG8_BAR; PG8_MMA(0, 0, At, B0); PG8_MMA(0, 1, At, B1); PG8_BAR; PG8_SCHED;
;             PG8_LDA(At, 0, 1); PG8_STAGE(PG8_SB(0, 0), b2, voffB); PG8_STAGE(PG8_SB(0, 1), b2 + hstep, voffB); PG8_STAGE(PG8_SA(0, 0), a2, voffA);
;             PG8_WAIT_V(8); PG8_WAIT_L(0); PG8_BAR; PG8_MMA(1, 0, At, B0); PG8_MMA(1, 1, At, B1); PG8_BAR; PG8_SCHED;
;             PG8_LDB(B0, 1, 0); PG8_LDB(B1, 1, 1); PG8_SCHED; PG8_LDA(At, 1, 0); PG8_STAGE(PG8_SA(0, 1), a2 + hstep, voffA);
;             PG8_WAIT_V(8); PG8_WAIT_L(0); PG8_BAR; PG8_MMA(0, 0, At, B0); PG8_MMA(0, 1, At, B1); PG8_BAR; PG8_SCHED;
	v_mfma_f32_16x16x32_bf16 v[62:65], v[130:133], v[186:189], 0
	v_mfma_f32_16x16x32_bf16 v[58:61], v[138:141], v[186:189], 0
	v_mfma_f32_16x16x32_bf16 v[46:49], v[130:133], v[198:201], 0
	v_mfma_f32_16x16x32_bf16 v[42:45], v[138:141], v[198:201], 0
	v_mfma_f32_16x16x32_bf16 v[30:33], v[130:133], v[206:209], 0
	v_mfma_f32_16x16x32_bf16 v[26:29], v[138:141], v[206:209], 0
	v_mfma_f32_16x16x32_bf16 v[14:17], v[130:133], v[224:227], 0
	v_mfma_f32_16x16x32_bf16 v[10:13], v[138:141], v[224:227], 0
	v_mfma_f32_16x16x32_bf16 v[62:65], v[134:137], v[194:197], v[62:65]
	v_mfma_f32_16x16x32_bf16 v[58:61], v[142:145], v[194:197], v[58:61]
	v_mfma_f32_16x16x32_bf16 v[46:49], v[134:137], v[202:205], v[46:49]
	v_mfma_f32_16x16x32_bf16 v[42:45], v[142:145], v[202:205], v[42:45]
	v_mfma_f32_16x16x32_bf16 v[30:33], v[134:137], v[220:223], v[30:33]
	v_mfma_f32_16x16x32_bf16 v[26:29], v[142:145], v[220:223], v[26:29]
	v_mfma_f32_16x16x32_bf16 v[14:17], v[134:137], v[228:231], v[14:17]
	v_mfma_f32_16x16x32_bf16 v[10:13], v[142:145], v[228:231], v[10:13]
	v_mfma_f32_16x16x32_bf16 v[54:57], v[146:149], v[186:189], 0
	v_mfma_f32_16x16x32_bf16 v[50:53], v[178:181], v[186:189], 0
	v_mfma_f32_16x16x32_bf16 v[38:41], v[146:149], v[198:201], 0
	v_mfma_f32_16x16x32_bf16 v[34:37], v[178:181], v[198:201], 0
	v_mfma_f32_16x16x32_bf16 v[22:25], v[146:149], v[206:209], 0
	v_mfma_f32_16x16x32_bf16 v[18:21], v[178:181], v[206:209], 0
	v_mfma_f32_16x16x32_bf16 v[6:9], v[146:149], v[224:227], 0
	v_mfma_f32_16x16x32_bf16 v[2:5], v[178:181], v[224:227], 0
	v_mfma_f32_16x16x32_bf16 v[54:57], v[150:153], v[194:197], v[54:57]
	v_mfma_f32_16x16x32_bf16 v[50:53], v[182:185], v[194:197], v[50:53]
	v_mfma_f32_16x16x32_bf16 v[38:41], v[150:153], v[202:205], v[38:41]
	v_mfma_f32_16x16x32_bf16 v[34:37], v[182:185], v[202:205], v[34:37]
	v_mfma_f32_16x16x32_bf16 v[22:25], v[150:153], v[220:223], v[22:25]
	v_mfma_f32_16x16x32_bf16 v[18:21], v[182:185], v[220:223], v[18:21]
	v_mfma_f32_16x16x32_bf16 v[6:9], v[150:153], v[228:231], v[6:9]
	v_mfma_f32_16x16x32_bf16 v[2:5], v[182:185], v[228:231], v[2:5]
	s_barrier
	s_add_i32 s39, 0, 0x18000
	s_add_i32 s41, 0, 0x1c000
	v_add_u32_e32 v142, s39, v190
	v_add_u32_e32 v182, s41, v190
	ds_read_b128 v[130:133], v142
	ds_read_b128 v[134:137], v142 offset:1024
	ds_read_b128 v[138:141], v142 offset:2048
	ds_read_b128 v[142:145], v142 offset:3072
	ds_read_b128 v[146:149], v182
	ds_read_b128 v[150:153], v182 offset:1024
	ds_read_b128 v[178:181], v182 offset:2048
	ds_read_b128 v[182:185], v182 offset:3072
	s_add_u32 s28, s28, 0x80000
	s_addc_u32 s29, s29, 0
	s_mov_b32 m0, s8
	v_lshl_add_u64 v[236:237], s[28:29], 0, v[172:173]
	ds_read_b128 v[186:189], v192 offset:32768
	ds_read_b128 v[194:197], v192 offset:33792
	ds_read_b128 v[198:201], v192 offset:34816
	ds_read_b128 v[202:205], v192 offset:35840
	ds_read_b128 v[206:209], v192 offset:36864
	ds_read_b128 v[220:223], v192 offset:37888
	ds_read_b128 v[224:227], v192 offset:38912
	ds_read_b128 v[228:231], v192 offset:39936
	global_load_lds_dwordx4 v[236:237], off
	v_lshl_add_u64 v[236:237], s[28:29], 0, v[156:157]
	s_mov_b32 m0, s9
	s_nop 0
	global_load_lds_dwordx4 v[236:237], off
	s_waitcnt vmcnt(8)
	s_waitcnt lgkmcnt(0)
	s_barrier
	v_mfma_f32_16x16x32_bf16 v[126:129], v[130:133], v[186:189], v[126:129]
	v_mfma_f32_16x16x32_bf16 v[122:125], v[138:141], v[186:189], v[122:125]
	v_mfma_f32_16x16x32_bf16 v[110:113], v[130:133], v[198:201], v[110:113]
	v_mfma_f32_16x16x32_bf16 v[106:109], v[138:141], v[198:201], v[106:109]
	v_mfma_f32_16x16x32_bf16 v[94:97], v[130:133], v[206:209], v[94:97]
	v_mfma_f32_16x16x32_bf16 v[90:93], v[138:141], v[206:209], v[90:93]
	v_mfma_f32_16x16x32_bf16 v[78:81], v[130:133], v[224:227], v[78:81]
	v_mfma_f32_16x16x32_bf16 v[74:77], v[138:141], v[224:227], v[74:77]
	v_mfma_f32_16x16x32_bf16 v[126:129], v[134:137], v[194:197], v[126:129]
	v_mfma_f32_16x16x32_bf16 v[122:125], v[142:145], v[194:197], v[122:125]
	v_mfma_f32_16x16x32_bf16 v[110:113], v[134:137], v[202:205], v[110:113]
	v_mfma_f32_16x16x32_bf16 v[106:109], v[142:145], v[202:205], v[106:109]
	v_mfma_f32_16x16x32_bf16 v[94:97], v[134:137], v[220:223], v[94:97]
	v_mfma_f32_16x16x32_bf16 v[90:93], v[142:145], v[220:223], v[90:93]
	v_mfma_f32_16x16x32_bf16 v[78:81], v[134:137], v[228:231], v[78:81]
	v_mfma_f32_16x16x32_bf16 v[74:77], v[142:145], v[228:231], v[74:77]
	v_mfma_f32_16x16x32_bf16 v[118:121], v[146:149], v[186:189], v[118:121]
	v_mfma_f32_16x16x32_bf16 v[114:117], v[178:181], v[186:189], v[114:117]
	v_mfma_f32_16x16x32_bf16 v[102:105], v[146:149], v[198:201], v[102:105]
	v_mfma_f32_16x16x32_bf16 v[98:101], v[178:181], v[198:201], v[98:101]
	v_mfma_f32_16x16x32_bf16 v[86:89], v[146:149], v[206:209], v[86:89]
	v_mfma_f32_16x16x32_bf16 v[82:85], v[178:181], v[206:209], v[82:85]
	v_mfma_f32_16x16x32_bf16 v[70:73], v[146:149], v[224:227], v[70:73]
	v_mfma_f32_16x16x32_bf16 v[66:69], v[178:181], v[224:227], v[66:69]
	v_mfma_f32_16x16x32_bf16 v[118:121], v[150:153], v[194:197], v[118:121]
	v_mfma_f32_16x16x32_bf16 v[114:117], v[182:185], v[194:197], v[114:117]
	v_mfma_f32_16x16x32_bf16 v[102:105], v[150:153], v[202:205], v[102:105]
	v_mfma_f32_16x16x32_bf16 v[98:101], v[182:185], v[202:205], v[98:101]
	v_mfma_f32_16x16x32_bf16 v[86:89], v[150:153], v[220:223], v[86:89]
	v_mfma_f32_16x16x32_bf16 v[82:85], v[182:185], v[220:223], v[82:85]
	v_mfma_f32_16x16x32_bf16 v[70:73], v[150:153], v[228:231], v[70:73]
	v_mfma_f32_16x16x32_bf16 v[66:69], v[182:185], v[228:231], v[66:69]
	s_barrier
; #define PG8_STAGE(bufoff, gbase, voff) do { _Pragma("unroll") for (int _i = 0; _i < 2; ++_i) \
;         __builtin_amdgcn_global_load_lds((const unsigned*)((const char*)(gbase) + (voff)[_i]), (PG8_LAS unsigned*)(lds + (bufoff) + ldsw + _i * 8192), 16, 0, 0); } while (0)
; #define PG8_LDA(dst, b, h) do { _Pragma("unroll") for (int m = 0; m < 4; ++m) _Pragma("unroll") for (int k = 0; k < 2; ++k) dst[m][k] = *(const PG8_LAS bf16x8*)(lds + PG8_SA(b, h) + aoff + m * 2048 + k * 1024); } while (0)
; #define PG8_LDB(dst, b, h) do { _Pragma("unroll") for (int n = 0; n < 2; ++n) _Pragma("unroll") for (int k = 0; k < 2; ++k) dst[n][k] = *(const PG8_LAS bf16x8*)(lds + PG8_SB(b, h) + boff + n * 2048 + k * 1024); } while (0)
; #define PG8_MMA(ai, bj, At, Bt) do { __builtin_amdgcn_s_setprio(1); _Pragma("unroll") for (int m = 0; m < 4; ++m) _Pragma("unroll") for (int n = 0; n < 2; ++n) _Pragma("unroll") for (int k = 0; k < 2; ++k) \
;         acc[ai][bj][m][n] = __builtin_amdgcn_mfma_f32_16x16x32_bf16(Bt[n][k], At[m][k], acc[ai][bj][m][n], 0, 0, 0); __builtin_amdgcn_s_setprio(0); } while (0)
; #define PG8_WAIT_V(n) asm volatile("s_waitcnt vmcnt(" #n ")" ::: "memory")
; #define PG8_WAIT_L(n) asm volatile("s_waitcnt lgkmcnt(" #n ")" ::: "memory")
; #define PG8_BAR __builtin_amdgcn_s_barrier()
; #define PG8_SCHED __builtin_amdgcn_sched_barrier(0)
; template <class Epi, class Sched, bool ALIGN_EPI = false, bool SP2 = false>
; __device__ __forceinline__ void gemm_phase(PG8_LAS unsigned char* lds, const Gemm g, const Sched& S, const Epi& E) {
;     ...
;             PG8_LDB(B0, 0, 0); PG8_LDB(B1, 0, 1); PG8_SCHED; PG8_LDA(At, 0, 0); PG8_STAGE(PG8_SA(1, 1), a1 + hstep, voffA);
;             PG8_WAIT_V(8); PG8_WAIT_L(0); PG8_BAR; PG8_MMA(0, 0, At, B0); PG8_MMA(0, 1, At, B1); PG8_BAR; PG8_SCHED;
;     ...
;             PG8_WAIT_V(8); PG8_WAIT_L(0); PG8_BAR; PG8_MMA(0, 0, At, B0); PG8_MMA(0, 1, At, B1); PG8_BAR; PG8_SCHED;
;             PG8_LDA(At, 1, 1); PG8_STAGE(PG8_SB(1, 0), b3, voffB); PG8_STAGE(PG8_SB(1, 1), b3 + hstep, voffB); PG8_STAGE(PG8_SA(1, 0), a3, voffA);
;             PG8_WAIT_V(8); PG8_WAIT_L(0); PG8_BAR; PG8_MMA(1, 0, At, B0); PG8_MMA(1, 1, At, B1); PG8_BAR; PG8_SCHED;
	s_add_i32 s28, s39, s5
	v_lshl_add_u64 v[170:171], v[170:171], 0, s[96:97]
	s_mov_b32 m0, s28
	ds_read_b128 v[186:189], v192 offset:49152
	ds_read_b128 v[194:197], v192 offset:50176
	ds_read_b128 v[198:201], v192 offset:51200
	ds_read_b128 v[202:205], v192 offset:52224
	ds_read_b128 v[206:209], v192 offset:53248
	ds_read_b128 v[220:223], v192 offset:54272
	ds_read_b128 v[224:227], v192 offset:55296
	ds_read_b128 v[228:231], v192 offset:56320
	global_load_lds_dwordx4 v[170:171], off
	s_add_i32 m0, s28, 0x2000
	s_add_u32 s26, s26, 0x80080
	v_lshl_add_u64 v[170:171], v[210:211], 0, s[96:97]
	s_addc_u32 s27, s27, 0
	s_add_i32 s28, s41, s5
	global_load_lds_dwordx4 v[170:171], off
	v_lshl_add_u64 v[170:171], s[26:27], 0, v[158:159]
	s_mov_b32 m0, s28
	s_nop 0
	global_load_lds_dwordx4 v[170:171], off
	v_lshl_add_u64 v[170:171], s[26:27], 0, v[154:155]
	s_add_i32 m0, s28, 0x2000
	s_nop 0
	global_load_lds_dwordx4 v[170:171], off
	v_lshl_add_u64 v[170:171], v[232:233], 0, s[96:97]
	s_mov_b32 m0, s10
	s_nop 0
	global_load_lds_dwordx4 v[170:171], off
	v_lshl_add_u64 v[170:171], v[234:235], 0, s[96:97]
	s_mov_b32 m0, s11
	s_nop 0
	global_load_lds_dwordx4 v[170:171], off
	s_waitcnt vmcnt(8)
	s_waitcnt lgkmcnt(0)
	s_barrier
	v_mfma_f32_16x16x32_bf16 v[62:65], v[130:133], v[186:189], v[62:65]
	v_mfma_f32_16x16x32_bf16 v[58:61], v[138:141], v[186:189], v[58:61]
	v_mfma_f32_16x16x32_bf16 v[46:49], v[130:133], v[198:201], v[46:49]
	v_mfma_f32_16x16x32_bf16 v[42:45], v[138:141], v[198:201], v[42:45]
	v_mfma_f32_16x16x32_bf16 v[30:33], v[130:133], v[206:209], v[30:33]
	v_mfma_f32_16x16x32_bf16 v[26:29], v[138:141], v[206:209], v[26:29]
	v_mfma_f32_16x16x32_bf16 v[14:17], v[130:133], v[224:227], v[14:17]
	v_mfma_f32_16x16x32_bf16 v[10:13], v[138:141], v[224:227], v[10:13]
	v_mfma_f32_16x16x32_bf16 v[62:65], v[134:137], v[194:197], v[62:65]
	v_mfma_f32_16x16x32_bf16 v[58:61], v[142:145], v[194:197], v[58:61]
	v_mfma_f32_16x16x32_bf16 v[46:49], v[134:137], v[202:205], v[46:49]
	v_mfma_f32_16x16x32_bf16 v[42:45], v[142:145], v[202:205], v[42:45]
	v_mfma_f32_16x16x32_bf16 v[30:33], v[134:137], v[220:223], v[30:33]
	v_mfma_f32_16x16x32_bf16 v[26:29], v[142:145], v[220:223], v[26:29]
	v_mfma_f32_16x16x32_bf16 v[14:17], v[134:137], v[228:231], v[14:17]
	v_mfma_f32_16x16x32_bf16 v[10:13], v[142:145], v[228:231], v[10:13]
	v_mfma_f32_16x16x32_bf16 v[54:57], v[146:149], v[186:189], v[54:57]
	v_mfma_f32_16x16x32_bf16 v[50:53], v[178:181], v[186:189], v[50:53]
	v_mfma_f32_16x16x32_bf16 v[38:41], v[146:149], v[198:201], v[38:41]
	v_mfma_f32_16x16x32_bf16 v[34:37], v[178:181], v[198:201], v[34:37]
	v_mfma_f32_16x16x32_bf16 v[22:25], v[146:149], v[206:209], v[22:25]
	v_mfma_f32_16x16x32_bf16 v[18:21], v[178:181], v[206:209], v[18:21]
	v_mfma_f32_16x16x32_bf16 v[6:9], v[146:149], v[224:227], v[6:9]
	v_mfma_f32_16x16x32_bf16 v[2:5], v[178:181], v[224:227], v[2:5]
	v_mfma_f32_16x16x32_bf16 v[54:57], v[150:153], v[194:197], v[54:57]
	v_mfma_f32_16x16x32_bf16 v[50:53], v[182:185], v[194:197], v[50:53]
	v_mfma_f32_16x16x32_bf16 v[38:41], v[150:153], v[202:205], v[38:41]
	v_mfma_f32_16x16x32_bf16 v[34:37], v[182:185], v[202:205], v[34:37]
	v_mfma_f32_16x16x32_bf16 v[22:25], v[150:153], v[220:223], v[22:25]
	v_mfma_f32_16x16x32_bf16 v[18:21], v[182:185], v[220:223], v[18:21]
	v_mfma_f32_16x16x32_bf16 v[6:9], v[150:153], v[228:231], v[6:9]
	v_mfma_f32_16x16x32_bf16 v[2:5], v[182:185], v[228:231], v[2:5]
	s_barrier
	s_add_i32 s17, s17, 2
	s_add_u32 s35, s35, 0x100
	s_addc_u32 s16, s16, 0
	s_add_u32 s48, s48, 0x100
	s_addc_u32 s49, s49, 0
	s_cmp_gt_u32 s17, 29
	s_cbranch_scc1 .Lpeel_exit_1
.LBB0_419:
	s_add_u32 s26, s48, 0xfff80080
	s_addc_u32 s27, s49, -1
	s_add_i32 s39, 0, 0x10000
	s_cmp_eq_u32 s17, 28
	s_cselect_b32 s29, s15, s27
	s_cselect_b32 s28, s30, s26
	s_cselect_b32 s27, s31, s16
	s_cselect_b32 s26, s34, s35
	s_add_i32 s41, 0, 0x14000
	v_add_u32_e32 v142, s39, v190
	v_add_u32_e32 v170, s41, v190
	ds_read_b128 v[130:133], v142
	ds_read_b128 v[134:137], v142 offset:1024
	ds_read_b128 v[138:141], v142 offset:2048
	ds_read_b128 v[142:145], v142 offset:3072
	ds_read_b128 v[146:149], v170
	ds_read_b128 v[150:153], v170 offset:1024
	ds_read_b128 v[178:181], v170 offset:2048
	ds_read_b128 v[182:185], v170 offset:3072
	v_lshl_add_u64 v[170:171], s[48:49], 0, v[176:177]
	s_add_i32 m0, s6, 0xc000
	ds_read_b128 v[186:189], v192
	ds_read_b128 v[194:197], v192 offset:1024
	ds_read_b128 v[198:201], v192 offset:2048
	ds_read_b128 v[202:205], v192 offset:3072
	ds_read_b128 v[206:209], v192 offset:4096
	ds_read_b128 v[220:223], v192 offset:5120
	ds_read_b128 v[224:227], v192 offset:6144
	ds_read_b128 v[228:231], v192 offset:7168
	global_load_lds_dwordx4 v[170:171], off
	v_lshl_add_u64 v[170:171], s[48:49], 0, v[174:175]
	s_add_i32 m0, s6, 0xe000
	s_nop 0
	global_load_lds_dwordx4 v[170:171], off
	s_waitcnt vmcnt(8)
	s_waitcnt lgkmcnt(0)
	s_barrier
; #define PG8_STAGE(bufoff, gbase, voff) do { _Pragma("unroll") for (int _i = 0; _i < 2; ++_i) \
;         __builtin_amdgcn_global_load_lds((const unsigned*)((const char*)(gbase) + (voff)[_i]), (PG8_LAS unsigned*)(lds + (bufoff) + ldsw + _i * 8192), 16, 0, 0); } while (0)
; #define PG8_LDA(dst, b, h) do { _Pragma("unroll") for (int m = 0; m < 4; ++m) _Pragma("unroll") for (int k = 0; k < 2; ++k) dst[m][k] = *(const PG8_LAS bf16x8*)(lds + PG8_SA(b, h) + aoff + m * 2048 + k * 1024); } while (0)
; #define PG8_LDB(dst, b, h) do { _Pragma("unroll") for (int n = 0; n < 2; ++n) _Pragma("unroll") for (int k = 0; k < 2; ++k) dst[n][k] = *(const PG8_LAS bf16x8*)(lds + PG8_SB(b, h) + boff + n * 2048 + k * 1024); } while (0)
; #define PG8_MMA(ai, bj, At, Bt) do { __builtin_amdgcn_s_setprio(1); _Pragma("unroll") for (int m = 0; m < 4; ++m) _Pragma("unroll") for (int n = 0; n < 2; ++n) _Pragma("unroll") for (int k = 0; k < 2; ++k) \
;         acc[ai][bj][m][n] = __builtin_amdgcn_mfma_f32_16x16x32_bf16(Bt[n][k], At[m][k], acc[ai][bj][m][n], 0, 0, 0); __builtin_amdgcn_s_setprio(0); } while (0)
; #define PG8_WAIT_V(n) asm volatile("s_waitcnt vmcnt(" #n ")" ::: "memory")
; #define PG8_WAIT_L(n) asm volatile("s_waitcnt lgkmcnt(" #n ")" ::: "memory")
; #define PG8_BAR __builtin_amdgcn_s_barrier()
; #define PG8_SCHED __builtin_amdgcn_sched_barrier(0)
; template <class Epi, class Sched, bool ALIGN_EPI = false, bool SP2 = false>
; __device__ __forceinline__ void gemm_phase(PG8_LAS unsigned char* lds, const Gemm g, const Sched& S, const Epi& E) {
;     ...
;             PG8_LDB(B0, 0, 0); PG8_LDB(B1, 0, 1); PG8_SCHED; PG8_LDA(At, 0, 0); PG8_STAGE(PG8_SA(1, 1), a1 + hstep, voffA);
;             PG8_WAIT_V(8); PG8_WAIT_L(0); PG8_BAR; PG8_MMA(0, 0, At, B0); PG8_MMA(0, 1, At, B1); PG8_BAR; PG8_SCHED;
;             PG8_LDA(At, 0, 1); PG8_STAGE(PG8_SB(0, 0), b2, voffB); PG8_STAGE(PG8_SB(0, 1), b2 + hstep, voffB); PG8_STAGE(PG8_SA(0, 0), a2, voffA);
;             PG8_WAIT_V(8); PG8_WAIT_L(0); PG8_BAR; PG8_MMA(1, 0, At, B0); PG8_MMA(1, 1, At, B1); PG8_BAR; PG8_SCHED;
	v_mfma_f32_16x16x32_bf16 v[126:129], v[130:133], v[186:189], v[126:129]
	v_mfma_f32_16x16x32_bf16 v[122:125], v[138:141], v[186:189], v[122:125]
	v_mfma_f32_16x16x32_bf16 v[110:113], v[130:133], v[198:201], v[110:113]
	v_mfma_f32_16x16x32_bf16 v[106:109], v[138:141], v[198:201], v[106:109]
	v_mfma_f32_16x16x32_bf16 v[94:97], v[130:133], v[206:209], v[94:97]
	v_mfma_f32_16x16x32_bf16 v[90:93], v[138:141], v[206:209], v[90:93]
	v_mfma_f32_16x16x32_bf16 v[78:81], v[130:133], v[224:227], v[78:81]
	v_mfma_f32_16x16x32_bf16 v[74:77], v[138:141], v[224:227], v[74:77]
	v_mfma_f32_16x16x32_bf16 v[126:129], v[134:137], v[194:197], v[126:129]
	v_mfma_f32_16x16x32_bf16 v[122:125], v[142:145], v[194:197], v[122:125]
	v_mfma_f32_16x16x32_bf16 v[110:113], v[134:137], v[202:205], v[110:113]
	v_mfma_f32_16x16x32_bf16 v[106:109], v[142:145], v[202:205], v[106:109]
	v_mfma_f32_16x16x32_bf16 v[94:97], v[134:137], v[220:223], v[94:97]
	v_mfma_f32_16x16x32_bf16 v[90:93], v[142:145], v[220:223], v[90:93]
	v_mfma_f32_16x16x32_bf16 v[78:81], v[134:137], v[228:231], v[78:81]
	v_mfma_f32_16x16x32_bf16 v[74:77], v[142:145], v[228:231], v[74:77]
	v_mfma_f32_16x16x32_bf16 v[118:121], v[146:149], v[186:189], v[118:121]
	v_mfma_f32_16x16x32_bf16 v[114:117], v[178:181], v[186:189], v[114:117]
	v_mfma_f32_16x16x32_bf16 v[102:105], v[146:149], v[198:201], v[102:105]
	v_mfma_f32_16x16x32_bf16 v[98:101], v[178:181], v[198:201], v[98:101]
	v_mfma_f32_16x16x32_bf16 v[86:89], v[146:149], v[206:209], v[86:89]
	v_mfma_f32_16x16x32_bf16 v[82:85], v[178:181], v[206:209], v[82:85]
	v_mfma_f32_16x16x32_bf16 v[70:73], v[146:149], v[224:227], v[70:73]
	v_mfma_f32_16x16x32_bf16 v[66:69], v[178:181], v[224:227], v[66:69]
	v_mfma_f32_16x16x32_bf16 v[118:121], v[150:153], v[194:197], v[118:121]
	v_mfma_f32_16x16x32_bf16 v[114:117], v[182:185], v[194:197], v[114:117]
	v_mfma_f32_16x16x32_bf16 v[102:105], v[150:153], v[202:205], v[102:105]
	v_mfma_f32_16x16x32_bf16 v[98:101], v[182:185], v[202:205], v[98:101]
	v_mfma_f32_16x16x32_bf16 v[86:89], v[150:153], v[220:223], v[86:89]
	v_mfma_f32_16x16x32_bf16 v[82:85], v[182:185], v[220:223], v[82:85]
	v_mfma_f32_16x16x32_bf16 v[70:73], v[150:153], v[228:231], v[70:73]
	v_mfma_f32_16x16x32_bf16 v[66:69], v[182:185], v[228:231], v[66:69]
	s_barrier
	s_add_i32 s39, s39, s5
	v_lshl_add_u64 v[170:171], s[26:27], 0, v[158:159]
	s_mov_b32 m0, s39
	ds_read_b128 v[186:189], v192 offset:16384
	ds_read_b128 v[194:197], v192 offset:17408
	ds_read_b128 v[198:201], v192 offset:18432
	ds_read_b128 v[202:205], v192 offset:19456
	ds_read_b128 v[206:209], v192 offset:20480
	ds_read_b128 v[220:223], v192 offset:21504
	ds_read_b128 v[224:227], v192 offset:22528
	ds_read_b128 v[228:231], v192 offset:23552
	global_load_lds_dwordx4 v[170:171], off
	s_add_i32 m0, s39, 0x2000
	s_add_u32 s50, s26, 0x80000
	v_lshl_add_u64 v[210:211], s[26:27], 0, v[154:155]
	s_addc_u32 s51, s27, 0
	s_add_i32 s39, s41, s5
	global_load_lds_dwordx4 v[210:211], off
	v_lshl_add_u64 v[232:233], s[50:51], 0, v[158:159]
	s_mov_b32 m0, s39
	v_lshl_add_u64 v[234:235], s[28:29], 0, v[156:157]
	global_load_lds_dwordx4 v[232:233], off
	v_lshl_add_u64 v[232:233], s[50:51], 0, v[154:155]
	s_add_i32 m0, s39, 0x2000
	s_nop 0
	global_load_lds_dwordx4 v[232:233], off
	v_lshl_add_u64 v[232:233], s[28:29], 0, v[172:173]
	s_mov_b32 m0, s6
	s_nop 0
	global_load_lds_dwordx4 v[232:233], off
	s_mov_b32 m0, s7
	s_nop 0
	global_load_lds_dwordx4 v[234:235], off
	s_waitcnt vmcnt(8)
	s_waitcnt lgkmcnt(0)
	s_barrier
	v_mfma_f32_16x16x32_bf16 v[62:65], v[130:133], v[186:189], v[62:65]
	v_mfma_f32_16x16x32_bf16 v[58:61], v[138:141], v[186:189], v[58:61]
	v_mfma_f32_16x16x32_bf16 v[46:49], v[130:133], v[198:201], v[46:49]
	v_mfma_f32_16x16x32_bf16 v[42:45], v[138:141], v[198:201], v[42:45]
	v_mfma_f32_16x16x32_bf16 v[30:33], v[130:133], v[206:209], v[30:33]
	v_mfma_f32_16x16x32_bf16 v[26:29], v[138:141], v[206:209], v[26:29]
	v_mfma_f32_16x16x32_bf16 v[14:17], v[130:133], v[224:227], v[14:17]
	v_mfma_f32_16x16x32_bf16 v[10:13], v[138:141], v[224:227], v[10:13]
	v_mfma_f32_16x16x32_bf16 v[62:65], v[134:137], v[194:197], v[62:65]
	v_mfma_f32_16x16x32_bf16 v[58:61], v[142:145], v[194:197], v[58:61]
	v_mfma_f32_16x16x32_bf16 v[46:49], v[134:137], v[202:205], v[46:49]
	v_mfma_f32_16x16x32_bf16 v[42:45], v[142:145], v[202:205], v[42:45]
	v_mfma_f32_16x16x32_bf16 v[30:33], v[134:137], v[220:223], v[30:33]
	v_mfma_f32_16x16x32_bf16 v[26:29], v[142:145], v[220:223], v[26:29]
	v_mfma_f32_16x16x32_bf16 v[14:17], v[134:137], v[228:231], v[14:17]
	v_mfma_f32_16x16x32_bf16 v[10:13], v[142:145], v[228:231], v[10:13]
	v_mfma_f32_16x16x32_bf16 v[54:57], v[146:149], v[186:189], v[54:57]
	v_mfma_f32_16x16x32_bf16 v[50:53], v[178:181], v[186:189], v[50:53]
	v_mfma_f32_16x16x32_bf16 v[38:41], v[146:149], v[198:201], v[38:41]
	v_mfma_f32_16x16x32_bf16 v[34:37], v[178:181], v[198:201], v[34:37]
	v_mfma_f32_16x16x32_bf16 v[22:25], v[146:149], v[206:209], v[22:25]
	v_mfma_f32_16x16x32_bf16 v[18:21], v[178:181], v[206:209], v[18:21]
	v_mfma_f32_16x16x32_bf16 v[6:9], v[146:149], v[224:227], v[6:9]
	v_mfma_f32_16x16x32_bf16 v[2:5], v[178:181], v[224:227], v[2:5]
	v_mfma_f32_16x16x32_bf16 v[54:57], v[150:153], v[194:197], v[54:57]
	v_mfma_f32_16x16x32_bf16 v[50:53], v[182:185], v[194:197], v[50:53]
	v_mfma_f32_16x16x32_bf16 v[38:41], v[150:153], v[202:205], v[38:41]
	v_mfma_f32_16x16x32_bf16 v[34:37], v[182:185], v[202:205], v[34:37]
	v_mfma_f32_16x16x32_bf16 v[22:25], v[150:153], v[220:223], v[22:25]
	v_mfma_f32_16x16x32_bf16 v[18:21], v[182:185], v[220:223], v[18:21]
	v_mfma_f32_16x16x32_bf16 v[6:9], v[150:153], v[228:231], v[6:9]
	v_mfma_f32_16x16x32_bf16 v[2:5], v[182:185], v[228:231], v[2:5]
	s_barrier
; #define PG8_STAGE(bufoff, gbase, voff) do { _Pragma("unroll") for (int _i = 0; _i < 2; ++_i) \
;         __builtin_amdgcn_global_load_lds((const unsigned*)((const char*)(gbase) + (voff)[_i]), (PG8_LAS unsigned*)(lds + (bufoff) + ldsw + _i * 8192), 16, 0, 0); } while (0)
; #define PG8_LDA(dst, b, h) do { _Pragma("unroll") for (int m = 0; m < 4; ++m) _Pragma("unroll") for (int k = 0; k < 2; ++k) dst[m][k] = *(const PG8_LAS bf16x8*)(lds + PG8_SA(b, h) + aoff + m * 2048 + k * 1024); } while (0)
; #define PG8_LDB(dst, b, h) do { _Pragma("unroll") for (int n = 0; n < 2; ++n) _Pragma("unroll") for (int k = 0; k < 2; ++k) dst[n][k] = *(const PG8_LAS bf16x8*)(lds + PG8_SB(b, h) + boff + n * 2048 + k * 1024); } while (0)
; #define PG8_MMA(ai, bj, At, Bt) do { __builtin_amdgcn_s_setprio(1); _Pragma("unroll") for (int m = 0; m < 4; ++m) _Pragma("unroll") for (int n = 0; n < 2; ++n) _Pragma("unroll") for (int k = 0; k < 2; ++k) \
;         acc[ai][bj][m][n] = __builtin_amdgcn_mfma_f32_16x16x32_bf16(Bt[n][k], At[m][k], acc[ai][bj][m][n], 0, 0, 0); __builtin_amdgcn_s_setprio(0); } while (0)
; #define PG8_WAIT_V(n) asm volatile("s_waitcnt vmcnt(" #n ")" ::: "memory")
; #define PG8_WAIT_L(n) asm volatile("s_waitcnt lgkmcnt(" #n ")" ::: "memory")
; #define PG8_BAR __builtin_amdgcn_s_barrier()
; #define PG8_SCHED __builtin_amdgcn_sched_barrier(0)
; template <class Epi, class Sched, bool ALIGN_EPI = false, bool SP2 = false>
; __device__ __forceinline__ void gemm_phase(PG8_LAS unsigned char* lds, const Gemm g, const Sched& S, const Epi& E) {
;     ...
;             PG8_LDB(B0, 1, 0); PG8_LDB(B1, 1, 1); PG8_SCHED; PG8_LDA(At, 1, 0); PG8_STAGE(PG8_SA(0, 1), a2 + hstep, voffA);
;             PG8_WAIT_V(8); PG8_WAIT_L(0); PG8_BAR; PG8_MMA(0, 0, At, B0); PG8_MMA(0, 1, At, B1); PG8_BAR; PG8_SCHED;
;             PG8_LDA(At, 1, 1); PG8_STAGE(PG8_SB(1, 0), b3, voffB); PG8_STAGE(PG8_SB(1, 1), b3 + hstep, voffB); PG8_STAGE(PG8_SA(1, 0), a3, voffA);
;             PG8_WAIT_V(8); PG8_WAIT_L(0); PG8_BAR; PG8_MMA(1, 0, At, B0); PG8_MMA(1, 1, At, B1); PG8_BAR; PG8_SCHED;
	s_add_i32 s39, 0, 0x18000
	s_add_i32 s41, 0, 0x1c000
	v_add_u32_e32 v142, s39, v190
	v_add_u32_e32 v182, s41, v190
	ds_read_b128 v[130:133], v142
	ds_read_b128 v[134:137], v142 offset:1024
	ds_read_b128 v[138:141], v142 offset:2048
	ds_read_b128 v[142:145], v142 offset:3072
	ds_read_b128 v[146:149], v182
	ds_read_b128 v[150:153], v182 offset:1024
	ds_read_b128 v[178:181], v182 offset:2048
	ds_read_b128 v[182:185], v182 offset:3072
	s_add_u32 s28, s28, 0x80000
	s_addc_u32 s29, s29, 0
	s_mov_b32 m0, s8
	v_lshl_add_u64 v[236:237], s[28:29], 0, v[172:173]
	ds_read_b128 v[186:189], v192 offset:32768
	ds_read_b128 v[194:197], v192 offset:33792
	ds_read_b128 v[198:201], v192 offset:34816
	ds_read_b128 v[202:205], v192 offset:35840
	ds_read_b128 v[206:209], v192 offset:36864
	ds_read_b128 v[220:223], v192 offset:37888
	ds_read_b128 v[224:227], v192 offset:38912
	ds_read_b128 v[228:231], v192 offset:39936
	global_load_lds_dwordx4 v[236:237], off
	v_lshl_add_u64 v[236:237], s[28:29], 0, v[156:157]
	s_mov_b32 m0, s9
	s_nop 0
	global_load_lds_dwordx4 v[236:237], off
	s_waitcnt vmcnt(8)
	s_waitcnt lgkmcnt(0)
	s_barrier
	v_mfma_f32_16x16x32_bf16 v[126:129], v[130:133], v[186:189], v[126:129]
	v_mfma_f32_16x16x32_bf16 v[122:125], v[138:141], v[186:189], v[122:125]
	v_mfma_f32_16x16x32_bf16 v[110:113], v[130:133], v[198:201], v[110:113]
	v_mfma_f32_16x16x32_bf16 v[106:109], v[138:141], v[198:201], v[106:109]
	v_mfma_f32_16x16x32_bf16 v[94:97], v[130:133], v[206:209], v[94:97]
	v_mfma_f32_16x16x32_bf16 v[90:93], v[138:141], v[206:209], v[90:93]
	v_mfma_f32_16x16x32_bf16 v[78:81], v[130:133], v[224:227], v[78:81]
	v_mfma_f32_16x16x32_bf16 v[74:77], v[138:141], v[224:227], v[74:77]
	v_mfma_f32_16x16x32_bf16 v[126:129], v[134:137], v[194:197], v[126:129]
	v_mfma_f32_16x16x32_bf16 v[122:125], v[142:145], v[194:197], v[122:125]
	v_mfma_f32_16x16x32_bf16 v[110:113], v[134:137], v[202:205], v[110:113]
	v_mfma_f32_16x16x32_bf16 v[106:109], v[142:145], v[202:205], v[106:109]
	v_mfma_f32_16x16x32_bf16 v[94:97], v[134:137], v[220:223], v[94:97]
	v_mfma_f32_16x16x32_bf16 v[90:93], v[142:145], v[220:223], v[90:93]
	v_mfma_f32_16x16x32_bf16 v[78:81], v[134:137], v[228:231], v[78:81]
	v_mfma_f32_16x16x32_bf16 v[74:77], v[142:145], v[228:231], v[74:77]
	v_mfma_f32_16x16x32_bf16 v[118:121], v[146:149], v[186:189], v[118:121]
	v_mfma_f32_16x16x32_bf16 v[114:117], v[178:181], v[186:189], v[114:117]
	v_mfma_f32_16x16x32_bf16 v[102:105], v[146:149], v[198:201], v[102:105]
	v_mfma_f32_16x16x32_bf16 v[98:101], v[178:181], v[198:201], v[98:101]
	v_mfma_f32_16x16x32_bf16 v[86:89], v[146:149], v[206:209], v[86:89]
	v_mfma_f32_16x16x32_bf16 v[82:85], v[178:181], v[206:209], v[82:85]
	v_mfma_f32_16x16x32_bf16 v[70:73], v[146:149], v[224:227], v[70:73]
	v_mfma_f32_16x16x32_bf16 v[66:69], v[178:181], v[224:227], v[66:69]
	v_mfma_f32_16x16x32_bf16 v[118:121], v[150:153], v[194:197], v[118:121]
	v_mfma_f32_16x16x32_bf16 v[114:117], v[182:185], v[194:197], v[114:117]
	v_mfma_f32_16x16x32_bf16 v[102:105], v[150:153], v[202:205], v[102:105]
	v_mfma_f32_16x16x32_bf16 v[98:101], v[182:185], v[202:205], v[98:101]
	v_mfma_f32_16x16x32_bf16 v[86:89], v[150:153], v[220:223], v[86:89]
	v_mfma_f32_16x16x32_bf16 v[82:85], v[182:185], v[220:223], v[82:85]
	v_mfma_f32_16x16x32_bf16 v[70:73], v[150:153], v[228:231], v[70:73]
	v_mfma_f32_16x16x32_bf16 v[66:69], v[182:185], v[228:231], v[66:69]
	s_barrier
	s_add_i32 s28, s39, s5
	v_lshl_add_u64 v[170:171], v[170:171], 0, s[96:97]
	s_mov_b32 m0, s28
	ds_read_b128 v[186:189], v192 offset:49152
	ds_read_b128 v[194:197], v192 offset:50176
	ds_read_b128 v[198:201], v192 offset:51200
	ds_read_b128 v[202:205], v192 offset:52224
	ds_read_b128 v[206:209], v192 offset:53248
	ds_read_b128 v[220:223], v192 offset:54272
	ds_read_b128 v[224:227], v192 offset:55296
	ds_read_b128 v[228:231], v192 offset:56320
	global_load_lds_dwordx4 v[170:171], off
	s_add_i32 m0, s28, 0x2000
	s_add_u32 s26, s26, 0x80080
	v_lshl_add_u64 v[170:171], v[210:211], 0, s[96:97]
	s_addc_u32 s27, s27, 0
	s_add_i32 s28, s41, s5
	global_load_lds_dwordx4 v[170:171], off
	v_lshl_add_u64 v[170:171], s[26:27], 0, v[158:159]
	s_mov_b32 m0, s28
	s_nop 0
	global_load_lds_dwordx4 v[170:171], off
	v_lshl_add_u64 v[170:171], s[26:27], 0, v[154:155]
	s_add_i32 m0, s28, 0x2000
	s_nop 0
	global_load_lds_dwordx4 v[170:171], off
	v_lshl_add_u64 v[170:171], v[232:233], 0, s[96:97]
	s_mov_b32 m0, s10
	s_nop 0
	global_load_lds_dwordx4 v[170:171], off
	v_lshl_add_u64 v[170:171], v[234:235], 0, s[96:97]
	s_mov_b32 m0, s11
	s_nop 0
	global_load_lds_dwordx4 v[170:171], off
	s_waitcnt vmcnt(8)
	s_waitcnt lgkmcnt(0)
	s_barrier
	v_mfma_f32_16x16x32_bf16 v[62:65], v[130:133], v[186:189], v[62:65]
	v_mfma_f32_16x16x32_bf16 v[58:61], v[138:141], v[186:189], v[58:61]
	v_mfma_f32_16x16x32_bf16 v[46:49], v[130:133], v[198:201], v[46:49]
	v_mfma_f32_16x16x32_bf16 v[42:45], v[138:141], v[198:201], v[42:45]
	v_mfma_f32_16x16x32_bf16 v[30:33], v[130:133], v[206:209], v[30:33]
	v_mfma_f32_16x16x32_bf16 v[26:29], v[138:141], v[206:209], v[26:29]
	v_mfma_f32_16x16x32_bf16 v[14:17], v[130:133], v[224:227], v[14:17]
	v_mfma_f32_16x16x32_bf16 v[10:13], v[138:141], v[224:227], v[10:13]
	v_mfma_f32_16x16x32_bf16 v[62:65], v[134:137], v[194:197], v[62:65]
	v_mfma_f32_16x16x32_bf16 v[58:61], v[142:145], v[194:197], v[58:61]
	v_mfma_f32_16x16x32_bf16 v[46:49], v[134:137], v[202:205], v[46:49]
	v_mfma_f32_16x16x32_bf16 v[42:45], v[142:145], v[202:205], v[42:45]
	v_mfma_f32_16x16x32_bf16 v[30:33], v[134:137], v[220:223], v[30:33]
	v_mfma_f32_16x16x32_bf16 v[26:29], v[142:145], v[220:223], v[26:29]
	v_mfma_f32_16x16x32_bf16 v[14:17], v[134:137], v[228:231], v[14:17]
	v_mfma_f32_16x16x32_bf16 v[10:13], v[142:145], v[228:231], v[10:13]
	v_mfma_f32_16x16x32_bf16 v[54:57], v[146:149], v[186:189], v[54:57]
	v_mfma_f32_16x16x32_bf16 v[50:53], v[178:181], v[186:189], v[50:53]
	v_mfma_f32_16x16x32_bf16 v[38:41], v[146:149], v[198:201], v[38:41]
	v_mfma_f32_16x16x32_bf16 v[34:37], v[178:181], v[198:201], v[34:37]
	v_mfma_f32_16x16x32_bf16 v[22:25], v[146:149], v[206:209], v[22:25]
	v_mfma_f32_16x16x32_bf16 v[18:21], v[178:181], v[206:209], v[18:21]
	v_mfma_f32_16x16x32_bf16 v[6:9], v[146:149], v[224:227], v[6:9]
	v_mfma_f32_16x16x32_bf16 v[2:5], v[178:181], v[224:227], v[2:5]
	v_mfma_f32_16x16x32_bf16 v[54:57], v[150:153], v[194:197], v[54:57]
	v_mfma_f32_16x16x32_bf16 v[50:53], v[182:185], v[194:197], v[50:53]
	v_mfma_f32_16x16x32_bf16 v[38:41], v[150:153], v[202:205], v[38:41]
	v_mfma_f32_16x16x32_bf16 v[34:37], v[182:185], v[202:205], v[34:37]
	v_mfma_f32_16x16x32_bf16 v[22:25], v[150:153], v[220:223], v[22:25]
	v_mfma_f32_16x16x32_bf16 v[18:21], v[182:185], v[220:223], v[18:21]
	v_mfma_f32_16x16x32_bf16 v[6:9], v[150:153], v[228:231], v[6:9]
	v_mfma_f32_16x16x32_bf16 v[2:5], v[182:185], v[228:231], v[2:5]
	s_barrier
	s_add_i32 s17, s17, 2
	s_add_u32 s35, s35, 0x100
	s_addc_u32 s16, s16, 0
	s_add_u32 s48, s48, 0x100
	s_addc_u32 s49, s49, 0
	s_cmp_gt_u32 s17, 29
	s_cbranch_scc0 .LBB0_419

; #define PG8_STAGE(bufoff, gbase, voff) do { _Pragma("unroll") for (int _i = 0; _i < 2; ++_i) \
;         __builtin_amdgcn_global_load_lds((const unsigned*)((const char*)(gbase) + (voff)[_i]), (PG8_LAS unsigned*)(lds + (bufoff) + ldsw + _i * 8192), 16, 0, 0); } while (0)
; #define PG8_LDA(dst, b, h) do { _Pragma("unroll") for (int m = 0; m < 4; ++m) _Pragma("unroll") for (int k = 0; k < 2; ++k) dst[m][k] = *(const PG8_LAS bf16x8*)(lds + PG8_SA(b, h) + aoff + m * 2048 + k * 1024); } while (0)
; #define PG8_LDB(dst, b, h) do { _Pragma("unroll") for (int n = 0; n < 2; ++n) _Pragma("unroll") for (int k = 0; k < 2; ++k) dst[n][k] = *(const PG8_LAS bf16x8*)(lds + PG8_SB(b, h) + boff + n * 2048 + k * 1024); } while (0)
; #define PG8_MMA(ai, bj, At, Bt) do { __builtin_amdgcn_s_setprio(1); _Pragma("unroll") for (int m = 0; m < 4; ++m) _Pragma("unroll") for (int n = 0; n < 2; ++n) _Pragma("unroll") for (int k = 0; k < 2; ++k) \
;         acc[ai][bj][m][n] = __builtin_amdgcn_mfma_f32_16x16x32_bf16(Bt[n][k], At[m][k], acc[ai][bj][m][n], 0, 0, 0); __builtin_amdgcn_s_setprio(0); } while (0)
; #define PG8_WAIT_V(n) asm volatile("s_waitcnt vmcnt(" #n ")" ::: "memory")
; template <class Epi, class Sched, bool ALIGN_EPI = false, bool SP2 = false>
; __device__ __forceinline__ void gemm_phase(PG8_LAS unsigned char* lds, const Gemm g, const Sched& S, const Epi& E) {
;     ...
;         const int nt = cur.nt;
;         for (int t = 0; t < nt; t += 2) {
;             const bool last = (t == nt - 2);
;             const char* a1 = cA + (size_t)(t + 1) * kstep;
;             const char* a2 = last ? nA : cA + (size_t)(t + 2) * kstep; const char* b2 = last ? nB : cB + (size_t)(t + 2) * kstep;
;             const char* a3 = a2 + kstep; const char* b3 = b2 + kstep;
;             if (last && has_next) S.a_ready(nxt);
;             if constexpr (SP2) {
;             PG8_LDB(B0, 0, 0); PG8_LDB(B1, 0, 1); PG8_SCHED; PG8_LDA(At, 0, 0); PG8_STAGE(PG8_SA(1, 1), a1 + hstep, voffA);
;             PG8_WAIT_V(8); PG8_WAIT_L(0); PG8_BAR; PG8_MMA(0, 0, At, B0); PG8_MMA(0, 1, At, B1); PG8_BAR; PG8_SCHED;
;             PG8_LDA(At, 0, 1); PG8_STAGE(PG8_SB(0, 0), b2, voffB); PG8_STAGE(PG8_SB(0, 1), b2 + hstep, voffB); PG8_STAGE(PG8_SA(0, 0), a2, voffA);
;             PG8_WAIT_V(8); PG8_WAIT_L(0); PG8_BAR; PG8_MMA(1, 0, At, B0); PG8_MMA(1, 1, At, B1); PG8_BAR; PG8_SCHED;
.LBB0_529:
	s_add_i32 s14, s13, -2
	s_add_u32 s15, s58, 0x100
	s_addc_u32 s16, s59, 0
	s_add_u32 s24, s24, 0x100080
	s_addc_u32 s25, s25, 0
	s_mov_b32 s17, 0
	s_waitcnt vmcnt(0)
	s_waitcnt vmcnt(0)
	s_add_i32 s21, s17, 2
	s_add_u32 s23, s24, 0xfff00080
	s_addc_u32 s26, s25, -1
	s_add_i32 s30, 0, 0x10000
	s_cmp_eq_u32 s14, s17
	s_cselect_b32 s29, s55, s26
	s_cselect_b32 s28, s54, s23
	s_cselect_b32 s27, s57, s16
	s_cselect_b32 s26, s56, s15
	s_add_i32 s17, 0, 0x14000
	v_add_u32_e32 v142, s30, v190
	v_add_u32_e32 v170, s17, v190
	ds_read_b128 v[130:133], v142
	ds_read_b128 v[134:137], v142 offset:1024
	ds_read_b128 v[138:141], v142 offset:2048
	ds_read_b128 v[142:145], v142 offset:3072
	ds_read_b128 v[146:149], v170
	ds_read_b128 v[150:153], v170 offset:1024
	ds_read_b128 v[178:181], v170 offset:2048
	ds_read_b128 v[182:185], v170 offset:3072
	v_lshl_add_u64 v[170:171], s[24:25], 0, v[176:177]
	s_add_i32 m0, s35, 0xc000
	ds_read_b128 v[186:189], v192
	ds_read_b128 v[194:197], v192 offset:1024
	ds_read_b128 v[198:201], v192 offset:2048
	ds_read_b128 v[202:205], v192 offset:3072
	ds_read_b128 v[206:209], v192 offset:4096
	ds_read_b128 v[220:223], v192 offset:5120
	ds_read_b128 v[224:227], v192 offset:6144
	ds_read_b128 v[228:231], v192 offset:7168
	global_load_lds_dwordx4 v[170:171], off
	v_lshl_add_u64 v[170:171], s[24:25], 0, v[174:175]
	s_add_i32 m0, s35, 0xe000
	s_nop 0
	global_load_lds_dwordx4 v[170:171], off
	s_waitcnt vmcnt(8)
	s_waitcnt lgkmcnt(0)
	s_barrier
	v_mfma_f32_16x16x32_bf16 v[126:129], v[130:133], v[186:189], 0
	v_mfma_f32_16x16x32_bf16 v[122:125], v[138:141], v[186:189], 0
	v_mfma_f32_16x16x32_bf16 v[118:121], v[130:133], v[198:201], 0
	v_mfma_f32_16x16x32_bf16 v[114:117], v[138:141], v[198:201], 0
	v_mfma_f32_16x16x32_bf16 v[102:105], v[130:133], v[206:209], 0
	v_mfma_f32_16x16x32_bf16 v[94:97], v[138:141], v[206:209], 0
	v_mfma_f32_16x16x32_bf16 v[86:89], v[130:133], v[224:227], 0
	v_mfma_f32_16x16x32_bf16 v[78:81], v[138:141], v[224:227], 0
	v_mfma_f32_16x16x32_bf16 v[126:129], v[134:137], v[194:197], v[126:129]
	v_mfma_f32_16x16x32_bf16 v[122:125], v[142:145], v[194:197], v[122:125]
	v_mfma_f32_16x16x32_bf16 v[118:121], v[134:137], v[202:205], v[118:121]
	v_mfma_f32_16x16x32_bf16 v[114:117], v[142:145], v[202:205], v[114:117]
	v_mfma_f32_16x16x32_bf16 v[102:105], v[134:137], v[220:223], v[102:105]
	v_mfma_f32_16x16x32_bf16 v[94:97], v[142:145], v[220:223], v[94:97]
	v_mfma_f32_16x16x32_bf16 v[86:89], v[134:137], v[228:231], v[86:89]
	v_mfma_f32_16x16x32_bf16 v[78:81], v[142:145], v[228:231], v[78:81]
	v_mfma_f32_16x16x32_bf16 v[110:113], v[146:149], v[186:189], 0
	v_mfma_f32_16x16x32_bf16 v[106:109], v[178:181], v[186:189], 0
	v_mfma_f32_16x16x32_bf16 v[98:101], v[146:149], v[198:201], 0
	v_mfma_f32_16x16x32_bf16 v[90:93], v[178:181], v[198:201], 0
	v_mfma_f32_16x16x32_bf16 v[82:85], v[146:149], v[206:209], 0
	v_mfma_f32_16x16x32_bf16 v[74:77], v[178:181], v[206:209], 0
	v_mfma_f32_16x16x32_bf16 v[70:73], v[146:149], v[224:227], 0
	v_mfma_f32_16x16x32_bf16 v[66:69], v[178:181], v[224:227], 0
	v_mfma_f32_16x16x32_bf16 v[110:113], v[150:153], v[194:197], v[110:113]
	v_mfma_f32_16x16x32_bf16 v[106:109], v[182:185], v[194:197], v[106:109]
	v_mfma_f32_16x16x32_bf16 v[98:101], v[150:153], v[202:205], v[98:101]
	v_mfma_f32_16x16x32_bf16 v[90:93], v[182:185], v[202:205], v[90:93]
	v_mfma_f32_16x16x32_bf16 v[82:85], v[150:153], v[220:223], v[82:85]
	v_mfma_f32_16x16x32_bf16 v[74:77], v[182:185], v[220:223], v[74:77]
	v_mfma_f32_16x16x32_bf16 v[70:73], v[150:153], v[228:231], v[70:73]
	v_mfma_f32_16x16x32_bf16 v[66:69], v[182:185], v[228:231], v[66:69]
	s_barrier
	s_add_i32 s23, s30, s34
	v_lshl_add_u64 v[170:171], s[26:27], 0, v[158:159]
	s_mov_b32 m0, s23
	ds_read_b128 v[186:189], v192 offset:16384
	ds_read_b128 v[194:197], v192 offset:17408
	ds_read_b128 v[198:201], v192 offset:18432
	ds_read_b128 v[202:205], v192 offset:19456
	ds_read_b128 v[206:209], v192 offset:20480
	ds_read_b128 v[220:223], v192 offset:21504
	ds_read_b128 v[224:227], v192 offset:22528
	ds_read_b128 v[228:231], v192 offset:23552
	global_load_lds_dwordx4 v[170:171], off
	s_add_i32 m0, s23, 0x2000
	s_add_u32 s58, s26, 0x100000
	v_lshl_add_u64 v[210:211], s[26:27], 0, v[172:173]
	s_addc_u32 s59, s27, 0
	s_add_i32 s17, s17, s34
	global_load_lds_dwordx4 v[210:211], off
	v_lshl_add_u64 v[232:233], s[58:59], 0, v[158:159]
	s_mov_b32 m0, s17
	v_lshl_add_u64 v[234:235], s[28:29], 0, v[156:157]
	global_load_lds_dwordx4 v[232:233], off
	v_lshl_add_u64 v[232:233], s[58:59], 0, v[172:173]
	s_add_i32 m0, s17, 0x2000
	s_nop 0
	global_load_lds_dwordx4 v[232:233], off
	v_lshl_add_u64 v[232:233], s[28:29], 0, v[154:155]
	s_mov_b32 m0, s35
	s_nop 0
	global_load_lds_dwordx4 v[232:233], off
	s_mov_b32 m0, s4
	s_nop 0
	global_load_lds_dwordx4 v[234:235], off
	s_waitcnt vmcnt(8)
	s_waitcnt lgkmcnt(0)
	s_barrier
; #define PG8_STAGE(bufoff, gbase, voff) do { _Pragma("unroll") for (int _i = 0; _i < 2; ++_i) \
;         __builtin_amdgcn_global_load_lds((const unsigned*)((const char*)(gbase) + (voff)[_i]), (PG8_LAS unsigned*)(lds + (bufoff) + ldsw + _i * 8192), 16, 0, 0); } while (0)
; #define PG8_LDA(dst, b, h) do { _Pragma("unroll") for (int m = 0; m < 4; ++m) _Pragma("unroll") for (int k = 0; k < 2; ++k) dst[m][k] = *(const PG8_LAS bf16x8*)(lds + PG8_SA(b, h) + aoff + m * 2048 + k * 1024); } while (0)
; #define PG8_LDB(dst, b, h) do { _Pragma("unroll") for (int n = 0; n < 2; ++n) _Pragma("unroll") for (int k = 0; k < 2; ++k) dst[n][k] = *(const PG8_LAS bf16x8*)(lds + PG8_SB(b, h) + boff + n * 2048 + k * 1024); } while (0)
; #define PG8_MMA(ai, bj, At, Bt) do { __builtin_amdgcn_s_setprio(1); _Pragma("unroll") for (int m = 0; m < 4; ++m) _Pragma("unroll") for (int n = 0; n < 2; ++n) _Pragma("unroll") for (int k = 0; k < 2; ++k) \
;         acc[ai][bj][m][n] = __builtin_amdgcn_mfma_f32_16x16x32_bf16(Bt[n][k], At[m][k], acc[ai][bj][m][n], 0, 0, 0); __builtin_amdgcn_s_setprio(0); } while (0)
; #define PG8_WAIT_V(n) asm volatile("s_waitcnt vmcnt(" #n ")" ::: "memory")
; #define PG8_WAIT_L(n) asm volatile("s_waitcnt lgkmcnt(" #n ")" ::: "memory")
; #define PG8_BAR __builtin_amdgcn_s_barrier()
; #define PG8_SCHED __builtin_amdgcn_sched_barrier(0)
; template <class Epi, class Sched, bool ALIGN_EPI = false, bool SP2 = false>
; __device__ __forceinline__ void gemm_phase(PG8_LAS unsigned char* lds, const Gemm g, const Sched& S, const Epi& E) {
;     ...
;             PG8_WAIT_V(8); PG8_WAIT_L(0); PG8_BAR; PG8_MMA(1, 0, At, B0); PG8_MMA(1, 1, At, B1); PG8_BAR; PG8_SCHED;
;             PG8_LDB(B0, 1, 0); PG8_LDB(B1, 1, 1); PG8_SCHED; PG8_LDA(At, 1, 0); PG8_STAGE(PG8_SA(0, 1), a2 + hstep, voffA);
;             PG8_WAIT_V(8); PG8_WAIT_L(0); PG8_BAR; PG8_MMA(0, 0, At, B0); PG8_MMA(0, 1, At, B1); PG8_BAR; PG8_SCHED;
	v_mfma_f32_16x16x32_bf16 v[62:65], v[130:133], v[186:189], 0
	v_mfma_f32_16x16x32_bf16 v[58:61], v[138:141], v[186:189], 0
	v_mfma_f32_16x16x32_bf16 v[54:57], v[130:133], v[198:201], 0
	v_mfma_f32_16x16x32_bf16 v[46:49], v[138:141], v[198:201], 0
	v_mfma_f32_16x16x32_bf16 v[38:41], v[130:133], v[206:209], 0
	v_mfma_f32_16x16x32_bf16 v[30:33], v[138:141], v[206:209], 0
	v_mfma_f32_16x16x32_bf16 v[22:25], v[130:133], v[224:227], 0
	v_mfma_f32_16x16x32_bf16 v[14:17], v[138:141], v[224:227], 0
	v_mfma_f32_16x16x32_bf16 v[62:65], v[134:137], v[194:197], v[62:65]
	v_mfma_f32_16x16x32_bf16 v[58:61], v[142:145], v[194:197], v[58:61]
	v_mfma_f32_16x16x32_bf16 v[54:57], v[134:137], v[202:205], v[54:57]
	v_mfma_f32_16x16x32_bf16 v[46:49], v[142:145], v[202:205], v[46:49]
	v_mfma_f32_16x16x32_bf16 v[38:41], v[134:137], v[220:223], v[38:41]
	v_mfma_f32_16x16x32_bf16 v[30:33], v[142:145], v[220:223], v[30:33]
	v_mfma_f32_16x16x32_bf16 v[22:25], v[134:137], v[228:231], v[22:25]
	v_mfma_f32_16x16x32_bf16 v[14:17], v[142:145], v[228:231], v[14:17]
	v_mfma_f32_16x16x32_bf16 v[50:53], v[146:149], v[186:189], 0
	v_mfma_f32_16x16x32_bf16 v[42:45], v[178:181], v[186:189], 0
	v_mfma_f32_16x16x32_bf16 v[34:37], v[146:149], v[198:201], 0
	v_mfma_f32_16x16x32_bf16 v[26:29], v[178:181], v[198:201], 0
	v_mfma_f32_16x16x32_bf16 v[18:21], v[146:149], v[206:209], 0
	v_mfma_f32_16x16x32_bf16 v[10:13], v[178:181], v[206:209], 0
	v_mfma_f32_16x16x32_bf16 v[6:9], v[146:149], v[224:227], 0
	v_mfma_f32_16x16x32_bf16 v[2:5], v[178:181], v[224:227], 0
	v_mfma_f32_16x16x32_bf16 v[50:53], v[150:153], v[194:197], v[50:53]
	v_mfma_f32_16x16x32_bf16 v[42:45], v[182:185], v[194:197], v[42:45]
	v_mfma_f32_16x16x32_bf16 v[34:37], v[150:153], v[202:205], v[34:37]
	v_mfma_f32_16x16x32_bf16 v[26:29], v[182:185], v[202:205], v[26:29]
	v_mfma_f32_16x16x32_bf16 v[18:21], v[150:153], v[220:223], v[18:21]
	v_mfma_f32_16x16x32_bf16 v[10:13], v[182:185], v[220:223], v[10:13]
	v_mfma_f32_16x16x32_bf16 v[6:9], v[150:153], v[228:231], v[6:9]
	v_mfma_f32_16x16x32_bf16 v[2:5], v[182:185], v[228:231], v[2:5]
	s_barrier
	s_add_i32 s17, 0, 0x18000
	s_add_i32 s23, 0, 0x1c000
	v_add_u32_e32 v142, s17, v190
	v_add_u32_e32 v182, s23, v190
	ds_read_b128 v[130:133], v142
	ds_read_b128 v[134:137], v142 offset:1024
	ds_read_b128 v[138:141], v142 offset:2048
	ds_read_b128 v[142:145], v142 offset:3072
	ds_read_b128 v[146:149], v182
	ds_read_b128 v[150:153], v182 offset:1024
	ds_read_b128 v[178:181], v182 offset:2048
	ds_read_b128 v[182:185], v182 offset:3072
	s_add_u32 s28, s28, 0x100000
	s_addc_u32 s29, s29, 0
	s_mov_b32 m0, s5
	v_lshl_add_u64 v[236:237], s[28:29], 0, v[154:155]
	ds_read_b128 v[186:189], v192 offset:32768
	ds_read_b128 v[194:197], v192 offset:33792
	ds_read_b128 v[198:201], v192 offset:34816
	ds_read_b128 v[202:205], v192 offset:35840
	ds_read_b128 v[206:209], v192 offset:36864
	ds_read_b128 v[220:223], v192 offset:37888
	ds_read_b128 v[224:227], v192 offset:38912
	ds_read_b128 v[228:231], v192 offset:39936
	global_load_lds_dwordx4 v[236:237], off
	v_lshl_add_u64 v[236:237], s[28:29], 0, v[156:157]
	s_mov_b32 m0, s6
	s_nop 0
	global_load_lds_dwordx4 v[236:237], off
	s_waitcnt vmcnt(8)
	s_waitcnt lgkmcnt(0)
	s_barrier
	v_mfma_f32_16x16x32_bf16 v[126:129], v[130:133], v[186:189], v[126:129]
	v_mfma_f32_16x16x32_bf16 v[122:125], v[138:141], v[186:189], v[122:125]
	v_mfma_f32_16x16x32_bf16 v[118:121], v[130:133], v[198:201], v[118:121]
	v_mfma_f32_16x16x32_bf16 v[114:117], v[138:141], v[198:201], v[114:117]
	v_mfma_f32_16x16x32_bf16 v[102:105], v[130:133], v[206:209], v[102:105]
	v_mfma_f32_16x16x32_bf16 v[94:97], v[138:141], v[206:209], v[94:97]
	v_mfma_f32_16x16x32_bf16 v[86:89], v[130:133], v[224:227], v[86:89]
	v_mfma_f32_16x16x32_bf16 v[78:81], v[138:141], v[224:227], v[78:81]
	v_mfma_f32_16x16x32_bf16 v[126:129], v[134:137], v[194:197], v[126:129]
	v_mfma_f32_16x16x32_bf16 v[122:125], v[142:145], v[194:197], v[122:125]
	v_mfma_f32_16x16x32_bf16 v[118:121], v[134:137], v[202:205], v[118:121]
	v_mfma_f32_16x16x32_bf16 v[114:117], v[142:145], v[202:205], v[114:117]
	v_mfma_f32_16x16x32_bf16 v[102:105], v[134:137], v[220:223], v[102:105]
	v_mfma_f32_16x16x32_bf16 v[94:97], v[142:145], v[220:223], v[94:97]
	v_mfma_f32_16x16x32_bf16 v[86:89], v[134:137], v[228:231], v[86:89]
	v_mfma_f32_16x16x32_bf16 v[78:81], v[142:145], v[228:231], v[78:81]
	v_mfma_f32_16x16x32_bf16 v[110:113], v[146:149], v[186:189], v[110:113]
	v_mfma_f32_16x16x32_bf16 v[106:109], v[178:181], v[186:189], v[106:109]
	v_mfma_f32_16x16x32_bf16 v[98:101], v[146:149], v[198:201], v[98:101]
	v_mfma_f32_16x16x32_bf16 v[90:93], v[178:181], v[198:201], v[90:93]
	v_mfma_f32_16x16x32_bf16 v[82:85], v[146:149], v[206:209], v[82:85]
	v_mfma_f32_16x16x32_bf16 v[74:77], v[178:181], v[206:209], v[74:77]
	v_mfma_f32_16x16x32_bf16 v[70:73], v[146:149], v[224:227], v[70:73]
	v_mfma_f32_16x16x32_bf16 v[66:69], v[178:181], v[224:227], v[66:69]
	v_mfma_f32_16x16x32_bf16 v[110:113], v[150:153], v[194:197], v[110:113]
	v_mfma_f32_16x16x32_bf16 v[106:109], v[182:185], v[194:197], v[106:109]
	v_mfma_f32_16x16x32_bf16 v[98:101], v[150:153], v[202:205], v[98:101]
	v_mfma_f32_16x16x32_bf16 v[90:93], v[182:185], v[202:205], v[90:93]
	v_mfma_f32_16x16x32_bf16 v[82:85], v[150:153], v[220:223], v[82:85]
	v_mfma_f32_16x16x32_bf16 v[74:77], v[182:185], v[220:223], v[74:77]
	v_mfma_f32_16x16x32_bf16 v[70:73], v[150:153], v[228:231], v[70:73]
	v_mfma_f32_16x16x32_bf16 v[66:69], v[182:185], v[228:231], v[66:69]
	s_barrier
; #define PG8_STAGE(bufoff, gbase, voff) do { _Pragma("unroll") for (int _i = 0; _i < 2; ++_i) \
;         __builtin_amdgcn_global_load_lds((const unsigned*)((const char*)(gbase) + (voff)[_i]), (PG8_LAS unsigned*)(lds + (bufoff) + ldsw + _i * 8192), 16, 0, 0); } while (0)
; #define PG8_LDA(dst, b, h) do { _Pragma("unroll") for (int m = 0; m < 4; ++m) _Pragma("unroll") for (int k = 0; k < 2; ++k) dst[m][k] = *(const PG8_LAS bf16x8*)(lds + PG8_SA(b, h) + aoff + m * 2048 + k * 1024); } while (0)
; #define PG8_LDB(dst, b, h) do { _Pragma("unroll") for (int n = 0; n < 2; ++n) _Pragma("unroll") for (int k = 0; k < 2; ++k) dst[n][k] = *(const PG8_LAS bf16x8*)(lds + PG8_SB(b, h) + boff + n * 2048 + k * 1024); } while (0)
; template <class Epi, class Sched, bool ALIGN_EPI = false, bool SP2 = false>
; __device__ __forceinline__ void gemm_phase(PG8_LAS unsigned char* lds, const Gemm g, const Sched& S, const Epi& E) {
;     ...
;         for (int t = 0; t < nt; t += 2) {
;             const bool last = (t == nt - 2);
;             const char* a1 = cA + (size_t)(t + 1) * kstep;
;             const char* a2 = last ? nA : cA + (size_t)(t + 2) * kstep; const char* b2 = last ? nB : cB + (size_t)(t + 2) * kstep;
;             const char* a3 = a2 + kstep; const char* b3 = b2 + kstep;
;             if (last && has_next) S.a_ready(nxt);
;             if constexpr (SP2) {
;             PG8_LDB(B0, 0, 0); PG8_LDB(B1, 0, 1); PG8_SCHED; PG8_LDA(At, 0, 0); PG8_STAGE(PG8_SA(1, 1), a1 + hstep, voffA);
;             PG8_WAIT_V(8); PG8_WAIT_L(0); PG8_BAR; PG8_MMA(0, 0, At, B0); PG8_MMA(0, 1, At, B1); PG8_BAR; PG8_SCHED;
;             PG8_LDA(At, 0, 1); PG8_STAGE(PG8_SB(0, 0), b2, voffB); PG8_STAGE(PG8_SB(0, 1), b2 + hstep, voffB); PG8_STAGE(PG8_SA(0, 0), a2, voffA);
;             PG8_WAIT_V(8); PG8_WAIT_L(0); PG8_BAR; PG8_MMA(1, 0, At, B0); PG8_MMA(1, 1, At, B1); PG8_BAR; PG8_SCHED;
;             PG8_LDB(B0, 1, 0); PG8_LDB(B1, 1, 1); PG8_SCHED; PG8_LDA(At, 1, 0); PG8_STAGE(PG8_SA(0, 1), a2 + hstep, voffA);
;             PG8_WAIT_V(8); PG8_WAIT_L(0); PG8_BAR; PG8_MMA(0, 0, At, B0); PG8_MMA(0, 1, At, B1); PG8_BAR; PG8_SCHED;
;             PG8_LDA(At, 1, 1); PG8_STAGE(PG8_SB(1, 0), b3, voffB); PG8_STAGE(PG8_SB(1, 1), b3 + hstep, voffB); PG8_STAGE(PG8_SA(1, 0), a3, voffA);
;             PG8_WAIT_V(8); PG8_WAIT_L(0); PG8_BAR; PG8_MMA(1, 0, At, B0); PG8_MMA(1, 1, At, B1); PG8_BAR; PG8_SCHED;
	s_add_i32 s17, s17, s34
	v_lshl_add_u64 v[170:171], v[170:171], 0, s[96:97]
	s_mov_b32 m0, s17
	ds_read_b128 v[186:189], v192 offset:49152
	ds_read_b128 v[194:197], v192 offset:50176
	ds_read_b128 v[198:201], v192 offset:51200
	ds_read_b128 v[202:205], v192 offset:52224
	ds_read_b128 v[206:209], v192 offset:53248
	ds_read_b128 v[220:223], v192 offset:54272
	ds_read_b128 v[224:227], v192 offset:55296
	ds_read_b128 v[228:231], v192 offset:56320
	global_load_lds_dwordx4 v[170:171], off
	s_add_i32 m0, s17, 0x2000
	s_add_u32 s26, s26, 0x100080
	v_lshl_add_u64 v[170:171], v[210:211], 0, s[96:97]
	s_addc_u32 s27, s27, 0
	s_add_i32 s17, s23, s34
	global_load_lds_dwordx4 v[170:171], off
	v_lshl_add_u64 v[170:171], s[26:27], 0, v[158:159]
	s_mov_b32 m0, s17
	s_nop 0
	global_load_lds_dwordx4 v[170:171], off
	v_lshl_add_u64 v[170:171], s[26:27], 0, v[172:173]
	s_add_i32 m0, s17, 0x2000
	s_nop 0
	global_load_lds_dwordx4 v[170:171], off
	v_lshl_add_u64 v[170:171], v[232:233], 0, s[96:97]
	s_mov_b32 m0, s9
	s_nop 0
	global_load_lds_dwordx4 v[170:171], off
	v_lshl_add_u64 v[170:171], v[234:235], 0, s[96:97]
	s_mov_b32 m0, s10
	s_nop 0
	global_load_lds_dwordx4 v[170:171], off
	s_waitcnt vmcnt(8)
	s_waitcnt lgkmcnt(0)
	s_barrier
	v_mfma_f32_16x16x32_bf16 v[62:65], v[130:133], v[186:189], v[62:65]
	v_mfma_f32_16x16x32_bf16 v[58:61], v[138:141], v[186:189], v[58:61]
	v_mfma_f32_16x16x32_bf16 v[54:57], v[130:133], v[198:201], v[54:57]
	v_mfma_f32_16x16x32_bf16 v[46:49], v[138:141], v[198:201], v[46:49]
	v_mfma_f32_16x16x32_bf16 v[38:41], v[130:133], v[206:209], v[38:41]
	v_mfma_f32_16x16x32_bf16 v[30:33], v[138:141], v[206:209], v[30:33]
	v_mfma_f32_16x16x32_bf16 v[22:25], v[130:133], v[224:227], v[22:25]
	v_mfma_f32_16x16x32_bf16 v[14:17], v[138:141], v[224:227], v[14:17]
	v_mfma_f32_16x16x32_bf16 v[62:65], v[134:137], v[194:197], v[62:65]
	v_mfma_f32_16x16x32_bf16 v[58:61], v[142:145], v[194:197], v[58:61]
	v_mfma_f32_16x16x32_bf16 v[54:57], v[134:137], v[202:205], v[54:57]
	v_mfma_f32_16x16x32_bf16 v[46:49], v[142:145], v[202:205], v[46:49]
	v_mfma_f32_16x16x32_bf16 v[38:41], v[134:137], v[220:223], v[38:41]
	v_mfma_f32_16x16x32_bf16 v[30:33], v[142:145], v[220:223], v[30:33]
	v_mfma_f32_16x16x32_bf16 v[22:25], v[134:137], v[228:231], v[22:25]
	v_mfma_f32_16x16x32_bf16 v[14:17], v[142:145], v[228:231], v[14:17]
	v_mfma_f32_16x16x32_bf16 v[50:53], v[146:149], v[186:189], v[50:53]
	v_mfma_f32_16x16x32_bf16 v[42:45], v[178:181], v[186:189], v[42:45]
	v_mfma_f32_16x16x32_bf16 v[34:37], v[146:149], v[198:201], v[34:37]
	v_mfma_f32_16x16x32_bf16 v[26:29], v[178:181], v[198:201], v[26:29]
	v_mfma_f32_16x16x32_bf16 v[18:21], v[146:149], v[206:209], v[18:21]
	v_mfma_f32_16x16x32_bf16 v[10:13], v[178:181], v[206:209], v[10:13]
	v_mfma_f32_16x16x32_bf16 v[6:9], v[146:149], v[224:227], v[6:9]
	v_mfma_f32_16x16x32_bf16 v[2:5], v[178:181], v[224:227], v[2:5]
	v_mfma_f32_16x16x32_bf16 v[50:53], v[150:153], v[194:197], v[50:53]
	v_mfma_f32_16x16x32_bf16 v[42:45], v[182:185], v[194:197], v[42:45]
	v_mfma_f32_16x16x32_bf16 v[34:37], v[150:153], v[202:205], v[34:37]
	v_mfma_f32_16x16x32_bf16 v[26:29], v[182:185], v[202:205], v[26:29]
	v_mfma_f32_16x16x32_bf16 v[18:21], v[150:153], v[220:223], v[18:21]
	v_mfma_f32_16x16x32_bf16 v[10:13], v[182:185], v[220:223], v[10:13]
	v_mfma_f32_16x16x32_bf16 v[6:9], v[150:153], v[228:231], v[6:9]
	v_mfma_f32_16x16x32_bf16 v[2:5], v[182:185], v[228:231], v[2:5]
	s_barrier
	s_add_u32 s15, s15, 0x100
	s_addc_u32 s16, s16, 0
	s_add_u32 s24, s24, 0x100
	s_addc_u32 s25, s25, 0
	s_cmp_ge_i32 s21, s13
	s_mov_b32 s17, s21
	s_cbranch_scc1 .Lpeel_exit_2
.LBB0_530:
	s_add_i32 s21, s17, 2
	s_add_u32 s23, s24, 0xfff00080
	s_addc_u32 s26, s25, -1
	s_add_i32 s30, 0, 0x10000
	s_cmp_eq_u32 s14, s17
	s_cselect_b32 s29, s55, s26
	s_cselect_b32 s28, s54, s23
	s_cselect_b32 s27, s57, s16
	s_cselect_b32 s26, s56, s15
	s_add_i32 s17, 0, 0x14000
	v_add_u32_e32 v142, s30, v190
	v_add_u32_e32 v170, s17, v190
	ds_read_b128 v[130:133], v142
	ds_read_b128 v[134:137], v142 offset:1024
	ds_read_b128 v[138:141], v142 offset:2048
	ds_read_b128 v[142:145], v142 offset:3072
	ds_read_b128 v[146:149], v170
	ds_read_b128 v[150:153], v170 offset:1024
	ds_read_b128 v[178:181], v170 offset:2048
	ds_read_b128 v[182:185], v170 offset:3072
	v_lshl_add_u64 v[170:171], s[24:25], 0, v[176:177]
	s_add_i32 m0, s35, 0xc000
	ds_read_b128 v[186:189], v192
	ds_read_b128 v[194:197], v192 offset:1024
	ds_read_b128 v[198:201], v192 offset:2048
	ds_read_b128 v[202:205], v192 offset:3072
	ds_read_b128 v[206:209], v192 offset:4096
	ds_read_b128 v[220:223], v192 offset:5120
	ds_read_b128 v[224:227], v192 offset:6144
	ds_read_b128 v[228:231], v192 offset:7168
	global_load_lds_dwordx4 v[170:171], off
	v_lshl_add_u64 v[170:171], s[24:25], 0, v[174:175]
	s_add_i32 m0, s35, 0xe000
	s_nop 0
	global_load_lds_dwordx4 v[170:171], off
	s_waitcnt vmcnt(8)
	s_waitcnt lgkmcnt(0)
	s_barrier
; #define PG8_STAGE(bufoff, gbase, voff) do { _Pragma("unroll") for (int _i = 0; _i < 2; ++_i) \
;         __builtin_amdgcn_global_load_lds((const unsigned*)((const char*)(gbase) + (voff)[_i]), (PG8_LAS unsigned*)(lds + (bufoff) + ldsw + _i * 8192), 16, 0, 0); } while (0)
; #define PG8_LDA(dst, b, h) do { _Pragma("unroll") for (int m = 0; m < 4; ++m) _Pragma("unroll") for (int k = 0; k < 2; ++k) dst[m][k] = *(const PG8_LAS bf16x8*)(lds + PG8_SA(b, h) + aoff + m * 2048 + k * 1024); } while (0)
; #define PG8_MMA(ai, bj, At, Bt) do { __builtin_amdgcn_s_setprio(1); _Pragma("unroll") for (int m = 0; m < 4; ++m) _Pragma("unroll") for (int n = 0; n < 2; ++n) _Pragma("unroll") for (int k = 0; k < 2; ++k) \
;         acc[ai][bj][m][n] = __builtin_amdgcn_mfma_f32_16x16x32_bf16(Bt[n][k], At[m][k], acc[ai][bj][m][n], 0, 0, 0); __builtin_amdgcn_s_setprio(0); } while (0)
; #define PG8_WAIT_V(n) asm volatile("s_waitcnt vmcnt(" #n ")" ::: "memory")
; #define PG8_WAIT_L(n) asm volatile("s_waitcnt lgkmcnt(" #n ")" ::: "memory")
; #define PG8_BAR __builtin_amdgcn_s_barrier()
; #define PG8_SCHED __builtin_amdgcn_sched_barrier(0)
; template <class Epi, class Sched, bool ALIGN_EPI = false, bool SP2 = false>
; __device__ __forceinline__ void gemm_phase(PG8_LAS unsigned char* lds, const Gemm g, const Sched& S, const Epi& E) {
;     ...
;             PG8_WAIT_V(8); PG8_WAIT_L(0); PG8_BAR; PG8_MMA(0, 0, At, B0); PG8_MMA(0, 1, At, B1); PG8_BAR; PG8_SCHED;
;             PG8_LDA(At, 0, 1); PG8_STAGE(PG8_SB(0, 0), b2, voffB); PG8_STAGE(PG8_SB(0, 1), b2 + hstep, voffB); PG8_STAGE(PG8_SA(0, 0), a2, voffA);
;             PG8_WAIT_V(8); PG8_WAIT_L(0); PG8_BAR; PG8_MMA(1, 0, At, B0); PG8_MMA(1, 1, At, B1); PG8_BAR; PG8_SCHED;
	v_mfma_f32_16x16x32_bf16 v[126:129], v[130:133], v[186:189], v[126:129]
	v_mfma_f32_16x16x32_bf16 v[122:125], v[138:141], v[186:189], v[122:125]
	v_mfma_f32_16x16x32_bf16 v[118:121], v[130:133], v[198:201], v[118:121]
	v_mfma_f32_16x16x32_bf16 v[114:117], v[138:141], v[198:201], v[114:117]
	v_mfma_f32_16x16x32_bf16 v[102:105], v[130:133], v[206:209], v[102:105]
	v_mfma_f32_16x16x32_bf16 v[94:97], v[138:141], v[206:209], v[94:97]
	v_mfma_f32_16x16x32_bf16 v[86:89], v[130:133], v[224:227], v[86:89]
	v_mfma_f32_16x16x32_bf16 v[78:81], v[138:141], v[224:227], v[78:81]
	v_mfma_f32_16x16x32_bf16 v[126:129], v[134:137], v[194:197], v[126:129]
	v_mfma_f32_16x16x32_bf16 v[122:125], v[142:145], v[194:197], v[122:125]
	v_mfma_f32_16x16x32_bf16 v[118:121], v[134:137], v[202:205], v[118:121]
	v_mfma_f32_16x16x32_bf16 v[114:117], v[142:145], v[202:205], v[114:117]
	v_mfma_f32_16x16x32_bf16 v[102:105], v[134:137], v[220:223], v[102:105]
	v_mfma_f32_16x16x32_bf16 v[94:97], v[142:145], v[220:223], v[94:97]
	v_mfma_f32_16x16x32_bf16 v[86:89], v[134:137], v[228:231], v[86:89]
	v_mfma_f32_16x16x32_bf16 v[78:81], v[142:145], v[228:231], v[78:81]
	v_mfma_f32_16x16x32_bf16 v[110:113], v[146:149], v[186:189], v[110:113]
	v_mfma_f32_16x16x32_bf16 v[106:109], v[178:181], v[186:189], v[106:109]
	v_mfma_f32_16x16x32_bf16 v[98:101], v[146:149], v[198:201], v[98:101]
	v_mfma_f32_16x16x32_bf16 v[90:93], v[178:181], v[198:201], v[90:93]
	v_mfma_f32_16x16x32_bf16 v[82:85], v[146:149], v[206:209], v[82:85]
	v_mfma_f32_16x16x32_bf16 v[74:77], v[178:181], v[206:209], v[74:77]
	v_mfma_f32_16x16x32_bf16 v[70:73], v[146:149], v[224:227], v[70:73]
	v_mfma_f32_16x16x32_bf16 v[66:69], v[178:181], v[224:227], v[66:69]
	v_mfma_f32_16x16x32_bf16 v[110:113], v[150:153], v[194:197], v[110:113]
	v_mfma_f32_16x16x32_bf16 v[106:109], v[182:185], v[194:197], v[106:109]
	v_mfma_f32_16x16x32_bf16 v[98:101], v[150:153], v[202:205], v[98:101]
	v_mfma_f32_16x16x32_bf16 v[90:93], v[182:185], v[202:205], v[90:93]
	v_mfma_f32_16x16x32_bf16 v[82:85], v[150:153], v[220:223], v[82:85]
	v_mfma_f32_16x16x32_bf16 v[74:77], v[182:185], v[220:223], v[74:77]
	v_mfma_f32_16x16x32_bf16 v[70:73], v[150:153], v[228:231], v[70:73]
	v_mfma_f32_16x16x32_bf16 v[66:69], v[182:185], v[228:231], v[66:69]
	s_barrier
	s_add_i32 s23, s30, s34
	v_lshl_add_u64 v[170:171], s[26:27], 0, v[158:159]
	s_mov_b32 m0, s23
	ds_read_b128 v[186:189], v192 offset:16384
	ds_read_b128 v[194:197], v192 offset:17408
	ds_read_b128 v[198:201], v192 offset:18432
	ds_read_b128 v[202:205], v192 offset:19456
	ds_read_b128 v[206:209], v192 offset:20480
	ds_read_b128 v[220:223], v192 offset:21504
	ds_read_b128 v[224:227], v192 offset:22528
	ds_read_b128 v[228:231], v192 offset:23552
	global_load_lds_dwordx4 v[170:171], off
	s_add_i32 m0, s23, 0x2000
	s_add_u32 s58, s26, 0x100000
	v_lshl_add_u64 v[210:211], s[26:27], 0, v[172:173]
	s_addc_u32 s59, s27, 0
	s_add_i32 s17, s17, s34
	global_load_lds_dwordx4 v[210:211], off
	v_lshl_add_u64 v[232:233], s[58:59], 0, v[158:159]
	s_mov_b32 m0, s17
	v_lshl_add_u64 v[234:235], s[28:29], 0, v[156:157]
	global_load_lds_dwordx4 v[232:233], off
	v_lshl_add_u64 v[232:233], s[58:59], 0, v[172:173]
	s_add_i32 m0, s17, 0x2000
	s_nop 0
	global_load_lds_dwordx4 v[232:233], off
	v_lshl_add_u64 v[232:233], s[28:29], 0, v[154:155]
	s_mov_b32 m0, s35
	s_nop 0
	global_load_lds_dwordx4 v[232:233], off
	s_mov_b32 m0, s4
	s_nop 0
	global_load_lds_dwordx4 v[234:235], off
	s_waitcnt vmcnt(8)
	s_waitcnt lgkmcnt(0)
	s_barrier
	v_mfma_f32_16x16x32_bf16 v[62:65], v[130:133], v[186:189], v[62:65]
	v_mfma_f32_16x16x32_bf16 v[58:61], v[138:141], v[186:189], v[58:61]
	v_mfma_f32_16x16x32_bf16 v[54:57], v[130:133], v[198:201], v[54:57]
	v_mfma_f32_16x16x32_bf16 v[46:49], v[138:141], v[198:201], v[46:49]
	v_mfma_f32_16x16x32_bf16 v[38:41], v[130:133], v[206:209], v[38:41]
	v_mfma_f32_16x16x32_bf16 v[30:33], v[138:141], v[206:209], v[30:33]
	v_mfma_f32_16x16x32_bf16 v[22:25], v[130:133], v[224:227], v[22:25]
	v_mfma_f32_16x16x32_bf16 v[14:17], v[138:141], v[224:227], v[14:17]
	v_mfma_f32_16x16x32_bf16 v[62:65], v[134:137], v[194:197], v[62:65]
	v_mfma_f32_16x16x32_bf16 v[58:61], v[142:145], v[194:197], v[58:61]
	v_mfma_f32_16x16x32_bf16 v[54:57], v[134:137], v[202:205], v[54:57]
	v_mfma_f32_16x16x32_bf16 v[46:49], v[142:145], v[202:205], v[46:49]
	v_mfma_f32_16x16x32_bf16 v[38:41], v[134:137], v[220:223], v[38:41]
	v_mfma_f32_16x16x32_bf16 v[30:33], v[142:145], v[220:223], v[30:33]
	v_mfma_f32_16x16x32_bf16 v[22:25], v[134:137], v[228:231], v[22:25]
	v_mfma_f32_16x16x32_bf16 v[14:17], v[142:145], v[228:231], v[14:17]
	v_mfma_f32_16x16x32_bf16 v[50:53], v[146:149], v[186:189], v[50:53]
	v_mfma_f32_16x16x32_bf16 v[42:45], v[178:181], v[186:189], v[42:45]
	v_mfma_f32_16x16x32_bf16 v[34:37], v[146:149], v[198:201], v[34:37]
	v_mfma_f32_16x16x32_bf16 v[26:29], v[178:181], v[198:201], v[26:29]
	v_mfma_f32_16x16x32_bf16 v[18:21], v[146:149], v[206:209], v[18:21]
	v_mfma_f32_16x16x32_bf16 v[10:13], v[178:181], v[206:209], v[10:13]
	v_mfma_f32_16x16x32_bf16 v[6:9], v[146:149], v[224:227], v[6:9]
	v_mfma_f32_16x16x32_bf16 v[2:5], v[178:181], v[224:227], v[2:5]
	v_mfma_f32_16x16x32_bf16 v[50:53], v[150:153], v[194:197], v[50:53]
	v_mfma_f32_16x16x32_bf16 v[42:45], v[182:185], v[194:197], v[42:45]
	v_mfma_f32_16x16x32_bf16 v[34:37], v[150:153], v[202:205], v[34:37]
	v_mfma_f32_16x16x32_bf16 v[26:29], v[182:185], v[202:205], v[26:29]
	v_mfma_f32_16x16x32_bf16 v[18:21], v[150:153], v[220:223], v[18:21]
	v_mfma_f32_16x16x32_bf16 v[10:13], v[182:185], v[220:223], v[10:13]
	v_mfma_f32_16x16x32_bf16 v[6:9], v[150:153], v[228:231], v[6:9]
	v_mfma_f32_16x16x32_bf16 v[2:5], v[182:185], v[228:231], v[2:5]
	s_barrier
; #define PG8_STAGE(bufoff, gbase, voff) do { _Pragma("unroll") for (int _i = 0; _i < 2; ++_i) \
;         __builtin_amdgcn_global_load_lds((const unsigned*)((const char*)(gbase) + (voff)[_i]), (PG8_LAS unsigned*)(lds + (bufoff) + ldsw + _i * 8192), 16, 0, 0); } while (0)
; #define PG8_LDA(dst, b, h) do { _Pragma("unroll") for (int m = 0; m < 4; ++m) _Pragma("unroll") for (int k = 0; k < 2; ++k) dst[m][k] = *(const PG8_LAS bf16x8*)(lds + PG8_SA(b, h) + aoff + m * 2048 + k * 1024); } while (0)
; #define PG8_LDB(dst, b, h) do { _Pragma("unroll") for (int n = 0; n < 2; ++n) _Pragma("unroll") for (int k = 0; k < 2; ++k) dst[n][k] = *(const PG8_LAS bf16x8*)(lds + PG8_SB(b, h) + boff + n * 2048 + k * 1024); } while (0)
; #define PG8_MMA(ai, bj, At, Bt) do { __builtin_amdgcn_s_setprio(1); _Pragma("unroll") for (int m = 0; m < 4; ++m) _Pragma("unroll") for (int n = 0; n < 2; ++n) _Pragma("unroll") for (int k = 0; k < 2; ++k) \
;         acc[ai][bj][m][n] = __builtin_amdgcn_mfma_f32_16x16x32_bf16(Bt[n][k], At[m][k], acc[ai][bj][m][n], 0, 0, 0); __builtin_amdgcn_s_setprio(0); } while (0)
; #define PG8_WAIT_V(n) asm volatile("s_waitcnt vmcnt(" #n ")" ::: "memory")
; #define PG8_WAIT_L(n) asm volatile("s_waitcnt lgkmcnt(" #n ")" ::: "memory")
; #define PG8_BAR __builtin_amdgcn_s_barrier()
; #define PG8_SCHED __builtin_amdgcn_sched_barrier(0)
; template <class Epi, class Sched, bool ALIGN_EPI = false, bool SP2 = false>
; __device__ __forceinline__ void gemm_phase(PG8_LAS unsigned char* lds, const Gemm g, const Sched& S, const Epi& E) {
;     ...
;             PG8_LDB(B0, 1, 0); PG8_LDB(B1, 1, 1); PG8_SCHED; PG8_LDA(At, 1, 0); PG8_STAGE(PG8_SA(0, 1), a2 + hstep, voffA);
;             PG8_WAIT_V(8); PG8_WAIT_L(0); PG8_BAR; PG8_MMA(0, 0, At, B0); PG8_MMA(0, 1, At, B1); PG8_BAR; PG8_SCHED;
;             PG8_LDA(At, 1, 1); PG8_STAGE(PG8_SB(1, 0), b3, voffB); PG8_STAGE(PG8_SB(1, 1), b3 + hstep, voffB); PG8_STAGE(PG8_SA(1, 0), a3, voffA);
;             PG8_WAIT_V(8); PG8_WAIT_L(0); PG8_BAR; PG8_MMA(1, 0, At, B0); PG8_MMA(1, 1, At, B1); PG8_BAR; PG8_SCHED;
	s_add_i32 s17, 0, 0x18000
	s_add_i32 s23, 0, 0x1c000
	v_add_u32_e32 v142, s17, v190
	v_add_u32_e32 v182, s23, v190
	ds_read_b128 v[130:133], v142
	ds_read_b128 v[134:137], v142 offset:1024
	ds_read_b128 v[138:141], v142 offset:2048
	ds_read_b128 v[142:145], v142 offset:3072
	ds_read_b128 v[146:149], v182
	ds_read_b128 v[150:153], v182 offset:1024
	ds_read_b128 v[178:181], v182 offset:2048
	ds_read_b128 v[182:185], v182 offset:3072
	s_add_u32 s28, s28, 0x100000
	s_addc_u32 s29, s29, 0
	s_mov_b32 m0, s5
	v_lshl_add_u64 v[236:237], s[28:29], 0, v[154:155]
	ds_read_b128 v[186:189], v192 offset:32768
	ds_read_b128 v[194:197], v192 offset:33792
	ds_read_b128 v[198:201], v192 offset:34816
	ds_read_b128 v[202:205], v192 offset:35840
	ds_read_b128 v[206:209], v192 offset:36864
	ds_read_b128 v[220:223], v192 offset:37888
	ds_read_b128 v[224:227], v192 offset:38912
	ds_read_b128 v[228:231], v192 offset:39936
	global_load_lds_dwordx4 v[236:237], off
	v_lshl_add_u64 v[236:237], s[28:29], 0, v[156:157]
	s_mov_b32 m0, s6
	s_nop 0
	global_load_lds_dwordx4 v[236:237], off
	s_waitcnt vmcnt(8)
	s_waitcnt lgkmcnt(0)
	s_barrier
	v_mfma_f32_16x16x32_bf16 v[126:129], v[130:133], v[186:189], v[126:129]
	v_mfma_f32_16x16x32_bf16 v[122:125], v[138:141], v[186:189], v[122:125]
	v_mfma_f32_16x16x32_bf16 v[118:121], v[130:133], v[198:201], v[118:121]
	v_mfma_f32_16x16x32_bf16 v[114:117], v[138:141], v[198:201], v[114:117]
	v_mfma_f32_16x16x32_bf16 v[102:105], v[130:133], v[206:209], v[102:105]
	v_mfma_f32_16x16x32_bf16 v[94:97], v[138:141], v[206:209], v[94:97]
	v_mfma_f32_16x16x32_bf16 v[86:89], v[130:133], v[224:227], v[86:89]
	v_mfma_f32_16x16x32_bf16 v[78:81], v[138:141], v[224:227], v[78:81]
	v_mfma_f32_16x16x32_bf16 v[126:129], v[134:137], v[194:197], v[126:129]
	v_mfma_f32_16x16x32_bf16 v[122:125], v[142:145], v[194:197], v[122:125]
	v_mfma_f32_16x16x32_bf16 v[118:121], v[134:137], v[202:205], v[118:121]
	v_mfma_f32_16x16x32_bf16 v[114:117], v[142:145], v[202:205], v[114:117]
	v_mfma_f32_16x16x32_bf16 v[102:105], v[134:137], v[220:223], v[102:105]
	v_mfma_f32_16x16x32_bf16 v[94:97], v[142:145], v[220:223], v[94:97]
	v_mfma_f32_16x16x32_bf16 v[86:89], v[134:137], v[228:231], v[86:89]
	v_mfma_f32_16x16x32_bf16 v[78:81], v[142:145], v[228:231], v[78:81]
	v_mfma_f32_16x16x32_bf16 v[110:113], v[146:149], v[186:189], v[110:113]
	v_mfma_f32_16x16x32_bf16 v[106:109], v[178:181], v[186:189], v[106:109]
	v_mfma_f32_16x16x32_bf16 v[98:101], v[146:149], v[198:201], v[98:101]
	v_mfma_f32_16x16x32_bf16 v[90:93], v[178:181], v[198:201], v[90:93]
	v_mfma_f32_16x16x32_bf16 v[82:85], v[146:149], v[206:209], v[82:85]
	v_mfma_f32_16x16x32_bf16 v[74:77], v[178:181], v[206:209], v[74:77]
	v_mfma_f32_16x16x32_bf16 v[70:73], v[146:149], v[224:227], v[70:73]
	v_mfma_f32_16x16x32_bf16 v[66:69], v[178:181], v[224:227], v[66:69]
	v_mfma_f32_16x16x32_bf16 v[110:113], v[150:153], v[194:197], v[110:113]
	v_mfma_f32_16x16x32_bf16 v[106:109], v[182:185], v[194:197], v[106:109]
	v_mfma_f32_16x16x32_bf16 v[98:101], v[150:153], v[202:205], v[98:101]
	v_mfma_f32_16x16x32_bf16 v[90:93], v[182:185], v[202:205], v[90:93]
	v_mfma_f32_16x16x32_bf16 v[82:85], v[150:153], v[220:223], v[82:85]
	v_mfma_f32_16x16x32_bf16 v[74:77], v[182:185], v[220:223], v[74:77]
	v_mfma_f32_16x16x32_bf16 v[70:73], v[150:153], v[228:231], v[70:73]
	v_mfma_f32_16x16x32_bf16 v[66:69], v[182:185], v[228:231], v[66:69]
	s_barrier
	s_add_i32 s17, s17, s34
	v_lshl_add_u64 v[170:171], v[170:171], 0, s[96:97]
	s_mov_b32 m0, s17
	ds_read_b128 v[186:189], v192 offset:49152
	ds_read_b128 v[194:197], v192 offset:50176
	ds_read_b128 v[198:201], v192 offset:51200
	ds_read_b128 v[202:205], v192 offset:52224
	ds_read_b128 v[206:209], v192 offset:53248
	ds_read_b128 v[220:223], v192 offset:54272
	ds_read_b128 v[224:227], v192 offset:55296
	ds_read_b128 v[228:231], v192 offset:56320
	global_load_lds_dwordx4 v[170:171], off
	s_add_i32 m0, s17, 0x2000
	s_add_u32 s26, s26, 0x100080
	v_lshl_add_u64 v[170:171], v[210:211], 0, s[96:97]
	s_addc_u32 s27, s27, 0
	s_add_i32 s17, s23, s34
	global_load_lds_dwordx4 v[170:171], off
	v_lshl_add_u64 v[170:171], s[26:27], 0, v[158:159]
	s_mov_b32 m0, s17
	s_nop 0
	global_load_lds_dwordx4 v[170:171], off
	v_lshl_add_u64 v[170:171], s[26:27], 0, v[172:173]
	s_add_i32 m0, s17, 0x2000
	s_nop 0
	global_load_lds_dwordx4 v[170:171], off
	v_lshl_add_u64 v[170:171], v[232:233], 0, s[96:97]
	s_mov_b32 m0, s9
	s_nop 0
	global_load_lds_dwordx4 v[170:171], off
	v_lshl_add_u64 v[170:171], v[234:235], 0, s[96:97]
	s_mov_b32 m0, s10
	s_nop 0
	global_load_lds_dwordx4 v[170:171], off
	s_waitcnt vmcnt(8)
	s_waitcnt lgkmcnt(0)
	s_barrier
	v_mfma_f32_16x16x32_bf16 v[62:65], v[130:133], v[186:189], v[62:65]
	v_mfma_f32_16x16x32_bf16 v[58:61], v[138:141], v[186:189], v[58:61]
	v_mfma_f32_16x16x32_bf16 v[54:57], v[130:133], v[198:201], v[54:57]
	v_mfma_f32_16x16x32_bf16 v[46:49], v[138:141], v[198:201], v[46:49]
	v_mfma_f32_16x16x32_bf16 v[38:41], v[130:133], v[206:209], v[38:41]
	v_mfma_f32_16x16x32_bf16 v[30:33], v[138:141], v[206:209], v[30:33]
	v_mfma_f32_16x16x32_bf16 v[22:25], v[130:133], v[224:227], v[22:25]
	v_mfma_f32_16x16x32_bf16 v[14:17], v[138:141], v[224:227], v[14:17]
	v_mfma_f32_16x16x32_bf16 v[62:65], v[134:137], v[194:197], v[62:65]
	v_mfma_f32_16x16x32_bf16 v[58:61], v[142:145], v[194:197], v[58:61]
	v_mfma_f32_16x16x32_bf16 v[54:57], v[134:137], v[202:205], v[54:57]
	v_mfma_f32_16x16x32_bf16 v[46:49], v[142:145], v[202:205], v[46:49]
	v_mfma_f32_16x16x32_bf16 v[38:41], v[134:137], v[220:223], v[38:41]
	v_mfma_f32_16x16x32_bf16 v[30:33], v[142:145], v[220:223], v[30:33]
	v_mfma_f32_16x16x32_bf16 v[22:25], v[134:137], v[228:231], v[22:25]
	v_mfma_f32_16x16x32_bf16 v[14:17], v[142:145], v[228:231], v[14:17]
	v_mfma_f32_16x16x32_bf16 v[50:53], v[146:149], v[186:189], v[50:53]
	v_mfma_f32_16x16x32_bf16 v[42:45], v[178:181], v[186:189], v[42:45]
	v_mfma_f32_16x16x32_bf16 v[34:37], v[146:149], v[198:201], v[34:37]
	v_mfma_f32_16x16x32_bf16 v[26:29], v[178:181], v[198:201], v[26:29]
	v_mfma_f32_16x16x32_bf16 v[18:21], v[146:149], v[206:209], v[18:21]
	v_mfma_f32_16x16x32_bf16 v[10:13], v[178:181], v[206:209], v[10:13]
	v_mfma_f32_16x16x32_bf16 v[6:9], v[146:149], v[224:227], v[6:9]
	v_mfma_f32_16x16x32_bf16 v[2:5], v[178:181], v[224:227], v[2:5]
	v_mfma_f32_16x16x32_bf16 v[50:53], v[150:153], v[194:197], v[50:53]
	v_mfma_f32_16x16x32_bf16 v[42:45], v[182:185], v[194:197], v[42:45]
	v_mfma_f32_16x16x32_bf16 v[34:37], v[150:153], v[202:205], v[34:37]
	v_mfma_f32_16x16x32_bf16 v[26:29], v[182:185], v[202:205], v[26:29]
	v_mfma_f32_16x16x32_bf16 v[18:21], v[150:153], v[220:223], v[18:21]
	v_mfma_f32_16x16x32_bf16 v[10:13], v[182:185], v[220:223], v[10:13]
	v_mfma_f32_16x16x32_bf16 v[6:9], v[150:153], v[228:231], v[6:9]
	v_mfma_f32_16x16x32_bf16 v[2:5], v[182:185], v[228:231], v[2:5]
	s_barrier
	s_add_u32 s15, s15, 0x100
	s_addc_u32 s16, s16, 0
	s_add_u32 s24, s24, 0x100
	s_addc_u32 s25, s25, 0
	s_cmp_ge_i32 s21, s13
	s_mov_b32 s17, s21
	s_cbranch_scc0 .LBB0_530

;     __host__ __device__ bool next(int i, Unit& u) const { return at((long)i * G + c, u); }
; #define PG8_STAGE(bufoff, gbase, voff) do { _Pragma("unroll") for (int _i = 0; _i < 2; ++_i) \
;         __builtin_amdgcn_global_load_lds((const unsigned*)((const char*)(gbase) + (voff)[_i]), (PG8_LAS unsigned*)(lds + (bufoff) + ldsw + _i * 8192), 16, 0, 0); } while (0)
; #define PG8_LDA(dst, b, h) do { _Pragma("unroll") for (int m = 0; m < 4; ++m) _Pragma("unroll") for (int k = 0; k < 2; ++k) dst[m][k] = *(const PG8_LAS bf16x8*)(lds + PG8_SA(b, h) + aoff + m * 2048 + k * 1024); } while (0)
; #define PG8_LDB(dst, b, h) do { _Pragma("unroll") for (int n = 0; n < 2; ++n) _Pragma("unroll") for (int k = 0; k < 2; ++k) dst[n][k] = *(const PG8_LAS bf16x8*)(lds + PG8_SB(b, h) + boff + n * 2048 + k * 1024); } while (0)
; #define PG8_WAIT_V(n) asm volatile("s_waitcnt vmcnt(" #n ")" ::: "memory")
; #define PG8_BAR __builtin_amdgcn_s_barrier()
; template <class Epi, class Sched, bool ALIGN_EPI = false, bool SP2 = false>
; __device__ __forceinline__ void gemm_phase(PG8_LAS unsigned char* lds, const Gemm g, const Sched& S, const Epi& E) {
;     ...
;         const bool has_next = S.next(ui + 1, nxt);
;         const char* nA = has_next ? (const char*)g.A + (size_t)nxt.pm * tstep + (size_t)nxt.k0 * kstep : cA; const char* nB = has_next ? (const char*)g.Bt + (size_t)nxt.pn * tstep + (size_t)nxt.k0 * kstep : cB;
;         const int nt = cur.nt;
;         for (int t = 0; t < nt; t += 2) {
;             const bool last = (t == nt - 2);
;             const char* a1 = cA + (size_t)(t + 1) * kstep;
;             const char* a2 = last ? nA : cA + (size_t)(t + 2) * kstep; const char* b2 = last ? nB : cB + (size_t)(t + 2) * kstep;
;             const char* a3 = a2 + kstep; const char* b3 = b2 + kstep;
;             if (last && has_next) S.a_ready(nxt);
;             if constexpr (SP2) {
;             PG8_LDB(B0, 0, 0); PG8_LDB(B1, 0, 1); PG8_SCHED; PG8_LDA(At, 0, 0); PG8_STAGE(PG8_SA(1, 1), a1 + hstep, voffA);
;             PG8_WAIT_V(8); PG8_WAIT_L(0); PG8_BAR; PG8_MMA(0, 0, At, B0); PG8_MMA(0, 1, At, B1); PG8_BAR; PG8_SCHED;
;             PG8_LDA(At, 0, 1); PG8_STAGE(PG8_SB(0, 0), b2, voffB); PG8_STAGE(PG8_SB(0, 1), b2 + hstep, voffB); PG8_STAGE(PG8_SA(0, 0), a2, voffA);
;             PG8_WAIT_V(8); PG8_WAIT_L(0); PG8_BAR; PG8_MMA(1, 0, At, B0); PG8_MMA(1, 1, At, B1); PG8_BAR; PG8_SCHED;
.LBB0_709:
	s_ashr_i32 s63, s62, 31
	s_lshl_b64 s[16:17], s[62:63], 21
	s_add_u32 s28, s4, s16
	s_addc_u32 s29, s5, s17
	s_and_b64 s[16:17], s[20:21], exec
	s_cselect_b32 s30, s29, s23
	s_cselect_b32 s31, s28, s22
	s_ashr_i32 s61, s60, 31
	s_lshl_b64 s[16:17], s[60:61], 21
	s_add_u32 s26, s6, s16
	s_addc_u32 s27, s7, s17
	s_and_b64 s[16:17], s[20:21], exec
	s_cselect_b32 s61, s27, s25
	s_cselect_b32 s63, s26, s24
	s_add_u32 s16, s24, 0x100
	s_addc_u32 s17, s25, 0
	s_add_u32 vcc_lo, s22, 0x100080
	s_addc_u32 vcc_hi, s23, 0
	s_mov_b32 s65, -2
	s_waitcnt vmcnt(0)
	s_add_u32 s22, vcc_lo, 0xfff00080
	s_addc_u32 s23, vcc_hi, -1
	s_add_i32 s68, 0, 0x10000
	s_cmp_eq_u32 s65, 60
	s_cselect_b32 s25, s30, s23
	s_cselect_b32 s24, s31, s22
	s_cselect_b32 s23, s61, s17
	s_cselect_b32 s22, s63, s16
	s_add_i32 s70, 0, 0x14000
	v_add_u32_e32 v70, s68, v220
	v_add_u32_e32 v170, s70, v220
	ds_read_b128 v[50:53], v70
	ds_read_b128 v[54:57], v70 offset:1024
	ds_read_b128 v[66:69], v70 offset:2048
	ds_read_b128 v[70:73], v70 offset:3072
	ds_read_b128 v[74:77], v170
	ds_read_b128 v[86:89], v170 offset:1024
	ds_read_b128 v[154:157], v170 offset:2048
	ds_read_b128 v[188:191], v170 offset:3072
	v_lshl_add_u64 v[170:171], vcc, 0, v[186:187]
	s_add_i32 m0, s10, 0xc000
	ds_read_b128 v[192:195], v222
	ds_read_b128 v[196:199], v222 offset:1024
	ds_read_b128 v[200:203], v222 offset:2048
	ds_read_b128 v[204:207], v222 offset:3072
	ds_read_b128 v[224:227], v222 offset:4096
	ds_read_b128 v[228:231], v222 offset:5120
	ds_read_b128 v[232:235], v222 offset:6144
	ds_read_b128 v[236:239], v222 offset:7168
	global_load_lds_dwordx4 v[170:171], off
	v_lshl_add_u64 v[170:171], vcc, 0, v[184:185]
	s_add_i32 m0, s10, 0xe000
	s_nop 0
	global_load_lds_dwordx4 v[170:171], off
	s_waitcnt vmcnt(8)
	s_waitcnt lgkmcnt(0)
	s_barrier
	v_mfma_f32_16x16x32_bf16 v[142:145], v[50:53], v[192:195], 0
	v_mfma_f32_16x16x32_bf16 v[130:133], v[66:69], v[192:195], 0
	v_mfma_f32_16x16x32_bf16 v[138:141], v[50:53], v[200:203], 0
	v_mfma_f32_16x16x32_bf16 v[126:129], v[66:69], v[200:203], 0
	v_mfma_f32_16x16x32_bf16 v[118:121], v[50:53], v[224:227], 0
	v_mfma_f32_16x16x32_bf16 v[110:113], v[66:69], v[224:227], 0
	v_mfma_f32_16x16x32_bf16 v[98:101], v[50:53], v[232:235], 0
	v_mfma_f32_16x16x32_bf16 v[94:97], v[66:69], v[232:235], 0
	v_mfma_f32_16x16x32_bf16 v[142:145], v[54:57], v[196:199], v[142:145]
	v_mfma_f32_16x16x32_bf16 v[130:133], v[70:73], v[196:199], v[130:133]
	v_mfma_f32_16x16x32_bf16 v[138:141], v[54:57], v[204:207], v[138:141]
	v_mfma_f32_16x16x32_bf16 v[126:129], v[70:73], v[204:207], v[126:129]
	v_mfma_f32_16x16x32_bf16 v[118:121], v[54:57], v[228:231], v[118:121]
	v_mfma_f32_16x16x32_bf16 v[110:113], v[70:73], v[228:231], v[110:113]
	v_mfma_f32_16x16x32_bf16 v[98:101], v[54:57], v[236:239], v[98:101]
	v_mfma_f32_16x16x32_bf16 v[94:97], v[70:73], v[236:239], v[94:97]
	v_mfma_f32_16x16x32_bf16 v[150:153], v[74:77], v[192:195], 0
	v_mfma_f32_16x16x32_bf16 v[146:149], v[154:157], v[192:195], 0
	v_mfma_f32_16x16x32_bf16 v[134:137], v[74:77], v[200:203], 0
	v_mfma_f32_16x16x32_bf16 v[122:125], v[154:157], v[200:203], 0
	v_mfma_f32_16x16x32_bf16 v[114:117], v[74:77], v[224:227], 0
	v_mfma_f32_16x16x32_bf16 v[106:109], v[154:157], v[224:227], 0
	v_mfma_f32_16x16x32_bf16 v[102:105], v[74:77], v[232:235], 0
	v_mfma_f32_16x16x32_bf16 v[90:93], v[154:157], v[232:235], 0
	v_mfma_f32_16x16x32_bf16 v[150:153], v[86:89], v[196:199], v[150:153]
	v_mfma_f32_16x16x32_bf16 v[146:149], v[188:191], v[196:199], v[146:149]
	v_mfma_f32_16x16x32_bf16 v[134:137], v[86:89], v[204:207], v[134:137]
	v_mfma_f32_16x16x32_bf16 v[122:125], v[188:191], v[204:207], v[122:125]
	v_mfma_f32_16x16x32_bf16 v[114:117], v[86:89], v[228:231], v[114:117]
	v_mfma_f32_16x16x32_bf16 v[106:109], v[188:191], v[228:231], v[106:109]
	v_mfma_f32_16x16x32_bf16 v[102:105], v[86:89], v[236:239], v[102:105]
	v_mfma_f32_16x16x32_bf16 v[90:93], v[188:191], v[236:239], v[90:93]
	s_barrier
	s_add_i32 s68, s68, s9
	v_lshl_add_u64 v[170:171], s[22:23], 0, v[158:159]
	s_mov_b32 m0, s68
	ds_read_b128 v[192:195], v222 offset:16384
	ds_read_b128 v[196:199], v222 offset:17408
	ds_read_b128 v[200:203], v222 offset:18432
	ds_read_b128 v[204:207], v222 offset:19456
	ds_read_b128 v[224:227], v222 offset:20480
	ds_read_b128 v[228:231], v222 offset:21504
	ds_read_b128 v[232:235], v222 offset:22528
	ds_read_b128 v[236:239], v222 offset:23552
	global_load_lds_dwordx4 v[170:171], off
	s_add_i32 m0, s68, 0x2000
	s_add_u32 s68, s22, 0x100000
	v_lshl_add_u64 v[208:209], s[22:23], 0, v[172:173]
	s_addc_u32 s69, s23, 0
	s_add_i32 s70, s70, s9
	global_load_lds_dwordx4 v[208:209], off
	v_lshl_add_u64 v[210:211], s[68:69], 0, v[158:159]
	s_mov_b32 m0, s70
	v_lshl_add_u64 v[244:245], s[24:25], 0, v[174:175]
	global_load_lds_dwordx4 v[210:211], off
	v_lshl_add_u64 v[210:211], s[68:69], 0, v[172:173]
	s_add_i32 m0, s70, 0x2000
	s_nop 0
	global_load_lds_dwordx4 v[210:211], off
	v_lshl_add_u64 v[210:211], s[24:25], 0, v[176:177]
	s_mov_b32 m0, s10
	s_nop 0
	global_load_lds_dwordx4 v[210:211], off
	s_mov_b32 m0, s11
	s_nop 0
	global_load_lds_dwordx4 v[244:245], off
	s_waitcnt vmcnt(8)
	s_waitcnt lgkmcnt(0)
	s_barrier
; #define PG8_STAGE(bufoff, gbase, voff) do { _Pragma("unroll") for (int _i = 0; _i < 2; ++_i) \
;         __builtin_amdgcn_global_load_lds((const unsigned*)((const char*)(gbase) + (voff)[_i]), (PG8_LAS unsigned*)(lds + (bufoff) + ldsw + _i * 8192), 16, 0, 0); } while (0)
; #define PG8_LDA(dst, b, h) do { _Pragma("unroll") for (int m = 0; m < 4; ++m) _Pragma("unroll") for (int k = 0; k < 2; ++k) dst[m][k] = *(const PG8_LAS bf16x8*)(lds + PG8_SA(b, h) + aoff + m * 2048 + k * 1024); } while (0)
; #define PG8_LDB(dst, b, h) do { _Pragma("unroll") for (int n = 0; n < 2; ++n) _Pragma("unroll") for (int k = 0; k < 2; ++k) dst[n][k] = *(const PG8_LAS bf16x8*)(lds + PG8_SB(b, h) + boff + n * 2048 + k * 1024); } while (0)
; #define PG8_MMA(ai, bj, At, Bt) do { __builtin_amdgcn_s_setprio(1); _Pragma("unroll") for (int m = 0; m < 4; ++m) _Pragma("unroll") for (int n = 0; n < 2; ++n) _Pragma("unroll") for (int k = 0; k < 2; ++k) \
;         acc[ai][bj][m][n] = __builtin_amdgcn_mfma_f32_16x16x32_bf16(Bt[n][k], At[m][k], acc[ai][bj][m][n], 0, 0, 0); __builtin_amdgcn_s_setprio(0); } while (0)
; #define PG8_WAIT_V(n) asm volatile("s_waitcnt vmcnt(" #n ")" ::: "memory")
; #define PG8_WAIT_L(n) asm volatile("s_waitcnt lgkmcnt(" #n ")" ::: "memory")
; #define PG8_BAR __builtin_amdgcn_s_barrier()
; #define PG8_SCHED __builtin_amdgcn_sched_barrier(0)
; template <class Epi, class Sched, bool ALIGN_EPI = false, bool SP2 = false>
; __device__ __forceinline__ void gemm_phase(PG8_LAS unsigned char* lds, const Gemm g, const Sched& S, const Epi& E) {
;     ...
;             PG8_WAIT_V(8); PG8_WAIT_L(0); PG8_BAR; PG8_MMA(1, 0, At, B0); PG8_MMA(1, 1, At, B1); PG8_BAR; PG8_SCHED;
;             PG8_LDB(B0, 1, 0); PG8_LDB(B1, 1, 1); PG8_SCHED; PG8_LDA(At, 1, 0); PG8_STAGE(PG8_SA(0, 1), a2 + hstep, voffA);
;             PG8_WAIT_V(8); PG8_WAIT_L(0); PG8_BAR; PG8_MMA(0, 0, At, B0); PG8_MMA(0, 1, At, B1); PG8_BAR; PG8_SCHED;
	v_mfma_f32_16x16x32_bf16 v[62:65], v[50:53], v[192:195], 0
	v_mfma_f32_16x16x32_bf16 v[42:45], v[66:69], v[192:195], 0
	v_mfma_f32_16x16x32_bf16 v[58:61], v[50:53], v[200:203], 0
	v_mfma_f32_16x16x32_bf16 v[38:41], v[66:69], v[200:203], 0
	v_mfma_f32_16x16x32_bf16 v[30:33], v[50:53], v[224:227], 0
	v_mfma_f32_16x16x32_bf16 v[22:25], v[66:69], v[224:227], 0
	v_mfma_f32_16x16x32_bf16 v[10:13], v[50:53], v[232:235], 0
	v_mfma_f32_16x16x32_bf16 v[6:9], v[66:69], v[232:235], 0
	v_mfma_f32_16x16x32_bf16 v[62:65], v[54:57], v[196:199], v[62:65]
	v_mfma_f32_16x16x32_bf16 v[42:45], v[70:73], v[196:199], v[42:45]
	v_mfma_f32_16x16x32_bf16 v[58:61], v[54:57], v[204:207], v[58:61]
	v_mfma_f32_16x16x32_bf16 v[38:41], v[70:73], v[204:207], v[38:41]
	v_mfma_f32_16x16x32_bf16 v[30:33], v[54:57], v[228:231], v[30:33]
	v_mfma_f32_16x16x32_bf16 v[22:25], v[70:73], v[228:231], v[22:25]
	v_mfma_f32_16x16x32_bf16 v[10:13], v[54:57], v[236:239], v[10:13]
	v_mfma_f32_16x16x32_bf16 v[6:9], v[70:73], v[236:239], v[6:9]
	v_mfma_f32_16x16x32_bf16 v[46:49], v[74:77], v[200:203], 0
	v_mfma_f32_16x16x32_bf16 v[34:37], v[154:157], v[200:203], 0
	v_mfma_f32_16x16x32_bf16 v[26:29], v[74:77], v[224:227], 0
	v_mfma_f32_16x16x32_bf16 v[18:21], v[154:157], v[224:227], 0
	v_mfma_f32_16x16x32_bf16 v[14:17], v[74:77], v[232:235], 0
	v_mfma_f32_16x16x32_bf16 v[2:5], v[154:157], v[232:235], 0
	v_mfma_f32_16x16x32_bf16 v[50:53], v[74:77], v[192:195], 0
	v_mfma_f32_16x16x32_bf16 v[54:57], v[154:157], v[192:195], 0
	v_mfma_f32_16x16x32_bf16 v[46:49], v[86:89], v[204:207], v[46:49]
	v_mfma_f32_16x16x32_bf16 v[34:37], v[188:191], v[204:207], v[34:37]
	v_mfma_f32_16x16x32_bf16 v[26:29], v[86:89], v[228:231], v[26:29]
	v_mfma_f32_16x16x32_bf16 v[18:21], v[188:191], v[228:231], v[18:21]
	v_mfma_f32_16x16x32_bf16 v[14:17], v[86:89], v[236:239], v[14:17]
	v_mfma_f32_16x16x32_bf16 v[2:5], v[188:191], v[236:239], v[2:5]
	v_mfma_f32_16x16x32_bf16 v[50:53], v[86:89], v[196:199], v[50:53]
	v_mfma_f32_16x16x32_bf16 v[54:57], v[188:191], v[196:199], v[54:57]
	s_barrier
	s_add_i32 s68, 0, 0x18000
	s_add_i32 s69, 0, 0x1c000
	v_add_u32_e32 v78, s68, v220
	v_add_u32_e32 v82, s69, v220
	ds_read_b128 v[66:69], v78
	ds_read_b128 v[70:73], v78 offset:1024
	ds_read_b128 v[74:77], v78 offset:2048
	ds_read_b128 v[78:81], v78 offset:3072
	ds_read_b128 v[86:89], v82
	ds_read_b128 v[154:157], v82 offset:1024
	ds_read_b128 v[188:191], v82 offset:2048
	ds_read_b128 v[192:195], v82 offset:3072
	s_add_u32 s24, s24, 0x100000
	s_addc_u32 s25, s25, 0
	s_mov_b32 m0, s12
	v_lshl_add_u64 v[240:241], s[24:25], 0, v[176:177]
	ds_read_b128 v[82:85], v222 offset:32768
	ds_read_b128 v[196:199], v222 offset:33792
	ds_read_b128 v[200:203], v222 offset:34816
	ds_read_b128 v[204:207], v222 offset:35840
	ds_read_b128 v[224:227], v222 offset:36864
	ds_read_b128 v[228:231], v222 offset:37888
	ds_read_b128 v[232:235], v222 offset:38912
	ds_read_b128 v[236:239], v222 offset:39936
	global_load_lds_dwordx4 v[240:241], off
	v_lshl_add_u64 v[240:241], s[24:25], 0, v[174:175]
	s_mov_b32 m0, s13
	s_nop 0
	global_load_lds_dwordx4 v[240:241], off
	s_waitcnt vmcnt(8)
	s_waitcnt lgkmcnt(0)
	s_barrier
	v_mfma_f32_16x16x32_bf16 v[142:145], v[66:69], v[82:85], v[142:145]
	v_mfma_f32_16x16x32_bf16 v[130:133], v[74:77], v[82:85], v[130:133]
	v_mfma_f32_16x16x32_bf16 v[138:141], v[66:69], v[200:203], v[138:141]
	v_mfma_f32_16x16x32_bf16 v[126:129], v[74:77], v[200:203], v[126:129]
	v_mfma_f32_16x16x32_bf16 v[118:121], v[66:69], v[224:227], v[118:121]
	v_mfma_f32_16x16x32_bf16 v[110:113], v[74:77], v[224:227], v[110:113]
	v_mfma_f32_16x16x32_bf16 v[98:101], v[66:69], v[232:235], v[98:101]
	v_mfma_f32_16x16x32_bf16 v[94:97], v[74:77], v[232:235], v[94:97]
	v_mfma_f32_16x16x32_bf16 v[142:145], v[70:73], v[196:199], v[142:145]
	v_mfma_f32_16x16x32_bf16 v[130:133], v[78:81], v[196:199], v[130:133]
	v_mfma_f32_16x16x32_bf16 v[138:141], v[70:73], v[204:207], v[138:141]
	v_mfma_f32_16x16x32_bf16 v[126:129], v[78:81], v[204:207], v[126:129]
	v_mfma_f32_16x16x32_bf16 v[118:121], v[70:73], v[228:231], v[118:121]
	v_mfma_f32_16x16x32_bf16 v[110:113], v[78:81], v[228:231], v[110:113]
	v_mfma_f32_16x16x32_bf16 v[98:101], v[70:73], v[236:239], v[98:101]
	v_mfma_f32_16x16x32_bf16 v[94:97], v[78:81], v[236:239], v[94:97]
	v_mfma_f32_16x16x32_bf16 v[150:153], v[86:89], v[82:85], v[150:153]
	v_mfma_f32_16x16x32_bf16 v[146:149], v[188:191], v[82:85], v[146:149]
	v_mfma_f32_16x16x32_bf16 v[134:137], v[86:89], v[200:203], v[134:137]
	v_mfma_f32_16x16x32_bf16 v[122:125], v[188:191], v[200:203], v[122:125]
	v_mfma_f32_16x16x32_bf16 v[114:117], v[86:89], v[224:227], v[114:117]
	v_mfma_f32_16x16x32_bf16 v[106:109], v[188:191], v[224:227], v[106:109]
	v_mfma_f32_16x16x32_bf16 v[102:105], v[86:89], v[232:235], v[102:105]
	v_mfma_f32_16x16x32_bf16 v[90:93], v[188:191], v[232:235], v[90:93]
	v_mfma_f32_16x16x32_bf16 v[150:153], v[154:157], v[196:199], v[150:153]
	v_mfma_f32_16x16x32_bf16 v[146:149], v[192:195], v[196:199], v[146:149]
	v_mfma_f32_16x16x32_bf16 v[134:137], v[154:157], v[204:207], v[134:137]
	v_mfma_f32_16x16x32_bf16 v[122:125], v[192:195], v[204:207], v[122:125]
	v_mfma_f32_16x16x32_bf16 v[114:117], v[154:157], v[228:231], v[114:117]
	v_mfma_f32_16x16x32_bf16 v[106:109], v[192:195], v[228:231], v[106:109]
	v_mfma_f32_16x16x32_bf16 v[102:105], v[154:157], v[236:239], v[102:105]
	v_mfma_f32_16x16x32_bf16 v[90:93], v[192:195], v[236:239], v[90:93]
	s_barrier
; #define PG8_STAGE(bufoff, gbase, voff) do { _Pragma("unroll") for (int _i = 0; _i < 2; ++_i) \
;         __builtin_amdgcn_global_load_lds((const unsigned*)((const char*)(gbase) + (voff)[_i]), (PG8_LAS unsigned*)(lds + (bufoff) + ldsw + _i * 8192), 16, 0, 0); } while (0)
; #define PG8_LDA(dst, b, h) do { _Pragma("unroll") for (int m = 0; m < 4; ++m) _Pragma("unroll") for (int k = 0; k < 2; ++k) dst[m][k] = *(const PG8_LAS bf16x8*)(lds + PG8_SA(b, h) + aoff + m * 2048 + k * 1024); } while (0)
; #define PG8_LDB(dst, b, h) do { _Pragma("unroll") for (int n = 0; n < 2; ++n) _Pragma("unroll") for (int k = 0; k < 2; ++k) dst[n][k] = *(const PG8_LAS bf16x8*)(lds + PG8_SB(b, h) + boff + n * 2048 + k * 1024); } while (0)
; template <class Epi, class Sched, bool ALIGN_EPI = false, bool SP2 = false>
; __device__ __forceinline__ void gemm_phase(PG8_LAS unsigned char* lds, const Gemm g, const Sched& S, const Epi& E) {
;     ...
;         for (int t = 0; t < nt; t += 2) {
;             const bool last = (t == nt - 2);
;             const char* a1 = cA + (size_t)(t + 1) * kstep;
;             const char* a2 = last ? nA : cA + (size_t)(t + 2) * kstep; const char* b2 = last ? nB : cB + (size_t)(t + 2) * kstep;
;             const char* a3 = a2 + kstep; const char* b3 = b2 + kstep;
;             if (last && has_next) S.a_ready(nxt);
;             if constexpr (SP2) {
;             PG8_LDB(B0, 0, 0); PG8_LDB(B1, 0, 1); PG8_SCHED; PG8_LDA(At, 0, 0); PG8_STAGE(PG8_SA(1, 1), a1 + hstep, voffA);
;             PG8_WAIT_V(8); PG8_WAIT_L(0); PG8_BAR; PG8_MMA(0, 0, At, B0); PG8_MMA(0, 1, At, B1); PG8_BAR; PG8_SCHED;
;             PG8_LDA(At, 0, 1); PG8_STAGE(PG8_SB(0, 0), b2, voffB); PG8_STAGE(PG8_SB(0, 1), b2 + hstep, voffB); PG8_STAGE(PG8_SA(0, 0), a2, voffA);
;             PG8_WAIT_V(8); PG8_WAIT_L(0); PG8_BAR; PG8_MMA(1, 0, At, B0); PG8_MMA(1, 1, At, B1); PG8_BAR; PG8_SCHED;
;             PG8_LDB(B0, 1, 0); PG8_LDB(B1, 1, 1); PG8_SCHED; PG8_LDA(At, 1, 0); PG8_STAGE(PG8_SA(0, 1), a2 + hstep, voffA);
;             PG8_WAIT_V(8); PG8_WAIT_L(0); PG8_BAR; PG8_MMA(0, 0, At, B0); PG8_MMA(0, 1, At, B1); PG8_BAR; PG8_SCHED;
;             PG8_LDA(At, 1, 1); PG8_STAGE(PG8_SB(1, 0), b3, voffB); PG8_STAGE(PG8_SB(1, 1), b3 + hstep, voffB); PG8_STAGE(PG8_SA(1, 0), a3, voffA);
;             PG8_WAIT_V(8); PG8_WAIT_L(0); PG8_BAR; PG8_MMA(1, 0, At, B0); PG8_MMA(1, 1, At, B1); PG8_BAR; PG8_SCHED;
	s_add_i32 s24, s68, s9
	s_nop 2
	v_lshl_add_u64 v[82:83], v[170:171], 0, s[96:97]
	s_mov_b32 m0, s24
	ds_read_b128 v[196:199], v222 offset:49152
	ds_read_b128 v[200:203], v222 offset:50176
	ds_read_b128 v[204:207], v222 offset:51200
	ds_read_b128 v[224:227], v222 offset:52224
	ds_read_b128 v[228:231], v222 offset:53248
	ds_read_b128 v[232:235], v222 offset:54272
	ds_read_b128 v[236:239], v222 offset:55296
	ds_read_b128 v[240:243], v222 offset:56320
	global_load_lds_dwordx4 v[82:83], off
	s_add_i32 m0, s24, 0x2000
	s_add_u32 s22, s22, 0x100080
	v_lshl_add_u64 v[82:83], v[208:209], 0, s[96:97]
	s_addc_u32 s23, s23, 0
	s_add_i32 s24, s69, s9
	global_load_lds_dwordx4 v[82:83], off
	v_lshl_add_u64 v[82:83], s[22:23], 0, v[158:159]
	s_mov_b32 m0, s24
	s_nop 0
	global_load_lds_dwordx4 v[82:83], off
	v_lshl_add_u64 v[82:83], s[22:23], 0, v[172:173]
	s_add_i32 m0, s24, 0x2000
	s_nop 0
	global_load_lds_dwordx4 v[82:83], off
	v_lshl_add_u64 v[82:83], v[210:211], 0, s[96:97]
	s_mov_b32 m0, s0
	s_nop 0
	global_load_lds_dwordx4 v[82:83], off
	v_lshl_add_u64 v[82:83], v[244:245], 0, s[96:97]
	s_mov_b32 m0, s34
	s_nop 0
	global_load_lds_dwordx4 v[82:83], off
	s_waitcnt vmcnt(8)
	s_waitcnt lgkmcnt(0)
	s_barrier
	v_mfma_f32_16x16x32_bf16 v[62:65], v[66:69], v[196:199], v[62:65]
	v_mfma_f32_16x16x32_bf16 v[42:45], v[74:77], v[196:199], v[42:45]
	v_mfma_f32_16x16x32_bf16 v[58:61], v[66:69], v[204:207], v[58:61]
	v_mfma_f32_16x16x32_bf16 v[38:41], v[74:77], v[204:207], v[38:41]
	v_mfma_f32_16x16x32_bf16 v[30:33], v[66:69], v[228:231], v[30:33]
	v_mfma_f32_16x16x32_bf16 v[22:25], v[74:77], v[228:231], v[22:25]
	v_mfma_f32_16x16x32_bf16 v[10:13], v[66:69], v[236:239], v[10:13]
	v_mfma_f32_16x16x32_bf16 v[6:9], v[74:77], v[236:239], v[6:9]
	v_mfma_f32_16x16x32_bf16 v[62:65], v[70:73], v[200:203], v[62:65]
	v_mfma_f32_16x16x32_bf16 v[42:45], v[78:81], v[200:203], v[42:45]
	v_mfma_f32_16x16x32_bf16 v[58:61], v[70:73], v[224:227], v[58:61]
	v_mfma_f32_16x16x32_bf16 v[38:41], v[78:81], v[224:227], v[38:41]
	v_mfma_f32_16x16x32_bf16 v[30:33], v[70:73], v[232:235], v[30:33]
	v_mfma_f32_16x16x32_bf16 v[22:25], v[78:81], v[232:235], v[22:25]
	v_mfma_f32_16x16x32_bf16 v[10:13], v[70:73], v[240:243], v[10:13]
	v_mfma_f32_16x16x32_bf16 v[6:9], v[78:81], v[240:243], v[6:9]
	v_mfma_f32_16x16x32_bf16 v[50:53], v[86:89], v[196:199], v[50:53]
	v_mfma_f32_16x16x32_bf16 v[54:57], v[188:191], v[196:199], v[54:57]
	v_mfma_f32_16x16x32_bf16 v[46:49], v[86:89], v[204:207], v[46:49]
	v_mfma_f32_16x16x32_bf16 v[34:37], v[188:191], v[204:207], v[34:37]
	v_mfma_f32_16x16x32_bf16 v[26:29], v[86:89], v[228:231], v[26:29]
	v_mfma_f32_16x16x32_bf16 v[18:21], v[188:191], v[228:231], v[18:21]
	v_mfma_f32_16x16x32_bf16 v[14:17], v[86:89], v[236:239], v[14:17]
	v_mfma_f32_16x16x32_bf16 v[2:5], v[188:191], v[236:239], v[2:5]
	v_mfma_f32_16x16x32_bf16 v[82:85], v[154:157], v[200:203], v[50:53]
	v_mfma_f32_16x16x32_bf16 v[78:81], v[192:195], v[200:203], v[54:57]
	v_mfma_f32_16x16x32_bf16 v[46:49], v[154:157], v[224:227], v[46:49]
	v_mfma_f32_16x16x32_bf16 v[34:37], v[192:195], v[224:227], v[34:37]
	v_mfma_f32_16x16x32_bf16 v[26:29], v[154:157], v[232:235], v[26:29]
	v_mfma_f32_16x16x32_bf16 v[18:21], v[192:195], v[232:235], v[18:21]
	v_mfma_f32_16x16x32_bf16 v[14:17], v[154:157], v[240:243], v[14:17]
	v_mfma_f32_16x16x32_bf16 v[2:5], v[192:195], v[240:243], v[2:5]
	s_barrier
	s_add_i32 s65, s65, 2
	s_add_u32 s16, s16, 0x100
	s_addc_u32 s17, s17, 0
	s_add_u32 vcc_lo, vcc_lo, 0x100
	s_addc_u32 vcc_hi, vcc_hi, 0
	s_cmp_gt_u32 s65, 61
	s_cbranch_scc1 .Lpeel_exit_3
.LBB0_710:
	s_add_u32 s22, vcc_lo, 0xfff00080
	s_addc_u32 s23, vcc_hi, -1
	s_add_i32 s68, 0, 0x10000
	s_cmp_eq_u32 s65, 60
	s_cselect_b32 s25, s30, s23
	s_cselect_b32 s24, s31, s22
	s_cselect_b32 s23, s61, s17
	s_cselect_b32 s22, s63, s16
	s_add_i32 s70, 0, 0x14000
	v_add_u32_e32 v70, s68, v220
	v_add_u32_e32 v170, s70, v220
	ds_read_b128 v[50:53], v70
	ds_read_b128 v[54:57], v70 offset:1024
	ds_read_b128 v[66:69], v70 offset:2048
	ds_read_b128 v[70:73], v70 offset:3072
	ds_read_b128 v[74:77], v170
	ds_read_b128 v[86:89], v170 offset:1024
	ds_read_b128 v[154:157], v170 offset:2048
	ds_read_b128 v[188:191], v170 offset:3072
	v_lshl_add_u64 v[170:171], vcc, 0, v[186:187]
	s_add_i32 m0, s10, 0xc000
	ds_read_b128 v[192:195], v222
	ds_read_b128 v[196:199], v222 offset:1024
	ds_read_b128 v[200:203], v222 offset:2048
	ds_read_b128 v[204:207], v222 offset:3072
	ds_read_b128 v[224:227], v222 offset:4096
	ds_read_b128 v[228:231], v222 offset:5120
	ds_read_b128 v[232:235], v222 offset:6144
	ds_read_b128 v[236:239], v222 offset:7168
	global_load_lds_dwordx4 v[170:171], off
	v_lshl_add_u64 v[170:171], vcc, 0, v[184:185]
	s_add_i32 m0, s10, 0xe000
	s_nop 0
	global_load_lds_dwordx4 v[170:171], off
	s_waitcnt vmcnt(8)
	s_waitcnt lgkmcnt(0)
	s_barrier
; #define PG8_STAGE(bufoff, gbase, voff) do { _Pragma("unroll") for (int _i = 0; _i < 2; ++_i) \
;         __builtin_amdgcn_global_load_lds((const unsigned*)((const char*)(gbase) + (voff)[_i]), (PG8_LAS unsigned*)(lds + (bufoff) + ldsw + _i * 8192), 16, 0, 0); } while (0)
; #define PG8_LDA(dst, b, h) do { _Pragma("unroll") for (int m = 0; m < 4; ++m) _Pragma("unroll") for (int k = 0; k < 2; ++k) dst[m][k] = *(const PG8_LAS bf16x8*)(lds + PG8_SA(b, h) + aoff + m * 2048 + k * 1024); } while (0)
; #define PG8_MMA(ai, bj, At, Bt) do { __builtin_amdgcn_s_setprio(1); _Pragma("unroll") for (int m = 0; m < 4; ++m) _Pragma("unroll") for (int n = 0; n < 2; ++n) _Pragma("unroll") for (int k = 0; k < 2; ++k) \
;         acc[ai][bj][m][n] = __builtin_amdgcn_mfma_f32_16x16x32_bf16(Bt[n][k], At[m][k], acc[ai][bj][m][n], 0, 0, 0); __builtin_amdgcn_s_setprio(0); } while (0)
; #define PG8_WAIT_V(n) asm volatile("s_waitcnt vmcnt(" #n ")" ::: "memory")
; #define PG8_WAIT_L(n) asm volatile("s_waitcnt lgkmcnt(" #n ")" ::: "memory")
; #define PG8_BAR __builtin_amdgcn_s_barrier()
; #define PG8_SCHED __builtin_amdgcn_sched_barrier(0)
; template <class Epi, class Sched, bool ALIGN_EPI = false, bool SP2 = false>
; __device__ __forceinline__ void gemm_phase(PG8_LAS unsigned char* lds, const Gemm g, const Sched& S, const Epi& E) {
;     ...
;             PG8_WAIT_V(8); PG8_WAIT_L(0); PG8_BAR; PG8_MMA(0, 0, At, B0); PG8_MMA(0, 1, At, B1); PG8_BAR; PG8_SCHED;
;             PG8_LDA(At, 0, 1); PG8_STAGE(PG8_SB(0, 0), b2, voffB); PG8_STAGE(PG8_SB(0, 1), b2 + hstep, voffB); PG8_STAGE(PG8_SA(0, 0), a2, voffA);
;             PG8_WAIT_V(8); PG8_WAIT_L(0); PG8_BAR; PG8_MMA(1, 0, At, B0); PG8_MMA(1, 1, At, B1); PG8_BAR; PG8_SCHED;
	v_mfma_f32_16x16x32_bf16 v[142:145], v[50:53], v[192:195], v[142:145]
	v_mfma_f32_16x16x32_bf16 v[130:133], v[66:69], v[192:195], v[130:133]
	v_mfma_f32_16x16x32_bf16 v[138:141], v[50:53], v[200:203], v[138:141]
	v_mfma_f32_16x16x32_bf16 v[126:129], v[66:69], v[200:203], v[126:129]
	v_mfma_f32_16x16x32_bf16 v[118:121], v[50:53], v[224:227], v[118:121]
	v_mfma_f32_16x16x32_bf16 v[110:113], v[66:69], v[224:227], v[110:113]
	v_mfma_f32_16x16x32_bf16 v[98:101], v[50:53], v[232:235], v[98:101]
	v_mfma_f32_16x16x32_bf16 v[94:97], v[66:69], v[232:235], v[94:97]
	v_mfma_f32_16x16x32_bf16 v[142:145], v[54:57], v[196:199], v[142:145]
	v_mfma_f32_16x16x32_bf16 v[130:133], v[70:73], v[196:199], v[130:133]
	v_mfma_f32_16x16x32_bf16 v[138:141], v[54:57], v[204:207], v[138:141]
	v_mfma_f32_16x16x32_bf16 v[126:129], v[70:73], v[204:207], v[126:129]
	v_mfma_f32_16x16x32_bf16 v[118:121], v[54:57], v[228:231], v[118:121]
	v_mfma_f32_16x16x32_bf16 v[110:113], v[70:73], v[228:231], v[110:113]
	v_mfma_f32_16x16x32_bf16 v[98:101], v[54:57], v[236:239], v[98:101]
	v_mfma_f32_16x16x32_bf16 v[94:97], v[70:73], v[236:239], v[94:97]
	v_mfma_f32_16x16x32_bf16 v[150:153], v[74:77], v[192:195], v[150:153]
	v_mfma_f32_16x16x32_bf16 v[146:149], v[154:157], v[192:195], v[146:149]
	v_mfma_f32_16x16x32_bf16 v[134:137], v[74:77], v[200:203], v[134:137]
	v_mfma_f32_16x16x32_bf16 v[122:125], v[154:157], v[200:203], v[122:125]
	v_mfma_f32_16x16x32_bf16 v[114:117], v[74:77], v[224:227], v[114:117]
	v_mfma_f32_16x16x32_bf16 v[106:109], v[154:157], v[224:227], v[106:109]
	v_mfma_f32_16x16x32_bf16 v[102:105], v[74:77], v[232:235], v[102:105]
	v_mfma_f32_16x16x32_bf16 v[90:93], v[154:157], v[232:235], v[90:93]
	v_mfma_f32_16x16x32_bf16 v[150:153], v[86:89], v[196:199], v[150:153]
	v_mfma_f32_16x16x32_bf16 v[146:149], v[188:191], v[196:199], v[146:149]
	v_mfma_f32_16x16x32_bf16 v[134:137], v[86:89], v[204:207], v[134:137]
	v_mfma_f32_16x16x32_bf16 v[122:125], v[188:191], v[204:207], v[122:125]
	v_mfma_f32_16x16x32_bf16 v[114:117], v[86:89], v[228:231], v[114:117]
	v_mfma_f32_16x16x32_bf16 v[106:109], v[188:191], v[228:231], v[106:109]
	v_mfma_f32_16x16x32_bf16 v[102:105], v[86:89], v[236:239], v[102:105]
	v_mfma_f32_16x16x32_bf16 v[90:93], v[188:191], v[236:239], v[90:93]
	s_barrier
	s_add_i32 s68, s68, s9
	v_lshl_add_u64 v[170:171], s[22:23], 0, v[158:159]
	s_mov_b32 m0, s68
	ds_read_b128 v[192:195], v222 offset:16384
	ds_read_b128 v[196:199], v222 offset:17408
	ds_read_b128 v[200:203], v222 offset:18432
	ds_read_b128 v[204:207], v222 offset:19456
	ds_read_b128 v[224:227], v222 offset:20480
	ds_read_b128 v[228:231], v222 offset:21504
	ds_read_b128 v[232:235], v222 offset:22528
	ds_read_b128 v[236:239], v222 offset:23552
	global_load_lds_dwordx4 v[170:171], off
	s_add_i32 m0, s68, 0x2000
	s_add_u32 s68, s22, 0x100000
	v_lshl_add_u64 v[208:209], s[22:23], 0, v[172:173]
	s_addc_u32 s69, s23, 0
	s_add_i32 s70, s70, s9
	global_load_lds_dwordx4 v[208:209], off
	v_lshl_add_u64 v[210:211], s[68:69], 0, v[158:159]
	s_mov_b32 m0, s70
	v_lshl_add_u64 v[244:245], s[24:25], 0, v[174:175]
	global_load_lds_dwordx4 v[210:211], off
	v_lshl_add_u64 v[210:211], s[68:69], 0, v[172:173]
	s_add_i32 m0, s70, 0x2000
	s_nop 0
	global_load_lds_dwordx4 v[210:211], off
	v_lshl_add_u64 v[210:211], s[24:25], 0, v[176:177]
	s_mov_b32 m0, s10
	s_nop 0
	global_load_lds_dwordx4 v[210:211], off
	s_mov_b32 m0, s11
	s_nop 0
	global_load_lds_dwordx4 v[244:245], off
	s_waitcnt vmcnt(8)
	s_waitcnt lgkmcnt(0)
	s_barrier
	v_mfma_f32_16x16x32_bf16 v[62:65], v[50:53], v[192:195], v[62:65]
	v_mfma_f32_16x16x32_bf16 v[42:45], v[66:69], v[192:195], v[42:45]
	v_mfma_f32_16x16x32_bf16 v[58:61], v[50:53], v[200:203], v[58:61]
	v_mfma_f32_16x16x32_bf16 v[38:41], v[66:69], v[200:203], v[38:41]
	v_mfma_f32_16x16x32_bf16 v[30:33], v[50:53], v[224:227], v[30:33]
	v_mfma_f32_16x16x32_bf16 v[22:25], v[66:69], v[224:227], v[22:25]
	v_mfma_f32_16x16x32_bf16 v[10:13], v[50:53], v[232:235], v[10:13]
	v_mfma_f32_16x16x32_bf16 v[6:9], v[66:69], v[232:235], v[6:9]
	v_mfma_f32_16x16x32_bf16 v[62:65], v[54:57], v[196:199], v[62:65]
	v_mfma_f32_16x16x32_bf16 v[42:45], v[70:73], v[196:199], v[42:45]
	v_mfma_f32_16x16x32_bf16 v[58:61], v[54:57], v[204:207], v[58:61]
	v_mfma_f32_16x16x32_bf16 v[38:41], v[70:73], v[204:207], v[38:41]
	v_mfma_f32_16x16x32_bf16 v[30:33], v[54:57], v[228:231], v[30:33]
	v_mfma_f32_16x16x32_bf16 v[22:25], v[70:73], v[228:231], v[22:25]
	v_mfma_f32_16x16x32_bf16 v[10:13], v[54:57], v[236:239], v[10:13]
	v_mfma_f32_16x16x32_bf16 v[6:9], v[70:73], v[236:239], v[6:9]
	v_mfma_f32_16x16x32_bf16 v[46:49], v[74:77], v[200:203], v[46:49]
	v_mfma_f32_16x16x32_bf16 v[34:37], v[154:157], v[200:203], v[34:37]
	v_mfma_f32_16x16x32_bf16 v[26:29], v[74:77], v[224:227], v[26:29]
	v_mfma_f32_16x16x32_bf16 v[18:21], v[154:157], v[224:227], v[18:21]
	v_mfma_f32_16x16x32_bf16 v[14:17], v[74:77], v[232:235], v[14:17]
	v_mfma_f32_16x16x32_bf16 v[2:5], v[154:157], v[232:235], v[2:5]
	v_mfma_f32_16x16x32_bf16 v[50:53], v[74:77], v[192:195], v[82:85]
	v_mfma_f32_16x16x32_bf16 v[54:57], v[154:157], v[192:195], v[78:81]
	v_mfma_f32_16x16x32_bf16 v[46:49], v[86:89], v[204:207], v[46:49]
	v_mfma_f32_16x16x32_bf16 v[34:37], v[188:191], v[204:207], v[34:37]
	v_mfma_f32_16x16x32_bf16 v[26:29], v[86:89], v[228:231], v[26:29]
	v_mfma_f32_16x16x32_bf16 v[18:21], v[188:191], v[228:231], v[18:21]
	v_mfma_f32_16x16x32_bf16 v[14:17], v[86:89], v[236:239], v[14:17]
	v_mfma_f32_16x16x32_bf16 v[2:5], v[188:191], v[236:239], v[2:5]
	v_mfma_f32_16x16x32_bf16 v[50:53], v[86:89], v[196:199], v[50:53]
	v_mfma_f32_16x16x32_bf16 v[54:57], v[188:191], v[196:199], v[54:57]
	s_barrier
; #define PG8_STAGE(bufoff, gbase, voff) do { _Pragma("unroll") for (int _i = 0; _i < 2; ++_i) \
;         __builtin_amdgcn_global_load_lds((const unsigned*)((const char*)(gbase) + (voff)[_i]), (PG8_LAS unsigned*)(lds + (bufoff) + ldsw + _i * 8192), 16, 0, 0); } while (0)
; #define PG8_LDA(dst, b, h) do { _Pragma("unroll") for (int m = 0; m < 4; ++m) _Pragma("unroll") for (int k = 0; k < 2; ++k) dst[m][k] = *(const PG8_LAS bf16x8*)(lds + PG8_SA(b, h) + aoff + m * 2048 + k * 1024); } while (0)
; #define PG8_LDB(dst, b, h) do { _Pragma("unroll") for (int n = 0; n < 2; ++n) _Pragma("unroll") for (int k = 0; k < 2; ++k) dst[n][k] = *(const PG8_LAS bf16x8*)(lds + PG8_SB(b, h) + boff + n * 2048 + k * 1024); } while (0)
; #define PG8_MMA(ai, bj, At, Bt) do { __builtin_amdgcn_s_setprio(1); _Pragma("unroll") for (int m = 0; m < 4; ++m) _Pragma("unroll") for (int n = 0; n < 2; ++n) _Pragma("unroll") for (int k = 0; k < 2; ++k) \
;         acc[ai][bj][m][n] = __builtin_amdgcn_mfma_f32_16x16x32_bf16(Bt[n][k], At[m][k], acc[ai][bj][m][n], 0, 0, 0); __builtin_amdgcn_s_setprio(0); } while (0)
; #define PG8_WAIT_V(n) asm volatile("s_waitcnt vmcnt(" #n ")" ::: "memory")
; #define PG8_WAIT_L(n) asm volatile("s_waitcnt lgkmcnt(" #n ")" ::: "memory")
; #define PG8_BAR __builtin_amdgcn_s_barrier()
; #define PG8_SCHED __builtin_amdgcn_sched_barrier(0)
; template <class Epi, class Sched, bool ALIGN_EPI = false, bool SP2 = false>
; __device__ __forceinline__ void gemm_phase(PG8_LAS unsigned char* lds, const Gemm g, const Sched& S, const Epi& E) {
;     ...
;             PG8_LDB(B0, 1, 0); PG8_LDB(B1, 1, 1); PG8_SCHED; PG8_LDA(At, 1, 0); PG8_STAGE(PG8_SA(0, 1), a2 + hstep, voffA);
;             PG8_WAIT_V(8); PG8_WAIT_L(0); PG8_BAR; PG8_MMA(0, 0, At, B0); PG8_MMA(0, 1, At, B1); PG8_BAR; PG8_SCHED;
;             PG8_LDA(At, 1, 1); PG8_STAGE(PG8_SB(1, 0), b3, voffB); PG8_STAGE(PG8_SB(1, 1), b3 + hstep, voffB); PG8_STAGE(PG8_SA(1, 0), a3, voffA);
;             PG8_WAIT_V(8); PG8_WAIT_L(0); PG8_BAR; PG8_MMA(1, 0, At, B0); PG8_MMA(1, 1, At, B1); PG8_BAR; PG8_SCHED;
	s_add_i32 s68, 0, 0x18000
	s_add_i32 s69, 0, 0x1c000
	v_add_u32_e32 v78, s68, v220
	v_add_u32_e32 v82, s69, v220
	ds_read_b128 v[66:69], v78
	ds_read_b128 v[70:73], v78 offset:1024
	ds_read_b128 v[74:77], v78 offset:2048
	ds_read_b128 v[78:81], v78 offset:3072
	ds_read_b128 v[86:89], v82
	ds_read_b128 v[154:157], v82 offset:1024
	ds_read_b128 v[188:191], v82 offset:2048
	ds_read_b128 v[192:195], v82 offset:3072
	s_add_u32 s24, s24, 0x100000
	s_addc_u32 s25, s25, 0
	s_mov_b32 m0, s12
	v_lshl_add_u64 v[240:241], s[24:25], 0, v[176:177]
	ds_read_b128 v[82:85], v222 offset:32768
	ds_read_b128 v[196:199], v222 offset:33792
	ds_read_b128 v[200:203], v222 offset:34816
	ds_read_b128 v[204:207], v222 offset:35840
	ds_read_b128 v[224:227], v222 offset:36864
	ds_read_b128 v[228:231], v222 offset:37888
	ds_read_b128 v[232:235], v222 offset:38912
	ds_read_b128 v[236:239], v222 offset:39936
	global_load_lds_dwordx4 v[240:241], off
	v_lshl_add_u64 v[240:241], s[24:25], 0, v[174:175]
	s_mov_b32 m0, s13
	s_nop 0
	global_load_lds_dwordx4 v[240:241], off
	s_waitcnt vmcnt(8)
	s_waitcnt lgkmcnt(0)
	s_barrier
	v_mfma_f32_16x16x32_bf16 v[142:145], v[66:69], v[82:85], v[142:145]
	v_mfma_f32_16x16x32_bf16 v[130:133], v[74:77], v[82:85], v[130:133]
	v_mfma_f32_16x16x32_bf16 v[138:141], v[66:69], v[200:203], v[138:141]
	v_mfma_f32_16x16x32_bf16 v[126:129], v[74:77], v[200:203], v[126:129]
	v_mfma_f32_16x16x32_bf16 v[118:121], v[66:69], v[224:227], v[118:121]
	v_mfma_f32_16x16x32_bf16 v[110:113], v[74:77], v[224:227], v[110:113]
	v_mfma_f32_16x16x32_bf16 v[98:101], v[66:69], v[232:235], v[98:101]
	v_mfma_f32_16x16x32_bf16 v[94:97], v[74:77], v[232:235], v[94:97]
	v_mfma_f32_16x16x32_bf16 v[142:145], v[70:73], v[196:199], v[142:145]
	v_mfma_f32_16x16x32_bf16 v[130:133], v[78:81], v[196:199], v[130:133]
	v_mfma_f32_16x16x32_bf16 v[138:141], v[70:73], v[204:207], v[138:141]
	v_mfma_f32_16x16x32_bf16 v[126:129], v[78:81], v[204:207], v[126:129]
	v_mfma_f32_16x16x32_bf16 v[118:121], v[70:73], v[228:231], v[118:121]
	v_mfma_f32_16x16x32_bf16 v[110:113], v[78:81], v[228:231], v[110:113]
	v_mfma_f32_16x16x32_bf16 v[98:101], v[70:73], v[236:239], v[98:101]
	v_mfma_f32_16x16x32_bf16 v[94:97], v[78:81], v[236:239], v[94:97]
	v_mfma_f32_16x16x32_bf16 v[150:153], v[86:89], v[82:85], v[150:153]
	v_mfma_f32_16x16x32_bf16 v[146:149], v[188:191], v[82:85], v[146:149]
	v_mfma_f32_16x16x32_bf16 v[134:137], v[86:89], v[200:203], v[134:137]
	v_mfma_f32_16x16x32_bf16 v[122:125], v[188:191], v[200:203], v[122:125]
	v_mfma_f32_16x16x32_bf16 v[114:117], v[86:89], v[224:227], v[114:117]
	v_mfma_f32_16x16x32_bf16 v[106:109], v[188:191], v[224:227], v[106:109]
	v_mfma_f32_16x16x32_bf16 v[102:105], v[86:89], v[232:235], v[102:105]
	v_mfma_f32_16x16x32_bf16 v[90:93], v[188:191], v[232:235], v[90:93]
	v_mfma_f32_16x16x32_bf16 v[150:153], v[154:157], v[196:199], v[150:153]
	v_mfma_f32_16x16x32_bf16 v[146:149], v[192:195], v[196:199], v[146:149]
	v_mfma_f32_16x16x32_bf16 v[134:137], v[154:157], v[204:207], v[134:137]
	v_mfma_f32_16x16x32_bf16 v[122:125], v[192:195], v[204:207], v[122:125]
	v_mfma_f32_16x16x32_bf16 v[114:117], v[154:157], v[228:231], v[114:117]
	v_mfma_f32_16x16x32_bf16 v[106:109], v[192:195], v[228:231], v[106:109]
	v_mfma_f32_16x16x32_bf16 v[102:105], v[154:157], v[236:239], v[102:105]
	v_mfma_f32_16x16x32_bf16 v[90:93], v[192:195], v[236:239], v[90:93]
	s_barrier
	s_add_i32 s24, s68, s9
	s_nop 2
	v_lshl_add_u64 v[82:83], v[170:171], 0, s[96:97]
	s_mov_b32 m0, s24
	ds_read_b128 v[196:199], v222 offset:49152
	ds_read_b128 v[200:203], v222 offset:50176
	ds_read_b128 v[204:207], v222 offset:51200
	ds_read_b128 v[224:227], v222 offset:52224
	ds_read_b128 v[228:231], v222 offset:53248
	ds_read_b128 v[232:235], v222 offset:54272
	ds_read_b128 v[236:239], v222 offset:55296
	ds_read_b128 v[240:243], v222 offset:56320
	global_load_lds_dwordx4 v[82:83], off
	s_add_i32 m0, s24, 0x2000
	s_add_u32 s22, s22, 0x100080
	v_lshl_add_u64 v[82:83], v[208:209], 0, s[96:97]
	s_addc_u32 s23, s23, 0
	s_add_i32 s24, s69, s9
	global_load_lds_dwordx4 v[82:83], off
	v_lshl_add_u64 v[82:83], s[22:23], 0, v[158:159]
	s_mov_b32 m0, s24
	s_nop 0
	global_load_lds_dwordx4 v[82:83], off
	v_lshl_add_u64 v[82:83], s[22:23], 0, v[172:173]
	s_add_i32 m0, s24, 0x2000
	s_nop 0
	global_load_lds_dwordx4 v[82:83], off
	v_lshl_add_u64 v[82:83], v[210:211], 0, s[96:97]
	s_mov_b32 m0, s0
	s_nop 0
	global_load_lds_dwordx4 v[82:83], off
	v_lshl_add_u64 v[82:83], v[244:245], 0, s[96:97]
	s_mov_b32 m0, s34
	s_nop 0
	global_load_lds_dwordx4 v[82:83], off
	s_waitcnt vmcnt(8)
	s_waitcnt lgkmcnt(0)
	s_barrier
	v_mfma_f32_16x16x32_bf16 v[62:65], v[66:69], v[196:199], v[62:65]
	v_mfma_f32_16x16x32_bf16 v[42:45], v[74:77], v[196:199], v[42:45]
	v_mfma_f32_16x16x32_bf16 v[58:61], v[66:69], v[204:207], v[58:61]
	v_mfma_f32_16x16x32_bf16 v[38:41], v[74:77], v[204:207], v[38:41]
	v_mfma_f32_16x16x32_bf16 v[30:33], v[66:69], v[228:231], v[30:33]
	v_mfma_f32_16x16x32_bf16 v[22:25], v[74:77], v[228:231], v[22:25]
	v_mfma_f32_16x16x32_bf16 v[10:13], v[66:69], v[236:239], v[10:13]
	v_mfma_f32_16x16x32_bf16 v[6:9], v[74:77], v[236:239], v[6:9]
	v_mfma_f32_16x16x32_bf16 v[62:65], v[70:73], v[200:203], v[62:65]
	v_mfma_f32_16x16x32_bf16 v[42:45], v[78:81], v[200:203], v[42:45]
	v_mfma_f32_16x16x32_bf16 v[58:61], v[70:73], v[224:227], v[58:61]
	v_mfma_f32_16x16x32_bf16 v[38:41], v[78:81], v[224:227], v[38:41]
	v_mfma_f32_16x16x32_bf16 v[30:33], v[70:73], v[232:235], v[30:33]
	v_mfma_f32_16x16x32_bf16 v[22:25], v[78:81], v[232:235], v[22:25]
	v_mfma_f32_16x16x32_bf16 v[10:13], v[70:73], v[240:243], v[10:13]
	v_mfma_f32_16x16x32_bf16 v[6:9], v[78:81], v[240:243], v[6:9]
	v_mfma_f32_16x16x32_bf16 v[50:53], v[86:89], v[196:199], v[50:53]
	v_mfma_f32_16x16x32_bf16 v[54:57], v[188:191], v[196:199], v[54:57]
	v_mfma_f32_16x16x32_bf16 v[46:49], v[86:89], v[204:207], v[46:49]
	v_mfma_f32_16x16x32_bf16 v[34:37], v[188:191], v[204:207], v[34:37]
	v_mfma_f32_16x16x32_bf16 v[26:29], v[86:89], v[228:231], v[26:29]
	v_mfma_f32_16x16x32_bf16 v[18:21], v[188:191], v[228:231], v[18:21]
	v_mfma_f32_16x16x32_bf16 v[14:17], v[86:89], v[236:239], v[14:17]
	v_mfma_f32_16x16x32_bf16 v[2:5], v[188:191], v[236:239], v[2:5]
	v_mfma_f32_16x16x32_bf16 v[82:85], v[154:157], v[200:203], v[50:53]
	v_mfma_f32_16x16x32_bf16 v[78:81], v[192:195], v[200:203], v[54:57]
	v_mfma_f32_16x16x32_bf16 v[46:49], v[154:157], v[224:227], v[46:49]
	v_mfma_f32_16x16x32_bf16 v[34:37], v[192:195], v[224:227], v[34:37]
	v_mfma_f32_16x16x32_bf16 v[26:29], v[154:157], v[232:235], v[26:29]
	v_mfma_f32_16x16x32_bf16 v[18:21], v[192:195], v[232:235], v[18:21]
	v_mfma_f32_16x16x32_bf16 v[14:17], v[154:157], v[240:243], v[14:17]
	v_mfma_f32_16x16x32_bf16 v[2:5], v[192:195], v[240:243], v[2:5]
	s_barrier
	s_add_i32 s65, s65, 2
	s_add_u32 s16, s16, 0x100
	s_addc_u32 s17, s17, 0
	s_add_u32 vcc_lo, vcc_lo, 0x100
	s_addc_u32 vcc_hi, vcc_hi, 0
	s_cmp_gt_u32 s65, 61
	s_cbranch_scc0 .LBB0_710

; #define PG8_STAGE(bufoff, gbase, voff) do { _Pragma("unroll") for (int _i = 0; _i < 2; ++_i) \
;         __builtin_amdgcn_global_load_lds((const unsigned*)((const char*)(gbase) + (voff)[_i]), (PG8_LAS unsigned*)(lds + (bufoff) + ldsw + _i * 8192), 16, 0, 0); } while (0)
; #define PG8_LDA(dst, b, h) do { _Pragma("unroll") for (int m = 0; m < 4; ++m) _Pragma("unroll") for (int k = 0; k < 2; ++k) dst[m][k] = *(const PG8_LAS bf16x8*)(lds + PG8_SA(b, h) + aoff + m * 2048 + k * 1024); } while (0)
; #define PG8_LDB(dst, b, h) do { _Pragma("unroll") for (int n = 0; n < 2; ++n) _Pragma("unroll") for (int k = 0; k < 2; ++k) dst[n][k] = *(const PG8_LAS bf16x8*)(lds + PG8_SB(b, h) + boff + n * 2048 + k * 1024); } while (0)
; #define PG8_MMA(ai, bj, At, Bt) do { __builtin_amdgcn_s_setprio(1); _Pragma("unroll") for (int m = 0; m < 4; ++m) _Pragma("unroll") for (int n = 0; n < 2; ++n) _Pragma("unroll") for (int k = 0; k < 2; ++k) \
;         acc[ai][bj][m][n] = __builtin_amdgcn_mfma_f32_16x16x32_bf16(Bt[n][k], At[m][k], acc[ai][bj][m][n], 0, 0, 0); __builtin_amdgcn_s_setprio(0); } while (0)
; #define PG8_WAIT_V(n) asm volatile("s_waitcnt vmcnt(" #n ")" ::: "memory")
; template <class Epi, class Sched, bool ALIGN_EPI = false, bool SP2 = false>
; __device__ __forceinline__ void gemm_phase(PG8_LAS unsigned char* lds, const Gemm g, const Sched& S, const Epi& E) {
;     ...
;         const int nt = cur.nt;
;         for (int t = 0; t < nt; t += 2) {
;             const bool last = (t == nt - 2);
;             const char* a1 = cA + (size_t)(t + 1) * kstep;
;             const char* a2 = last ? nA : cA + (size_t)(t + 2) * kstep; const char* b2 = last ? nB : cB + (size_t)(t + 2) * kstep;
;             const char* a3 = a2 + kstep; const char* b3 = b2 + kstep;
;             if (last && has_next) S.a_ready(nxt);
;             if constexpr (SP2) {
;             PG8_LDB(B0, 0, 0); PG8_LDB(B1, 0, 1); PG8_SCHED; PG8_LDA(At, 0, 0); PG8_STAGE(PG8_SA(1, 1), a1 + hstep, voffA);
;             PG8_WAIT_V(8); PG8_WAIT_L(0); PG8_BAR; PG8_MMA(0, 0, At, B0); PG8_MMA(0, 1, At, B1); PG8_BAR; PG8_SCHED;
;             PG8_LDA(At, 0, 1); PG8_STAGE(PG8_SB(0, 0), b2, voffB); PG8_STAGE(PG8_SB(0, 1), b2 + hstep, voffB); PG8_STAGE(PG8_SA(0, 0), a2, voffA);
;             PG8_WAIT_V(8); PG8_WAIT_L(0); PG8_BAR; PG8_MMA(1, 0, At, B0); PG8_MMA(1, 1, At, B1); PG8_BAR; PG8_SCHED;
.LBB0_914:
	s_add_i32 s15, s14, -2
	s_add_u32 s16, s50, 0x100
	s_addc_u32 s17, s51, 0
	s_mov_b32 s28, 0
	s_waitcnt vmcnt(0)
	s_waitcnt vmcnt(0)
	s_add_i32 s30, s28, 2
	s_add_u32 s26, s48, 0x100
	s_addc_u32 s27, s49, 0
	s_add_i32 s43, 0, 0x10000
	s_cmp_eq_u32 s15, s28
	s_cselect_b32 s51, s45, s27
	s_cselect_b32 s50, s44, s26
	s_cselect_b32 s29, s47, s17
	s_cselect_b32 s28, s46, s16
	s_add_i32 s59, 0, 0x14000
	v_add_u32_e32 v142, s43, v188
	v_add_u32_e32 v170, s59, v188
	ds_read_b128 v[130:133], v142
	ds_read_b128 v[134:137], v142 offset:1024
	ds_read_b128 v[138:141], v142 offset:2048
	ds_read_b128 v[142:145], v142 offset:3072
	ds_read_b128 v[146:149], v170
	ds_read_b128 v[150:153], v170 offset:1024
	ds_read_b128 v[178:181], v170 offset:2048
	ds_read_b128 v[182:185], v170 offset:3072
	v_lshl_add_u64 v[170:171], s[48:49], 0, v[176:177]
	s_add_i32 m0, s9, 0xc000
	ds_read_b128 v[192:195], v190
	ds_read_b128 v[196:199], v190 offset:1024
	ds_read_b128 v[200:203], v190 offset:2048
	ds_read_b128 v[204:207], v190 offset:3072
	ds_read_b128 v[220:223], v190 offset:4096
	ds_read_b128 v[224:227], v190 offset:5120
	ds_read_b128 v[228:231], v190 offset:6144
	ds_read_b128 v[232:235], v190 offset:7168
	global_load_lds_dwordx4 v[170:171], off
	v_lshl_add_u64 v[170:171], s[48:49], 0, v[174:175]
	s_add_i32 m0, s9, 0xe000
	s_nop 0
	global_load_lds_dwordx4 v[170:171], off
	s_waitcnt vmcnt(8)
	s_waitcnt lgkmcnt(0)
	s_barrier
	v_mfma_f32_16x16x32_bf16 v[126:129], v[130:133], v[192:195], 0
	v_mfma_f32_16x16x32_bf16 v[122:125], v[138:141], v[192:195], 0
	v_mfma_f32_16x16x32_bf16 v[118:121], v[130:133], v[200:203], 0
	v_mfma_f32_16x16x32_bf16 v[114:117], v[138:141], v[200:203], 0
	v_mfma_f32_16x16x32_bf16 v[102:105], v[130:133], v[220:223], 0
	v_mfma_f32_16x16x32_bf16 v[94:97], v[138:141], v[220:223], 0
	v_mfma_f32_16x16x32_bf16 v[86:89], v[130:133], v[228:231], 0
	v_mfma_f32_16x16x32_bf16 v[78:81], v[138:141], v[228:231], 0
	v_mfma_f32_16x16x32_bf16 v[126:129], v[134:137], v[196:199], v[126:129]
	v_mfma_f32_16x16x32_bf16 v[122:125], v[142:145], v[196:199], v[122:125]
	v_mfma_f32_16x16x32_bf16 v[118:121], v[134:137], v[204:207], v[118:121]
	v_mfma_f32_16x16x32_bf16 v[114:117], v[142:145], v[204:207], v[114:117]
	v_mfma_f32_16x16x32_bf16 v[102:105], v[134:137], v[224:227], v[102:105]
	v_mfma_f32_16x16x32_bf16 v[94:97], v[142:145], v[224:227], v[94:97]
	v_mfma_f32_16x16x32_bf16 v[86:89], v[134:137], v[232:235], v[86:89]
	v_mfma_f32_16x16x32_bf16 v[78:81], v[142:145], v[232:235], v[78:81]
	v_mfma_f32_16x16x32_bf16 v[110:113], v[146:149], v[192:195], 0
	v_mfma_f32_16x16x32_bf16 v[106:109], v[178:181], v[192:195], 0
	v_mfma_f32_16x16x32_bf16 v[98:101], v[146:149], v[200:203], 0
	v_mfma_f32_16x16x32_bf16 v[90:93], v[178:181], v[200:203], 0
	v_mfma_f32_16x16x32_bf16 v[82:85], v[146:149], v[220:223], 0
	v_mfma_f32_16x16x32_bf16 v[74:77], v[178:181], v[220:223], 0
	v_mfma_f32_16x16x32_bf16 v[70:73], v[146:149], v[228:231], 0
	v_mfma_f32_16x16x32_bf16 v[66:69], v[178:181], v[228:231], 0
	v_mfma_f32_16x16x32_bf16 v[110:113], v[150:153], v[196:199], v[110:113]
	v_mfma_f32_16x16x32_bf16 v[106:109], v[182:185], v[196:199], v[106:109]
	v_mfma_f32_16x16x32_bf16 v[98:101], v[150:153], v[204:207], v[98:101]
	v_mfma_f32_16x16x32_bf16 v[90:93], v[182:185], v[204:207], v[90:93]
	v_mfma_f32_16x16x32_bf16 v[82:85], v[150:153], v[224:227], v[82:85]
	v_mfma_f32_16x16x32_bf16 v[74:77], v[182:185], v[224:227], v[74:77]
	v_mfma_f32_16x16x32_bf16 v[70:73], v[150:153], v[232:235], v[70:73]
	v_mfma_f32_16x16x32_bf16 v[66:69], v[182:185], v[232:235], v[66:69]
	s_barrier
	s_add_i32 s43, s43, s8
	v_lshl_add_u64 v[170:171], s[28:29], 0, v[158:159]
	s_mov_b32 m0, s43
	ds_read_b128 v[192:195], v190 offset:16384
	ds_read_b128 v[196:199], v190 offset:17408
	ds_read_b128 v[200:203], v190 offset:18432
	ds_read_b128 v[204:207], v190 offset:19456
	ds_read_b128 v[220:223], v190 offset:20480
	ds_read_b128 v[224:227], v190 offset:21504
	ds_read_b128 v[228:231], v190 offset:22528
	ds_read_b128 v[232:235], v190 offset:23552
	global_load_lds_dwordx4 v[170:171], off
	s_add_i32 m0, s43, 0x2000
	s_add_u32 s48, s28, 0x2b0000
	v_lshl_add_u64 v[186:187], s[28:29], 0, v[172:173]
	s_addc_u32 s49, s29, 0
	s_add_i32 s43, s59, s8
	global_load_lds_dwordx4 v[186:187], off
	v_lshl_add_u64 v[208:209], s[48:49], 0, v[158:159]
	s_mov_b32 m0, s43
	v_lshl_add_u64 v[210:211], s[50:51], 0, v[156:157]
	global_load_lds_dwordx4 v[208:209], off
	v_lshl_add_u64 v[208:209], s[48:49], 0, v[172:173]
	s_add_i32 m0, s43, 0x2000
	s_nop 0
	global_load_lds_dwordx4 v[208:209], off
	v_lshl_add_u64 v[208:209], s[50:51], 0, v[154:155]
	s_mov_b32 m0, s9
	s_nop 0
	global_load_lds_dwordx4 v[208:209], off
	s_mov_b32 m0, s10
	s_nop 0
	global_load_lds_dwordx4 v[210:211], off
	s_waitcnt vmcnt(8)
	s_waitcnt lgkmcnt(0)
	s_barrier
; #define PG8_STAGE(bufoff, gbase, voff) do { _Pragma("unroll") for (int _i = 0; _i < 2; ++_i) \
;         __builtin_amdgcn_global_load_lds((const unsigned*)((const char*)(gbase) + (voff)[_i]), (PG8_LAS unsigned*)(lds + (bufoff) + ldsw + _i * 8192), 16, 0, 0); } while (0)
; #define PG8_LDA(dst, b, h) do { _Pragma("unroll") for (int m = 0; m < 4; ++m) _Pragma("unroll") for (int k = 0; k < 2; ++k) dst[m][k] = *(const PG8_LAS bf16x8*)(lds + PG8_SA(b, h) + aoff + m * 2048 + k * 1024); } while (0)
; #define PG8_LDB(dst, b, h) do { _Pragma("unroll") for (int n = 0; n < 2; ++n) _Pragma("unroll") for (int k = 0; k < 2; ++k) dst[n][k] = *(const PG8_LAS bf16x8*)(lds + PG8_SB(b, h) + boff + n * 2048 + k * 1024); } while (0)
; #define PG8_MMA(ai, bj, At, Bt) do { __builtin_amdgcn_s_setprio(1); _Pragma("unroll") for (int m = 0; m < 4; ++m) _Pragma("unroll") for (int n = 0; n < 2; ++n) _Pragma("unroll") for (int k = 0; k < 2; ++k) \
;         acc[ai][bj][m][n] = __builtin_amdgcn_mfma_f32_16x16x32_bf16(Bt[n][k], At[m][k], acc[ai][bj][m][n], 0, 0, 0); __builtin_amdgcn_s_setprio(0); } while (0)
; #define PG8_WAIT_V(n) asm volatile("s_waitcnt vmcnt(" #n ")" ::: "memory")
; #define PG8_WAIT_L(n) asm volatile("s_waitcnt lgkmcnt(" #n ")" ::: "memory")
; #define PG8_BAR __builtin_amdgcn_s_barrier()
; #define PG8_SCHED __builtin_amdgcn_sched_barrier(0)
; template <class Epi, class Sched, bool ALIGN_EPI = false, bool SP2 = false>
; __device__ __forceinline__ void gemm_phase(PG8_LAS unsigned char* lds, const Gemm g, const Sched& S, const Epi& E) {
;     ...
;             PG8_WAIT_V(8); PG8_WAIT_L(0); PG8_BAR; PG8_MMA(1, 0, At, B0); PG8_MMA(1, 1, At, B1); PG8_BAR; PG8_SCHED;
;             PG8_LDB(B0, 1, 0); PG8_LDB(B1, 1, 1); PG8_SCHED; PG8_LDA(At, 1, 0); PG8_STAGE(PG8_SA(0, 1), a2 + hstep, voffA);
;             PG8_WAIT_V(8); PG8_WAIT_L(0); PG8_BAR; PG8_MMA(0, 0, At, B0); PG8_MMA(0, 1, At, B1); PG8_BAR; PG8_SCHED;
	v_mfma_f32_16x16x32_bf16 v[62:65], v[130:133], v[192:195], 0
	v_mfma_f32_16x16x32_bf16 v[58:61], v[138:141], v[192:195], 0
	v_mfma_f32_16x16x32_bf16 v[54:57], v[130:133], v[200:203], 0
	v_mfma_f32_16x16x32_bf16 v[46:49], v[138:141], v[200:203], 0
	v_mfma_f32_16x16x32_bf16 v[38:41], v[130:133], v[220:223], 0
	v_mfma_f32_16x16x32_bf16 v[30:33], v[138:141], v[220:223], 0
	v_mfma_f32_16x16x32_bf16 v[22:25], v[130:133], v[228:231], 0
	v_mfma_f32_16x16x32_bf16 v[14:17], v[138:141], v[228:231], 0
	v_mfma_f32_16x16x32_bf16 v[62:65], v[134:137], v[196:199], v[62:65]
	v_mfma_f32_16x16x32_bf16 v[58:61], v[142:145], v[196:199], v[58:61]
	v_mfma_f32_16x16x32_bf16 v[54:57], v[134:137], v[204:207], v[54:57]
	v_mfma_f32_16x16x32_bf16 v[46:49], v[142:145], v[204:207], v[46:49]
	v_mfma_f32_16x16x32_bf16 v[38:41], v[134:137], v[224:227], v[38:41]
	v_mfma_f32_16x16x32_bf16 v[30:33], v[142:145], v[224:227], v[30:33]
	v_mfma_f32_16x16x32_bf16 v[22:25], v[134:137], v[232:235], v[22:25]
	v_mfma_f32_16x16x32_bf16 v[14:17], v[142:145], v[232:235], v[14:17]
	v_mfma_f32_16x16x32_bf16 v[50:53], v[146:149], v[192:195], 0
	v_mfma_f32_16x16x32_bf16 v[42:45], v[178:181], v[192:195], 0
	v_mfma_f32_16x16x32_bf16 v[34:37], v[146:149], v[200:203], 0
	v_mfma_f32_16x16x32_bf16 v[26:29], v[178:181], v[200:203], 0
	v_mfma_f32_16x16x32_bf16 v[18:21], v[146:149], v[220:223], 0
	v_mfma_f32_16x16x32_bf16 v[10:13], v[178:181], v[220:223], 0
	v_mfma_f32_16x16x32_bf16 v[6:9], v[146:149], v[228:231], 0
	v_mfma_f32_16x16x32_bf16 v[2:5], v[178:181], v[228:231], 0
	v_mfma_f32_16x16x32_bf16 v[50:53], v[150:153], v[196:199], v[50:53]
	v_mfma_f32_16x16x32_bf16 v[42:45], v[182:185], v[196:199], v[42:45]
	v_mfma_f32_16x16x32_bf16 v[34:37], v[150:153], v[204:207], v[34:37]
	v_mfma_f32_16x16x32_bf16 v[26:29], v[182:185], v[204:207], v[26:29]
	v_mfma_f32_16x16x32_bf16 v[18:21], v[150:153], v[224:227], v[18:21]
	v_mfma_f32_16x16x32_bf16 v[10:13], v[182:185], v[224:227], v[10:13]
	v_mfma_f32_16x16x32_bf16 v[6:9], v[150:153], v[232:235], v[6:9]
	v_mfma_f32_16x16x32_bf16 v[2:5], v[182:185], v[232:235], v[2:5]
	s_barrier
	s_add_i32 s43, 0, 0x18000
	s_add_i32 s59, 0, 0x1c000
	v_add_u32_e32 v142, s43, v188
	v_add_u32_e32 v182, s59, v188
	ds_read_b128 v[130:133], v142
	ds_read_b128 v[134:137], v142 offset:1024
	ds_read_b128 v[138:141], v142 offset:2048
	ds_read_b128 v[142:145], v142 offset:3072
	ds_read_b128 v[146:149], v182
	ds_read_b128 v[150:153], v182 offset:1024
	ds_read_b128 v[178:181], v182 offset:2048
	ds_read_b128 v[182:185], v182 offset:3072
	s_add_u32 s48, s50, 0x2b0000
	s_addc_u32 s49, s51, 0
	s_mov_b32 m0, s11
	v_lshl_add_u64 v[236:237], s[48:49], 0, v[154:155]
	ds_read_b128 v[192:195], v190 offset:32768
	ds_read_b128 v[196:199], v190 offset:33792
	ds_read_b128 v[200:203], v190 offset:34816
	ds_read_b128 v[204:207], v190 offset:35840
	ds_read_b128 v[220:223], v190 offset:36864
	ds_read_b128 v[224:227], v190 offset:37888
	ds_read_b128 v[228:231], v190 offset:38912
	ds_read_b128 v[232:235], v190 offset:39936
	global_load_lds_dwordx4 v[236:237], off
	v_lshl_add_u64 v[236:237], s[48:49], 0, v[156:157]
	s_mov_b32 m0, s12
	s_nop 0
	global_load_lds_dwordx4 v[236:237], off
	s_waitcnt vmcnt(8)
	s_waitcnt lgkmcnt(0)
	s_barrier
	v_mfma_f32_16x16x32_bf16 v[126:129], v[130:133], v[192:195], v[126:129]
	v_mfma_f32_16x16x32_bf16 v[122:125], v[138:141], v[192:195], v[122:125]
	v_mfma_f32_16x16x32_bf16 v[118:121], v[130:133], v[200:203], v[118:121]
	v_mfma_f32_16x16x32_bf16 v[114:117], v[138:141], v[200:203], v[114:117]
	v_mfma_f32_16x16x32_bf16 v[102:105], v[130:133], v[220:223], v[102:105]
	v_mfma_f32_16x16x32_bf16 v[94:97], v[138:141], v[220:223], v[94:97]
	v_mfma_f32_16x16x32_bf16 v[86:89], v[130:133], v[228:231], v[86:89]
	v_mfma_f32_16x16x32_bf16 v[78:81], v[138:141], v[228:231], v[78:81]
	v_mfma_f32_16x16x32_bf16 v[126:129], v[134:137], v[196:199], v[126:129]
	v_mfma_f32_16x16x32_bf16 v[122:125], v[142:145], v[196:199], v[122:125]
	v_mfma_f32_16x16x32_bf16 v[118:121], v[134:137], v[204:207], v[118:121]
	v_mfma_f32_16x16x32_bf16 v[114:117], v[142:145], v[204:207], v[114:117]
	v_mfma_f32_16x16x32_bf16 v[102:105], v[134:137], v[224:227], v[102:105]
	v_mfma_f32_16x16x32_bf16 v[94:97], v[142:145], v[224:227], v[94:97]
	v_mfma_f32_16x16x32_bf16 v[86:89], v[134:137], v[232:235], v[86:89]
	v_mfma_f32_16x16x32_bf16 v[78:81], v[142:145], v[232:235], v[78:81]
	v_mfma_f32_16x16x32_bf16 v[110:113], v[146:149], v[192:195], v[110:113]
	v_mfma_f32_16x16x32_bf16 v[106:109], v[178:181], v[192:195], v[106:109]
	v_mfma_f32_16x16x32_bf16 v[98:101], v[146:149], v[200:203], v[98:101]
	v_mfma_f32_16x16x32_bf16 v[90:93], v[178:181], v[200:203], v[90:93]
	v_mfma_f32_16x16x32_bf16 v[82:85], v[146:149], v[220:223], v[82:85]
	v_mfma_f32_16x16x32_bf16 v[74:77], v[178:181], v[220:223], v[74:77]
	v_mfma_f32_16x16x32_bf16 v[70:73], v[146:149], v[228:231], v[70:73]
	v_mfma_f32_16x16x32_bf16 v[66:69], v[178:181], v[228:231], v[66:69]
	v_mfma_f32_16x16x32_bf16 v[110:113], v[150:153], v[196:199], v[110:113]
	v_mfma_f32_16x16x32_bf16 v[106:109], v[182:185], v[196:199], v[106:109]
	v_mfma_f32_16x16x32_bf16 v[98:101], v[150:153], v[204:207], v[98:101]
	v_mfma_f32_16x16x32_bf16 v[90:93], v[182:185], v[204:207], v[90:93]
	v_mfma_f32_16x16x32_bf16 v[82:85], v[150:153], v[224:227], v[82:85]
	v_mfma_f32_16x16x32_bf16 v[74:77], v[182:185], v[224:227], v[74:77]
	v_mfma_f32_16x16x32_bf16 v[70:73], v[150:153], v[232:235], v[70:73]
	v_mfma_f32_16x16x32_bf16 v[66:69], v[182:185], v[232:235], v[66:69]
	s_barrier
; #define PG8_STAGE(bufoff, gbase, voff) do { _Pragma("unroll") for (int _i = 0; _i < 2; ++_i) \
;         __builtin_amdgcn_global_load_lds((const unsigned*)((const char*)(gbase) + (voff)[_i]), (PG8_LAS unsigned*)(lds + (bufoff) + ldsw + _i * 8192), 16, 0, 0); } while (0)
; #define PG8_LDA(dst, b, h) do { _Pragma("unroll") for (int m = 0; m < 4; ++m) _Pragma("unroll") for (int k = 0; k < 2; ++k) dst[m][k] = *(const PG8_LAS bf16x8*)(lds + PG8_SA(b, h) + aoff + m * 2048 + k * 1024); } while (0)
; #define PG8_LDB(dst, b, h) do { _Pragma("unroll") for (int n = 0; n < 2; ++n) _Pragma("unroll") for (int k = 0; k < 2; ++k) dst[n][k] = *(const PG8_LAS bf16x8*)(lds + PG8_SB(b, h) + boff + n * 2048 + k * 1024); } while (0)
; template <class Epi, class Sched, bool ALIGN_EPI = false, bool SP2 = false>
; __device__ __forceinline__ void gemm_phase(PG8_LAS unsigned char* lds, const Gemm g, const Sched& S, const Epi& E) {
;     ...
;         for (int t = 0; t < nt; t += 2) {
;             const bool last = (t == nt - 2);
;             const char* a1 = cA + (size_t)(t + 1) * kstep;
;             const char* a2 = last ? nA : cA + (size_t)(t + 2) * kstep; const char* b2 = last ? nB : cB + (size_t)(t + 2) * kstep;
;             const char* a3 = a2 + kstep; const char* b3 = b2 + kstep;
;             if (last && has_next) S.a_ready(nxt);
;             if constexpr (SP2) {
;             PG8_LDB(B0, 0, 0); PG8_LDB(B1, 0, 1); PG8_SCHED; PG8_LDA(At, 0, 0); PG8_STAGE(PG8_SA(1, 1), a1 + hstep, voffA);
;             PG8_WAIT_V(8); PG8_WAIT_L(0); PG8_BAR; PG8_MMA(0, 0, At, B0); PG8_MMA(0, 1, At, B1); PG8_BAR; PG8_SCHED;
;             PG8_LDA(At, 0, 1); PG8_STAGE(PG8_SB(0, 0), b2, voffB); PG8_STAGE(PG8_SB(0, 1), b2 + hstep, voffB); PG8_STAGE(PG8_SA(0, 0), a2, voffA);
;             PG8_WAIT_V(8); PG8_WAIT_L(0); PG8_BAR; PG8_MMA(1, 0, At, B0); PG8_MMA(1, 1, At, B1); PG8_BAR; PG8_SCHED;
;             PG8_LDB(B0, 1, 0); PG8_LDB(B1, 1, 1); PG8_SCHED; PG8_LDA(At, 1, 0); PG8_STAGE(PG8_SA(0, 1), a2 + hstep, voffA);
;             PG8_WAIT_V(8); PG8_WAIT_L(0); PG8_BAR; PG8_MMA(0, 0, At, B0); PG8_MMA(0, 1, At, B1); PG8_BAR; PG8_SCHED;
;             PG8_LDA(At, 1, 1); PG8_STAGE(PG8_SB(1, 0), b3, voffB); PG8_STAGE(PG8_SB(1, 1), b3 + hstep, voffB); PG8_STAGE(PG8_SA(1, 0), a3, voffA);
;             PG8_WAIT_V(8); PG8_WAIT_L(0); PG8_BAR; PG8_MMA(1, 0, At, B0); PG8_MMA(1, 1, At, B1); PG8_BAR; PG8_SCHED;
	s_add_i32 s43, s43, s8
	v_lshl_add_u64 v[170:171], v[170:171], 0, s[96:97]
	s_mov_b32 m0, s43
	ds_read_b128 v[192:195], v190 offset:49152
	ds_read_b128 v[196:199], v190 offset:50176
	ds_read_b128 v[200:203], v190 offset:51200
	ds_read_b128 v[204:207], v190 offset:52224
	ds_read_b128 v[220:223], v190 offset:53248
	ds_read_b128 v[224:227], v190 offset:54272
	ds_read_b128 v[228:231], v190 offset:55296
	ds_read_b128 v[232:235], v190 offset:56320
	global_load_lds_dwordx4 v[170:171], off
	s_add_i32 m0, s43, 0x2000
	s_add_u32 s28, s28, 0x2b0080
	v_lshl_add_u64 v[170:171], v[186:187], 0, s[96:97]
	s_addc_u32 s29, s29, 0
	s_add_i32 s43, s59, s8
	global_load_lds_dwordx4 v[170:171], off
	v_lshl_add_u64 v[170:171], s[28:29], 0, v[158:159]
	s_mov_b32 m0, s43
	s_nop 0
	global_load_lds_dwordx4 v[170:171], off
	v_lshl_add_u64 v[170:171], s[28:29], 0, v[172:173]
	s_add_i32 m0, s43, 0x2000
	s_nop 0
	global_load_lds_dwordx4 v[170:171], off
	v_lshl_add_u64 v[170:171], v[208:209], 0, s[96:97]
	s_mov_b32 m0, s35
	s_nop 0
	global_load_lds_dwordx4 v[170:171], off
	v_lshl_add_u64 v[170:171], v[210:211], 0, s[96:97]
	s_mov_b32 m0, s52
	s_nop 0
	global_load_lds_dwordx4 v[170:171], off
	s_waitcnt vmcnt(8)
	s_waitcnt lgkmcnt(0)
	s_barrier
	v_mfma_f32_16x16x32_bf16 v[62:65], v[130:133], v[192:195], v[62:65]
	v_mfma_f32_16x16x32_bf16 v[58:61], v[138:141], v[192:195], v[58:61]
	v_mfma_f32_16x16x32_bf16 v[54:57], v[130:133], v[200:203], v[54:57]
	v_mfma_f32_16x16x32_bf16 v[46:49], v[138:141], v[200:203], v[46:49]
	v_mfma_f32_16x16x32_bf16 v[38:41], v[130:133], v[220:223], v[38:41]
	v_mfma_f32_16x16x32_bf16 v[30:33], v[138:141], v[220:223], v[30:33]
	v_mfma_f32_16x16x32_bf16 v[22:25], v[130:133], v[228:231], v[22:25]
	v_mfma_f32_16x16x32_bf16 v[14:17], v[138:141], v[228:231], v[14:17]
	v_mfma_f32_16x16x32_bf16 v[62:65], v[134:137], v[196:199], v[62:65]
	v_mfma_f32_16x16x32_bf16 v[58:61], v[142:145], v[196:199], v[58:61]
	v_mfma_f32_16x16x32_bf16 v[54:57], v[134:137], v[204:207], v[54:57]
	v_mfma_f32_16x16x32_bf16 v[46:49], v[142:145], v[204:207], v[46:49]
	v_mfma_f32_16x16x32_bf16 v[38:41], v[134:137], v[224:227], v[38:41]
	v_mfma_f32_16x16x32_bf16 v[30:33], v[142:145], v[224:227], v[30:33]
	v_mfma_f32_16x16x32_bf16 v[22:25], v[134:137], v[232:235], v[22:25]
	v_mfma_f32_16x16x32_bf16 v[14:17], v[142:145], v[232:235], v[14:17]
	v_mfma_f32_16x16x32_bf16 v[50:53], v[146:149], v[192:195], v[50:53]
	v_mfma_f32_16x16x32_bf16 v[42:45], v[178:181], v[192:195], v[42:45]
	v_mfma_f32_16x16x32_bf16 v[34:37], v[146:149], v[200:203], v[34:37]
	v_mfma_f32_16x16x32_bf16 v[26:29], v[178:181], v[200:203], v[26:29]
	v_mfma_f32_16x16x32_bf16 v[18:21], v[146:149], v[220:223], v[18:21]
	v_mfma_f32_16x16x32_bf16 v[10:13], v[178:181], v[220:223], v[10:13]
	v_mfma_f32_16x16x32_bf16 v[6:9], v[146:149], v[228:231], v[6:9]
	v_mfma_f32_16x16x32_bf16 v[2:5], v[178:181], v[228:231], v[2:5]
	v_mfma_f32_16x16x32_bf16 v[50:53], v[150:153], v[196:199], v[50:53]
	v_mfma_f32_16x16x32_bf16 v[42:45], v[182:185], v[196:199], v[42:45]
	v_mfma_f32_16x16x32_bf16 v[34:37], v[150:153], v[204:207], v[34:37]
	v_mfma_f32_16x16x32_bf16 v[26:29], v[182:185], v[204:207], v[26:29]
	v_mfma_f32_16x16x32_bf16 v[18:21], v[150:153], v[224:227], v[18:21]
	v_mfma_f32_16x16x32_bf16 v[10:13], v[182:185], v[224:227], v[10:13]
	v_mfma_f32_16x16x32_bf16 v[6:9], v[150:153], v[232:235], v[6:9]
	v_mfma_f32_16x16x32_bf16 v[2:5], v[182:185], v[232:235], v[2:5]
	s_barrier
	s_add_u32 s16, s16, 0x100
	s_addc_u32 s17, s17, 0
	s_cmp_ge_i32 s30, s14
	s_mov_b64 s[48:49], s[26:27]
	s_mov_b32 s28, s30
	s_cbranch_scc1 .Lpeel_exit_4
.LBB0_915:
	s_add_i32 s30, s28, 2
	s_add_u32 s26, s48, 0x100
	s_addc_u32 s27, s49, 0
	s_add_i32 s43, 0, 0x10000
	s_cmp_eq_u32 s15, s28
	s_cselect_b32 s51, s45, s27
	s_cselect_b32 s50, s44, s26
	s_cselect_b32 s29, s47, s17
	s_cselect_b32 s28, s46, s16
	s_add_i32 s59, 0, 0x14000
	v_add_u32_e32 v142, s43, v188
	v_add_u32_e32 v170, s59, v188
	ds_read_b128 v[130:133], v142
	ds_read_b128 v[134:137], v142 offset:1024
	ds_read_b128 v[138:141], v142 offset:2048
	ds_read_b128 v[142:145], v142 offset:3072
	ds_read_b128 v[146:149], v170
	ds_read_b128 v[150:153], v170 offset:1024
	ds_read_b128 v[178:181], v170 offset:2048
	ds_read_b128 v[182:185], v170 offset:3072
	v_lshl_add_u64 v[170:171], s[48:49], 0, v[176:177]
	s_add_i32 m0, s9, 0xc000
	ds_read_b128 v[192:195], v190
	ds_read_b128 v[196:199], v190 offset:1024
	ds_read_b128 v[200:203], v190 offset:2048
	ds_read_b128 v[204:207], v190 offset:3072
	ds_read_b128 v[220:223], v190 offset:4096
	ds_read_b128 v[224:227], v190 offset:5120
	ds_read_b128 v[228:231], v190 offset:6144
	ds_read_b128 v[232:235], v190 offset:7168
	global_load_lds_dwordx4 v[170:171], off
	v_lshl_add_u64 v[170:171], s[48:49], 0, v[174:175]
	s_add_i32 m0, s9, 0xe000
	s_nop 0
	global_load_lds_dwordx4 v[170:171], off
	s_waitcnt vmcnt(8)
	s_waitcnt lgkmcnt(0)
	s_barrier
; #define PG8_STAGE(bufoff, gbase, voff) do { _Pragma("unroll") for (int _i = 0; _i < 2; ++_i) \
;         __builtin_amdgcn_global_load_lds((const unsigned*)((const char*)(gbase) + (voff)[_i]), (PG8_LAS unsigned*)(lds + (bufoff) + ldsw + _i * 8192), 16, 0, 0); } while (0)
; #define PG8_LDA(dst, b, h) do { _Pragma("unroll") for (int m = 0; m < 4; ++m) _Pragma("unroll") for (int k = 0; k < 2; ++k) dst[m][k] = *(const PG8_LAS bf16x8*)(lds + PG8_SA(b, h) + aoff + m * 2048 + k * 1024); } while (0)
; #define PG8_MMA(ai, bj, At, Bt) do { __builtin_amdgcn_s_setprio(1); _Pragma("unroll") for (int m = 0; m < 4; ++m) _Pragma("unroll") for (int n = 0; n < 2; ++n) _Pragma("unroll") for (int k = 0; k < 2; ++k) \
;         acc[ai][bj][m][n] = __builtin_amdgcn_mfma_f32_16x16x32_bf16(Bt[n][k], At[m][k], acc[ai][bj][m][n], 0, 0, 0); __builtin_amdgcn_s_setprio(0); } while (0)
; #define PG8_WAIT_V(n) asm volatile("s_waitcnt vmcnt(" #n ")" ::: "memory")
; #define PG8_WAIT_L(n) asm volatile("s_waitcnt lgkmcnt(" #n ")" ::: "memory")
; #define PG8_BAR __builtin_amdgcn_s_barrier()
; #define PG8_SCHED __builtin_amdgcn_sched_barrier(0)
; template <class Epi, class Sched, bool ALIGN_EPI = false, bool SP2 = false>
; __device__ __forceinline__ void gemm_phase(PG8_LAS unsigned char* lds, const Gemm g, const Sched& S, const Epi& E) {
;     ...
;             PG8_WAIT_V(8); PG8_WAIT_L(0); PG8_BAR; PG8_MMA(0, 0, At, B0); PG8_MMA(0, 1, At, B1); PG8_BAR; PG8_SCHED;
;             PG8_LDA(At, 0, 1); PG8_STAGE(PG8_SB(0, 0), b2, voffB); PG8_STAGE(PG8_SB(0, 1), b2 + hstep, voffB); PG8_STAGE(PG8_SA(0, 0), a2, voffA);
;             PG8_WAIT_V(8); PG8_WAIT_L(0); PG8_BAR; PG8_MMA(1, 0, At, B0); PG8_MMA(1, 1, At, B1); PG8_BAR; PG8_SCHED;
	v_mfma_f32_16x16x32_bf16 v[126:129], v[130:133], v[192:195], v[126:129]
	v_mfma_f32_16x16x32_bf16 v[122:125], v[138:141], v[192:195], v[122:125]
	v_mfma_f32_16x16x32_bf16 v[118:121], v[130:133], v[200:203], v[118:121]
	v_mfma_f32_16x16x32_bf16 v[114:117], v[138:141], v[200:203], v[114:117]
	v_mfma_f32_16x16x32_bf16 v[102:105], v[130:133], v[220:223], v[102:105]
	v_mfma_f32_16x16x32_bf16 v[94:97], v[138:141], v[220:223], v[94:97]
	v_mfma_f32_16x16x32_bf16 v[86:89], v[130:133], v[228:231], v[86:89]
	v_mfma_f32_16x16x32_bf16 v[78:81], v[138:141], v[228:231], v[78:81]
	v_mfma_f32_16x16x32_bf16 v[126:129], v[134:137], v[196:199], v[126:129]
	v_mfma_f32_16x16x32_bf16 v[122:125], v[142:145], v[196:199], v[122:125]
	v_mfma_f32_16x16x32_bf16 v[118:121], v[134:137], v[204:207], v[118:121]
	v_mfma_f32_16x16x32_bf16 v[114:117], v[142:145], v[204:207], v[114:117]
	v_mfma_f32_16x16x32_bf16 v[102:105], v[134:137], v[224:227], v[102:105]
	v_mfma_f32_16x16x32_bf16 v[94:97], v[142:145], v[224:227], v[94:97]
	v_mfma_f32_16x16x32_bf16 v[86:89], v[134:137], v[232:235], v[86:89]
	v_mfma_f32_16x16x32_bf16 v[78:81], v[142:145], v[232:235], v[78:81]
	v_mfma_f32_16x16x32_bf16 v[110:113], v[146:149], v[192:195], v[110:113]
	v_mfma_f32_16x16x32_bf16 v[106:109], v[178:181], v[192:195], v[106:109]
	v_mfma_f32_16x16x32_bf16 v[98:101], v[146:149], v[200:203], v[98:101]
	v_mfma_f32_16x16x32_bf16 v[90:93], v[178:181], v[200:203], v[90:93]
	v_mfma_f32_16x16x32_bf16 v[82:85], v[146:149], v[220:223], v[82:85]
	v_mfma_f32_16x16x32_bf16 v[74:77], v[178:181], v[220:223], v[74:77]
	v_mfma_f32_16x16x32_bf16 v[70:73], v[146:149], v[228:231], v[70:73]
	v_mfma_f32_16x16x32_bf16 v[66:69], v[178:181], v[228:231], v[66:69]
	v_mfma_f32_16x16x32_bf16 v[110:113], v[150:153], v[196:199], v[110:113]
	v_mfma_f32_16x16x32_bf16 v[106:109], v[182:185], v[196:199], v[106:109]
	v_mfma_f32_16x16x32_bf16 v[98:101], v[150:153], v[204:207], v[98:101]
	v_mfma_f32_16x16x32_bf16 v[90:93], v[182:185], v[204:207], v[90:93]
	v_mfma_f32_16x16x32_bf16 v[82:85], v[150:153], v[224:227], v[82:85]
	v_mfma_f32_16x16x32_bf16 v[74:77], v[182:185], v[224:227], v[74:77]
	v_mfma_f32_16x16x32_bf16 v[70:73], v[150:153], v[232:235], v[70:73]
	v_mfma_f32_16x16x32_bf16 v[66:69], v[182:185], v[232:235], v[66:69]
	s_barrier
	s_add_i32 s43, s43, s8
	v_lshl_add_u64 v[170:171], s[28:29], 0, v[158:159]
	s_mov_b32 m0, s43
	ds_read_b128 v[192:195], v190 offset:16384
	ds_read_b128 v[196:199], v190 offset:17408
	ds_read_b128 v[200:203], v190 offset:18432
	ds_read_b128 v[204:207], v190 offset:19456
	ds_read_b128 v[220:223], v190 offset:20480
	ds_read_b128 v[224:227], v190 offset:21504
	ds_read_b128 v[228:231], v190 offset:22528
	ds_read_b128 v[232:235], v190 offset:23552
	global_load_lds_dwordx4 v[170:171], off
	s_add_i32 m0, s43, 0x2000
	s_add_u32 s48, s28, 0x2b0000
	v_lshl_add_u64 v[186:187], s[28:29], 0, v[172:173]
	s_addc_u32 s49, s29, 0
	s_add_i32 s43, s59, s8
	global_load_lds_dwordx4 v[186:187], off
	v_lshl_add_u64 v[208:209], s[48:49], 0, v[158:159]
	s_mov_b32 m0, s43
	v_lshl_add_u64 v[210:211], s[50:51], 0, v[156:157]
	global_load_lds_dwordx4 v[208:209], off
	v_lshl_add_u64 v[208:209], s[48:49], 0, v[172:173]
	s_add_i32 m0, s43, 0x2000
	s_nop 0
	global_load_lds_dwordx4 v[208:209], off
	v_lshl_add_u64 v[208:209], s[50:51], 0, v[154:155]
	s_mov_b32 m0, s9
	s_nop 0
	global_load_lds_dwordx4 v[208:209], off
	s_mov_b32 m0, s10
	s_nop 0
	global_load_lds_dwordx4 v[210:211], off
	s_waitcnt vmcnt(8)
	s_waitcnt lgkmcnt(0)
	s_barrier
	v_mfma_f32_16x16x32_bf16 v[62:65], v[130:133], v[192:195], v[62:65]
	v_mfma_f32_16x16x32_bf16 v[58:61], v[138:141], v[192:195], v[58:61]
	v_mfma_f32_16x16x32_bf16 v[54:57], v[130:133], v[200:203], v[54:57]
	v_mfma_f32_16x16x32_bf16 v[46:49], v[138:141], v[200:203], v[46:49]
	v_mfma_f32_16x16x32_bf16 v[38:41], v[130:133], v[220:223], v[38:41]
	v_mfma_f32_16x16x32_bf16 v[30:33], v[138:141], v[220:223], v[30:33]
	v_mfma_f32_16x16x32_bf16 v[22:25], v[130:133], v[228:231], v[22:25]
	v_mfma_f32_16x16x32_bf16 v[14:17], v[138:141], v[228:231], v[14:17]
	v_mfma_f32_16x16x32_bf16 v[62:65], v[134:137], v[196:199], v[62:65]
	v_mfma_f32_16x16x32_bf16 v[58:61], v[142:145], v[196:199], v[58:61]
	v_mfma_f32_16x16x32_bf16 v[54:57], v[134:137], v[204:207], v[54:57]
	v_mfma_f32_16x16x32_bf16 v[46:49], v[142:145], v[204:207], v[46:49]
	v_mfma_f32_16x16x32_bf16 v[38:41], v[134:137], v[224:227], v[38:41]
	v_mfma_f32_16x16x32_bf16 v[30:33], v[142:145], v[224:227], v[30:33]
	v_mfma_f32_16x16x32_bf16 v[22:25], v[134:137], v[232:235], v[22:25]
	v_mfma_f32_16x16x32_bf16 v[14:17], v[142:145], v[232:235], v[14:17]
	v_mfma_f32_16x16x32_bf16 v[50:53], v[146:149], v[192:195], v[50:53]
	v_mfma_f32_16x16x32_bf16 v[42:45], v[178:181], v[192:195], v[42:45]
	v_mfma_f32_16x16x32_bf16 v[34:37], v[146:149], v[200:203], v[34:37]
	v_mfma_f32_16x16x32_bf16 v[26:29], v[178:181], v[200:203], v[26:29]
	v_mfma_f32_16x16x32_bf16 v[18:21], v[146:149], v[220:223], v[18:21]
	v_mfma_f32_16x16x32_bf16 v[10:13], v[178:181], v[220:223], v[10:13]
	v_mfma_f32_16x16x32_bf16 v[6:9], v[146:149], v[228:231], v[6:9]
	v_mfma_f32_16x16x32_bf16 v[2:5], v[178:181], v[228:231], v[2:5]
	v_mfma_f32_16x16x32_bf16 v[50:53], v[150:153], v[196:199], v[50:53]
	v_mfma_f32_16x16x32_bf16 v[42:45], v[182:185], v[196:199], v[42:45]
	v_mfma_f32_16x16x32_bf16 v[34:37], v[150:153], v[204:207], v[34:37]
	v_mfma_f32_16x16x32_bf16 v[26:29], v[182:185], v[204:207], v[26:29]
	v_mfma_f32_16x16x32_bf16 v[18:21], v[150:153], v[224:227], v[18:21]
	v_mfma_f32_16x16x32_bf16 v[10:13], v[182:185], v[224:227], v[10:13]
	v_mfma_f32_16x16x32_bf16 v[6:9], v[150:153], v[232:235], v[6:9]
	v_mfma_f32_16x16x32_bf16 v[2:5], v[182:185], v[232:235], v[2:5]
	s_barrier
; #define PG8_STAGE(bufoff, gbase, voff) do { _Pragma("unroll") for (int _i = 0; _i < 2; ++_i) \
;         __builtin_amdgcn_global_load_lds((const unsigned*)((const char*)(gbase) + (voff)[_i]), (PG8_LAS unsigned*)(lds + (bufoff) + ldsw + _i * 8192), 16, 0, 0); } while (0)
; #define PG8_LDA(dst, b, h) do { _Pragma("unroll") for (int m = 0; m < 4; ++m) _Pragma("unroll") for (int k = 0; k < 2; ++k) dst[m][k] = *(const PG8_LAS bf16x8*)(lds + PG8_SA(b, h) + aoff + m * 2048 + k * 1024); } while (0)
; #define PG8_LDB(dst, b, h) do { _Pragma("unroll") for (int n = 0; n < 2; ++n) _Pragma("unroll") for (int k = 0; k < 2; ++k) dst[n][k] = *(const PG8_LAS bf16x8*)(lds + PG8_SB(b, h) + boff + n * 2048 + k * 1024); } while (0)
; #define PG8_MMA(ai, bj, At, Bt) do { __builtin_amdgcn_s_setprio(1); _Pragma("unroll") for (int m = 0; m < 4; ++m) _Pragma("unroll") for (int n = 0; n < 2; ++n) _Pragma("unroll") for (int k = 0; k < 2; ++k) \
;         acc[ai][bj][m][n] = __builtin_amdgcn_mfma_f32_16x16x32_bf16(Bt[n][k], At[m][k], acc[ai][bj][m][n], 0, 0, 0); __builtin_amdgcn_s_setprio(0); } while (0)
; #define PG8_WAIT_V(n) asm volatile("s_waitcnt vmcnt(" #n ")" ::: "memory")
; #define PG8_WAIT_L(n) asm volatile("s_waitcnt lgkmcnt(" #n ")" ::: "memory")
; #define PG8_BAR __builtin_amdgcn_s_barrier()
; #define PG8_SCHED __builtin_amdgcn_sched_barrier(0)
; template <class Epi, class Sched, bool ALIGN_EPI = false, bool SP2 = false>
; __device__ __forceinline__ void gemm_phase(PG8_LAS unsigned char* lds, const Gemm g, const Sched& S, const Epi& E) {
;     ...
;             PG8_LDB(B0, 1, 0); PG8_LDB(B1, 1, 1); PG8_SCHED; PG8_LDA(At, 1, 0); PG8_STAGE(PG8_SA(0, 1), a2 + hstep, voffA);
;             PG8_WAIT_V(8); PG8_WAIT_L(0); PG8_BAR; PG8_MMA(0, 0, At, B0); PG8_MMA(0, 1, At, B1); PG8_BAR; PG8_SCHED;
;             PG8_LDA(At, 1, 1); PG8_STAGE(PG8_SB(1, 0), b3, voffB); PG8_STAGE(PG8_SB(1, 1), b3 + hstep, voffB); PG8_STAGE(PG8_SA(1, 0), a3, voffA);
;             PG8_WAIT_V(8); PG8_WAIT_L(0); PG8_BAR; PG8_MMA(1, 0, At, B0); PG8_MMA(1, 1, At, B1); PG8_BAR; PG8_SCHED;
	s_add_i32 s43, 0, 0x18000
	s_add_i32 s59, 0, 0x1c000
	v_add_u32_e32 v142, s43, v188
	v_add_u32_e32 v182, s59, v188
	ds_read_b128 v[130:133], v142
	ds_read_b128 v[134:137], v142 offset:1024
	ds_read_b128 v[138:141], v142 offset:2048
	ds_read_b128 v[142:145], v142 offset:3072
	ds_read_b128 v[146:149], v182
	ds_read_b128 v[150:153], v182 offset:1024
	ds_read_b128 v[178:181], v182 offset:2048
	ds_read_b128 v[182:185], v182 offset:3072
	s_add_u32 s48, s50, 0x2b0000
	s_addc_u32 s49, s51, 0
	s_mov_b32 m0, s11
	v_lshl_add_u64 v[236:237], s[48:49], 0, v[154:155]
	ds_read_b128 v[192:195], v190 offset:32768
	ds_read_b128 v[196:199], v190 offset:33792
	ds_read_b128 v[200:203], v190 offset:34816
	ds_read_b128 v[204:207], v190 offset:35840
	ds_read_b128 v[220:223], v190 offset:36864
	ds_read_b128 v[224:227], v190 offset:37888
	ds_read_b128 v[228:231], v190 offset:38912
	ds_read_b128 v[232:235], v190 offset:39936
	global_load_lds_dwordx4 v[236:237], off
	v_lshl_add_u64 v[236:237], s[48:49], 0, v[156:157]
	s_mov_b32 m0, s12
	s_nop 0
	global_load_lds_dwordx4 v[236:237], off
	s_waitcnt vmcnt(8)
	s_waitcnt lgkmcnt(0)
	s_barrier
	v_mfma_f32_16x16x32_bf16 v[126:129], v[130:133], v[192:195], v[126:129]
	v_mfma_f32_16x16x32_bf16 v[122:125], v[138:141], v[192:195], v[122:125]
	v_mfma_f32_16x16x32_bf16 v[118:121], v[130:133], v[200:203], v[118:121]
	v_mfma_f32_16x16x32_bf16 v[114:117], v[138:141], v[200:203], v[114:117]
	v_mfma_f32_16x16x32_bf16 v[102:105], v[130:133], v[220:223], v[102:105]
	v_mfma_f32_16x16x32_bf16 v[94:97], v[138:141], v[220:223], v[94:97]
	v_mfma_f32_16x16x32_bf16 v[86:89], v[130:133], v[228:231], v[86:89]
	v_mfma_f32_16x16x32_bf16 v[78:81], v[138:141], v[228:231], v[78:81]
	v_mfma_f32_16x16x32_bf16 v[126:129], v[134:137], v[196:199], v[126:129]
	v_mfma_f32_16x16x32_bf16 v[122:125], v[142:145], v[196:199], v[122:125]
	v_mfma_f32_16x16x32_bf16 v[118:121], v[134:137], v[204:207], v[118:121]
	v_mfma_f32_16x16x32_bf16 v[114:117], v[142:145], v[204:207], v[114:117]
	v_mfma_f32_16x16x32_bf16 v[102:105], v[134:137], v[224:227], v[102:105]
	v_mfma_f32_16x16x32_bf16 v[94:97], v[142:145], v[224:227], v[94:97]
	v_mfma_f32_16x16x32_bf16 v[86:89], v[134:137], v[232:235], v[86:89]
	v_mfma_f32_16x16x32_bf16 v[78:81], v[142:145], v[232:235], v[78:81]
	v_mfma_f32_16x16x32_bf16 v[110:113], v[146:149], v[192:195], v[110:113]
	v_mfma_f32_16x16x32_bf16 v[106:109], v[178:181], v[192:195], v[106:109]
	v_mfma_f32_16x16x32_bf16 v[98:101], v[146:149], v[200:203], v[98:101]
	v_mfma_f32_16x16x32_bf16 v[90:93], v[178:181], v[200:203], v[90:93]
	v_mfma_f32_16x16x32_bf16 v[82:85], v[146:149], v[220:223], v[82:85]
	v_mfma_f32_16x16x32_bf16 v[74:77], v[178:181], v[220:223], v[74:77]
	v_mfma_f32_16x16x32_bf16 v[70:73], v[146:149], v[228:231], v[70:73]
	v_mfma_f32_16x16x32_bf16 v[66:69], v[178:181], v[228:231], v[66:69]
	v_mfma_f32_16x16x32_bf16 v[110:113], v[150:153], v[196:199], v[110:113]
	v_mfma_f32_16x16x32_bf16 v[106:109], v[182:185], v[196:199], v[106:109]
	v_mfma_f32_16x16x32_bf16 v[98:101], v[150:153], v[204:207], v[98:101]
	v_mfma_f32_16x16x32_bf16 v[90:93], v[182:185], v[204:207], v[90:93]
	v_mfma_f32_16x16x32_bf16 v[82:85], v[150:153], v[224:227], v[82:85]
	v_mfma_f32_16x16x32_bf16 v[74:77], v[182:185], v[224:227], v[74:77]
	v_mfma_f32_16x16x32_bf16 v[70:73], v[150:153], v[232:235], v[70:73]
	v_mfma_f32_16x16x32_bf16 v[66:69], v[182:185], v[232:235], v[66:69]
	s_barrier
	s_add_i32 s43, s43, s8
	v_lshl_add_u64 v[170:171], v[170:171], 0, s[96:97]
	s_mov_b32 m0, s43
	ds_read_b128 v[192:195], v190 offset:49152
	ds_read_b128 v[196:199], v190 offset:50176
	ds_read_b128 v[200:203], v190 offset:51200
	ds_read_b128 v[204:207], v190 offset:52224
	ds_read_b128 v[220:223], v190 offset:53248
	ds_read_b128 v[224:227], v190 offset:54272
	ds_read_b128 v[228:231], v190 offset:55296
	ds_read_b128 v[232:235], v190 offset:56320
	global_load_lds_dwordx4 v[170:171], off
	s_add_i32 m0, s43, 0x2000
	s_add_u32 s28, s28, 0x2b0080
	v_lshl_add_u64 v[170:171], v[186:187], 0, s[96:97]
	s_addc_u32 s29, s29, 0
	s_add_i32 s43, s59, s8
	global_load_lds_dwordx4 v[170:171], off
	v_lshl_add_u64 v[170:171], s[28:29], 0, v[158:159]
	s_mov_b32 m0, s43
	s_nop 0
	global_load_lds_dwordx4 v[170:171], off
	v_lshl_add_u64 v[170:171], s[28:29], 0, v[172:173]
	s_add_i32 m0, s43, 0x2000
	s_nop 0
	global_load_lds_dwordx4 v[170:171], off
	v_lshl_add_u64 v[170:171], v[208:209], 0, s[96:97]
	s_mov_b32 m0, s35
	s_nop 0
	global_load_lds_dwordx4 v[170:171], off
	v_lshl_add_u64 v[170:171], v[210:211], 0, s[96:97]
	s_mov_b32 m0, s52
	s_nop 0
	global_load_lds_dwordx4 v[170:171], off
	s_waitcnt vmcnt(8)
	s_waitcnt lgkmcnt(0)
	s_barrier
	v_mfma_f32_16x16x32_bf16 v[62:65], v[130:133], v[192:195], v[62:65]
	v_mfma_f32_16x16x32_bf16 v[58:61], v[138:141], v[192:195], v[58:61]
	v_mfma_f32_16x16x32_bf16 v[54:57], v[130:133], v[200:203], v[54:57]
	v_mfma_f32_16x16x32_bf16 v[46:49], v[138:141], v[200:203], v[46:49]
	v_mfma_f32_16x16x32_bf16 v[38:41], v[130:133], v[220:223], v[38:41]
	v_mfma_f32_16x16x32_bf16 v[30:33], v[138:141], v[220:223], v[30:33]
	v_mfma_f32_16x16x32_bf16 v[22:25], v[130:133], v[228:231], v[22:25]
	v_mfma_f32_16x16x32_bf16 v[14:17], v[138:141], v[228:231], v[14:17]
	v_mfma_f32_16x16x32_bf16 v[62:65], v[134:137], v[196:199], v[62:65]
	v_mfma_f32_16x16x32_bf16 v[58:61], v[142:145], v[196:199], v[58:61]
	v_mfma_f32_16x16x32_bf16 v[54:57], v[134:137], v[204:207], v[54:57]
	v_mfma_f32_16x16x32_bf16 v[46:49], v[142:145], v[204:207], v[46:49]
	v_mfma_f32_16x16x32_bf16 v[38:41], v[134:137], v[224:227], v[38:41]
	v_mfma_f32_16x16x32_bf16 v[30:33], v[142:145], v[224:227], v[30:33]
	v_mfma_f32_16x16x32_bf16 v[22:25], v[134:137], v[232:235], v[22:25]
	v_mfma_f32_16x16x32_bf16 v[14:17], v[142:145], v[232:235], v[14:17]
	v_mfma_f32_16x16x32_bf16 v[50:53], v[146:149], v[192:195], v[50:53]
	v_mfma_f32_16x16x32_bf16 v[42:45], v[178:181], v[192:195], v[42:45]
	v_mfma_f32_16x16x32_bf16 v[34:37], v[146:149], v[200:203], v[34:37]
	v_mfma_f32_16x16x32_bf16 v[26:29], v[178:181], v[200:203], v[26:29]
	v_mfma_f32_16x16x32_bf16 v[18:21], v[146:149], v[220:223], v[18:21]
	v_mfma_f32_16x16x32_bf16 v[10:13], v[178:181], v[220:223], v[10:13]
	v_mfma_f32_16x16x32_bf16 v[6:9], v[146:149], v[228:231], v[6:9]
	v_mfma_f32_16x16x32_bf16 v[2:5], v[178:181], v[228:231], v[2:5]
	v_mfma_f32_16x16x32_bf16 v[50:53], v[150:153], v[196:199], v[50:53]
	v_mfma_f32_16x16x32_bf16 v[42:45], v[182:185], v[196:199], v[42:45]
	v_mfma_f32_16x16x32_bf16 v[34:37], v[150:153], v[204:207], v[34:37]
	v_mfma_f32_16x16x32_bf16 v[26:29], v[182:185], v[204:207], v[26:29]
	v_mfma_f32_16x16x32_bf16 v[18:21], v[150:153], v[224:227], v[18:21]
	v_mfma_f32_16x16x32_bf16 v[10:13], v[182:185], v[224:227], v[10:13]
	v_mfma_f32_16x16x32_bf16 v[6:9], v[150:153], v[232:235], v[6:9]
	v_mfma_f32_16x16x32_bf16 v[2:5], v[182:185], v[232:235], v[2:5]
	s_barrier
	s_add_u32 s16, s16, 0x100
	s_addc_u32 s17, s17, 0
	s_cmp_ge_i32 s30, s14
	s_mov_b64 s[48:49], s[26:27]
	s_mov_b32 s28, s30
	s_cbranch_scc0 .LBB0_915
